# attention NOMAX loops: redundant lgkmcnt waits consolidated, LDS-DMA m0 save/restore dropped (m0 written directly), add-of-zero removed; on top of v1
# baseline (speedup 1.0000x reference)
.LBB0_863:
	v_lshl_add_u32 v206, s89, 1, v168
	ds_read_b64_tr_b16 v[194:195], v206 offset:24576
	ds_read_b64_tr_b16 v[196:197], v206 offset:25088
	v_add_f32_e32 v108, v80, v81
	ds_read_b128 v[246:249], v188 offset:1024
	v_add_f32_e32 v108, v82, v108
	v_add_f32_e32 v108, v83, v108
	v_add_f32_e32 v108, v84, v108
	v_add_f32_e32 v108, v85, v108
	v_cvt_pk_bf16_f32 v156, v80, v81
	v_cvt_pk_bf16_f32 v157, v82, v83
	v_mfma_f32_32x32x16_bf16 v[112:127], v[100:103], v[242:245], 0
	ds_read_b64_tr_b16 v[80:81], v206 offset:28672
	ds_read_b64_tr_b16 v[82:83], v206 offset:29184
	v_add_f32_e32 v104, v86, v108
	v_add_f32_e32 v104, v87, v104
	v_add_f32_e32 v104, v88, v104
	v_add_f32_e32 v144, v89, v104
	v_mfma_f32_32x32x16_bf16 v[96:111], v[96:99], v[242:245], 0
	v_cvt_pk_bf16_f32 v158, v84, v85
	v_cvt_pk_bf16_f32 v159, v86, v87
	ds_read_b64_tr_b16 v[84:85], v206 offset:25600
	ds_read_b64_tr_b16 v[86:87], v206 offset:26112
	ds_read_b128 v[242:245], v188 offset:2048
	v_add_f32_e32 v144, v90, v144
	v_add_f32_e32 v144, v91, v144
	v_add_f32_e32 v144, v92, v144
	v_add_f32_e32 v144, v93, v144
	v_cvt_pk_bf16_f32 v152, v88, v89
	v_cvt_pk_bf16_f32 v153, v90, v91
	s_waitcnt lgkmcnt(5)
	v_mfma_f32_32x32x16_bf16 v[112:127], v[164:167], v[246:249], v[112:127]
	ds_read_b64_tr_b16 v[88:89], v206 offset:29696
	ds_read_b64_tr_b16 v[90:91], v206 offset:30208
	v_add_f32_e32 v144, v94, v144
	v_add_f32_e32 v144, v95, v144
	v_add_f32_e32 v144, v64, v144
	v_add_f32_e32 v144, v65, v144
	v_mfma_f32_32x32x16_bf16 v[96:111], v[160:163], v[246:249], v[96:111]
	v_cvt_pk_bf16_f32 v154, v92, v93
	v_cvt_pk_bf16_f32 v155, v94, v95
	ds_read_b64_tr_b16 v[92:93], v206 offset:26624
	ds_read_b64_tr_b16 v[94:95], v206 offset:27136
	ds_read_b128 v[246:249], v188 offset:3072
	v_add_f32_e32 v144, v66, v144
	v_add_f32_e32 v144, v67, v144
	v_add_f32_e32 v144, v68, v144
	v_add_f32_e32 v144, v69, v144
	v_cvt_pk_bf16_f32 v148, v64, v65
	v_cvt_pk_bf16_f32 v149, v66, v67
	s_waitcnt lgkmcnt(5)
	v_mfma_f32_32x32x16_bf16 v[112:127], v[140:143], v[242:245], v[112:127]
	ds_read_b64_tr_b16 v[198:199], v206 offset:30720
	ds_read_b64_tr_b16 v[200:201], v206 offset:31232
	v_add_f32_e32 v140, v70, v144
	v_add_f32_e32 v140, v71, v140
	v_add_f32_e32 v140, v72, v140
	v_add_f32_e32 v140, v73, v140
	v_mfma_f32_32x32x16_bf16 v[96:111], v[136:139], v[242:245], v[96:111]
	v_cvt_pk_bf16_f32 v150, v68, v69
	v_cvt_pk_bf16_f32 v151, v70, v71
	ds_read_b64_tr_b16 v[202:203], v206 offset:27648
	ds_read_b64_tr_b16 v[204:205], v206 offset:28160
	v_add_f32_e32 v68, v74, v140
	v_add_f32_e32 v68, v75, v68
	v_add_f32_e32 v68, v76, v68
	v_add_f32_e32 v68, v77, v68
	v_cvt_pk_bf16_f32 v144, v72, v73
	v_cvt_pk_bf16_f32 v145, v74, v75
	s_waitcnt lgkmcnt(4)
	v_mfma_f32_32x32x16_bf16 v[112:127], v[132:135], v[246:249], v[112:127]
	ds_read_b64_tr_b16 v[72:73], v206 offset:31744
	ds_read_b64_tr_b16 v[74:75], v206 offset:32256
	v_add_f32_e32 v68, v78, v68
	v_add_f32_e32 v68, v79, v68
	v_cvt_pk_bf16_f32 v146, v76, v77
	v_mfma_f32_32x32x16_bf16 v[96:111], v[128:131], v[246:249], v[96:111]
	v_cvt_pk_bf16_f32 v147, v78, v79
	s_add_i32 m0, s87, s35
	v_lshl_add_u64 v[64:65], v[180:181], 0, s[54:55]
	global_load_lds_dwordx4 v[64:65], off
	s_lshl_b32 s88, s86, 1
	s_add_i32 s88, s88, s16
	s_mov_b32 m0, s88
	v_lshl_add_u64 v[64:65], v[178:179], 0, s[54:55]
	global_load_lds_dwordx4 v[64:65], off
	s_addk_i32 m0, 0x2000
	v_lshl_add_u64 v[64:65], v[176:177], 0, s[54:55]
	global_load_lds_dwordx4 v[64:65], off
	v_add_f32_e32 v193, v193, v68
	v_mfma_f32_32x32x16_bf16 v[48:63], v[156:159], v[194:197], v[48:63]
	ds_read_b64_tr_b16 v[76:77], v206 offset:32768
	ds_read_b64_tr_b16 v[78:79], v206 offset:33280
	v_exp_f32_e32 v112, v112
	v_exp_f32_e32 v113, v113
	v_mfma_f32_32x32x16_bf16 v[32:47], v[156:159], v[80:83], v[32:47]
	ds_read_b64_tr_b16 v[194:195], v206 offset:36864
	ds_read_b64_tr_b16 v[196:197], v206 offset:37376
	v_exp_f32_e32 v114, v114
	v_exp_f32_e32 v115, v115
	v_add_u32_e32 v128, s86, v189
	ds_read_b128 v[68:71], v128
	ds_read_b128 v[64:67], v128 offset:512
	v_mfma_f32_32x32x16_bf16 v[48:63], v[152:155], v[84:87], v[48:63]
	ds_read_b64_tr_b16 v[80:81], v206 offset:33792
	ds_read_b64_tr_b16 v[82:83], v206 offset:34304
	v_exp_f32_e32 v116, v116
	v_exp_f32_e32 v117, v117
	ds_read_b128 v[164:167], v128 offset:2048
	ds_read_b128 v[140:143], v128 offset:2560
	v_mfma_f32_32x32x16_bf16 v[32:47], v[152:155], v[88:91], v[32:47]
	ds_read_b64_tr_b16 v[84:85], v206 offset:37888
	ds_read_b64_tr_b16 v[86:87], v206 offset:38400
	v_exp_f32_e32 v118, v118
	v_exp_f32_e32 v119, v119
	ds_read_b128 v[160:163], v128 offset:4096
	ds_read_b128 v[132:135], v128 offset:4608
	v_mfma_f32_32x32x16_bf16 v[48:63], v[148:151], v[92:95], v[48:63]
	ds_read_b64_tr_b16 v[88:89], v206 offset:34816
	ds_read_b64_tr_b16 v[90:91], v206 offset:35328
	v_exp_f32_e32 v120, v120
	v_exp_f32_e32 v121, v121
	ds_read_b128 v[136:139], v128 offset:6144
	ds_read_b128 v[128:131], v128 offset:6656
	s_waitcnt lgkmcnt(14)
	v_mfma_f32_32x32x16_bf16 v[32:47], v[148:151], v[198:201], v[32:47]
	ds_read_b64_tr_b16 v[92:93], v206 offset:38912
	ds_read_b64_tr_b16 v[94:95], v206 offset:39424
	v_exp_f32_e32 v122, v122
	v_exp_f32_e32 v123, v123
	v_mfma_f32_32x32x16_bf16 v[48:63], v[144:147], v[202:205], v[48:63]
	ds_read_b64_tr_b16 v[198:199], v206 offset:35840
	ds_read_b64_tr_b16 v[200:201], v206 offset:36352
	v_exp_f32_e32 v124, v124
	v_exp_f32_e32 v125, v125
	v_mfma_f32_32x32x16_bf16 v[32:47], v[144:147], v[72:75], v[32:47]
	ds_read_b64_tr_b16 v[202:203], v206 offset:39936
	ds_read_b64_tr_b16 v[204:205], v206 offset:40448
	v_exp_f32_e32 v126, v126
	v_exp_f32_e32 v127, v127
	s_waitcnt lgkmcnt(14)
	v_mfma_f32_32x32x16_bf16 v[16:31], v[156:159], v[76:79], v[16:31]
	v_exp_f32_e32 v96, v96
	v_exp_f32_e32 v97, v97
	v_mfma_f32_32x32x16_bf16 v[0:15], v[156:159], v[194:197], v[0:15]
	v_exp_f32_e32 v98, v98
	v_exp_f32_e32 v99, v99
	v_mfma_f32_32x32x16_bf16 v[16:31], v[152:155], v[80:83], v[16:31]
	v_exp_f32_e32 v100, v100
	v_exp_f32_e32 v101, v101
	s_waitcnt lgkmcnt(8)
	v_mfma_f32_32x32x16_bf16 v[0:15], v[152:155], v[84:87], v[0:15]
	v_exp_f32_e32 v102, v102
	v_exp_f32_e32 v103, v103
	v_mfma_f32_32x32x16_bf16 v[16:31], v[148:151], v[88:91], v[16:31]
	v_exp_f32_e32 v104, v104
	v_exp_f32_e32 v105, v105
	s_waitcnt lgkmcnt(2)
	v_mfma_f32_32x32x16_bf16 v[0:15], v[148:151], v[92:95], v[0:15]
	v_exp_f32_e32 v106, v106
	v_exp_f32_e32 v107, v107
	v_mfma_f32_32x32x16_bf16 v[16:31], v[144:147], v[198:201], v[16:31]
	v_exp_f32_e32 v108, v108
	v_exp_f32_e32 v109, v109
	s_waitcnt lgkmcnt(0)
	v_mfma_f32_32x32x16_bf16 v[0:15], v[144:147], v[202:205], v[0:15]
	ds_read_b128 v[242:245], v188
	v_exp_f32_e32 v110, v110
	v_exp_f32_e32 v111, v111
	s_waitcnt vmcnt(3) lgkmcnt(0)
	s_barrier
	s_add_i32 s88, s86, 0x2000
	s_cmpk_lg_i32 s86, 0x4000
	s_cselect_b32 s88, s88, 0
	v_lshl_add_u32 v206, s87, 1, v168
	ds_read_b64_tr_b16 v[194:195], v206 offset:24576
	ds_read_b64_tr_b16 v[196:197], v206 offset:25088
	ds_read_b128 v[246:249], v188 offset:1024
	v_add_f32_e32 v76, v112, v113
	v_add_f32_e32 v76, v114, v76
	v_add_f32_e32 v76, v115, v76
	v_add_f32_e32 v76, v116, v76
	v_mfma_f32_32x32x16_bf16 v[80:95], v[68:71], v[242:245], 0
	v_add_f32_e32 v76, v117, v76
	v_cvt_pk_bf16_f32 v156, v112, v113
	v_cvt_pk_bf16_f32 v157, v114, v115
	ds_read_b64_tr_b16 v[112:113], v206 offset:28672
	ds_read_b64_tr_b16 v[114:115], v206 offset:29184
	v_add_f32_e32 v72, v118, v76
	v_add_f32_e32 v72, v119, v72
	v_add_f32_e32 v72, v120, v72
	v_add_f32_e32 v144, v121, v72
	v_mfma_f32_32x32x16_bf16 v[64:79], v[64:67], v[242:245], 0
	v_cvt_pk_bf16_f32 v158, v116, v117
	v_cvt_pk_bf16_f32 v159, v118, v119
	ds_read_b64_tr_b16 v[116:117], v206 offset:25600
	ds_read_b64_tr_b16 v[118:119], v206 offset:26112
	ds_read_b128 v[242:245], v188 offset:2048
	v_add_f32_e32 v144, v122, v144
	v_add_f32_e32 v144, v123, v144
	v_add_f32_e32 v144, v124, v144
	v_add_f32_e32 v144, v125, v144
	s_waitcnt lgkmcnt(5)
	v_mfma_f32_32x32x16_bf16 v[80:95], v[164:167], v[246:249], v[80:95]
	v_cvt_pk_bf16_f32 v152, v120, v121
	v_cvt_pk_bf16_f32 v153, v122, v123
	ds_read_b64_tr_b16 v[120:121], v206 offset:29696
	ds_read_b64_tr_b16 v[122:123], v206 offset:30208
	v_add_f32_e32 v144, v126, v144
	v_add_f32_e32 v144, v127, v144
	v_add_f32_e32 v144, v96, v144
	v_add_f32_e32 v144, v97, v144
	v_mfma_f32_32x32x16_bf16 v[64:79], v[140:143], v[246:249], v[64:79]
	v_cvt_pk_bf16_f32 v154, v124, v125
	v_cvt_pk_bf16_f32 v155, v126, v127
	ds_read_b64_tr_b16 v[124:125], v206 offset:26624
	ds_read_b64_tr_b16 v[126:127], v206 offset:27136
	ds_read_b128 v[246:249], v188 offset:3072
	v_add_f32_e32 v144, v98, v144
	v_add_f32_e32 v144, v99, v144
	v_add_f32_e32 v144, v100, v144
	v_add_f32_e32 v144, v101, v144
	s_waitcnt lgkmcnt(5)
	v_mfma_f32_32x32x16_bf16 v[80:95], v[160:163], v[242:245], v[80:95]
	v_cvt_pk_bf16_f32 v148, v96, v97
	v_cvt_pk_bf16_f32 v149, v98, v99
	ds_read_b64_tr_b16 v[198:199], v206 offset:30720
	ds_read_b64_tr_b16 v[200:201], v206 offset:31232
	v_add_f32_e32 v140, v102, v144
	v_add_f32_e32 v140, v103, v140
	v_add_f32_e32 v140, v104, v140
	v_add_f32_e32 v140, v105, v140
	v_mfma_f32_32x32x16_bf16 v[64:79], v[132:135], v[242:245], v[64:79]
	v_cvt_pk_bf16_f32 v150, v100, v101
	v_cvt_pk_bf16_f32 v151, v102, v103
	ds_read_b64_tr_b16 v[202:203], v206 offset:27648
	ds_read_b64_tr_b16 v[204:205], v206 offset:28160
	v_add_f32_e32 v100, v106, v140
	v_add_f32_e32 v100, v107, v100
	v_add_f32_e32 v100, v108, v100
	v_add_f32_e32 v100, v109, v100
	s_waitcnt lgkmcnt(4)
	v_mfma_f32_32x32x16_bf16 v[80:95], v[136:139], v[246:249], v[80:95]
	v_cvt_pk_bf16_f32 v144, v104, v105
	v_cvt_pk_bf16_f32 v145, v106, v107
	ds_read_b64_tr_b16 v[104:105], v206 offset:31744
	ds_read_b64_tr_b16 v[106:107], v206 offset:32256
	v_add_f32_e32 v100, v110, v100
	v_add_f32_e32 v100, v111, v100
	v_cvt_pk_bf16_f32 v146, v108, v109
	v_mfma_f32_32x32x16_bf16 v[64:79], v[128:131], v[246:249], v[64:79]
	v_cvt_pk_bf16_f32 v147, v110, v111
	s_add_i32 m0, s86, s35
	s_nop 0
	global_load_lds_dwordx4 v[180:181], off
	s_lshl_b32 s87, s88, 1
	s_add_i32 s87, s87, s16
	s_mov_b32 m0, s87
	s_nop 0
	global_load_lds_dwordx4 v[178:179], off
	s_addk_i32 m0, 0x2000
	s_nop 0
	global_load_lds_dwordx4 v[176:177], off
	v_add_f32_e32 v193, v193, v100
	v_mfma_f32_32x32x16_bf16 v[48:63], v[156:159], v[194:197], v[48:63]
	ds_read_b64_tr_b16 v[108:109], v206 offset:32768
	ds_read_b64_tr_b16 v[110:111], v206 offset:33280
	v_exp_f32_e32 v80, v80
	v_exp_f32_e32 v81, v81
	v_mfma_f32_32x32x16_bf16 v[32:47], v[156:159], v[112:115], v[32:47]
	ds_read_b64_tr_b16 v[194:195], v206 offset:36864
	ds_read_b64_tr_b16 v[196:197], v206 offset:37376
	v_exp_f32_e32 v82, v82
	v_exp_f32_e32 v83, v83
	v_add_u32_e32 v128, s88, v189
	ds_read_b128 v[100:103], v128
	ds_read_b128 v[96:99], v128 offset:512
	v_mfma_f32_32x32x16_bf16 v[48:63], v[152:155], v[116:119], v[48:63]
	ds_read_b64_tr_b16 v[112:113], v206 offset:33792
	ds_read_b64_tr_b16 v[114:115], v206 offset:34304
	v_exp_f32_e32 v84, v84
	v_exp_f32_e32 v85, v85
	ds_read_b128 v[164:167], v128 offset:2048
	ds_read_b128 v[160:163], v128 offset:2560
	v_mfma_f32_32x32x16_bf16 v[32:47], v[152:155], v[120:123], v[32:47]
	ds_read_b64_tr_b16 v[116:117], v206 offset:37888
	ds_read_b64_tr_b16 v[118:119], v206 offset:38400
	v_exp_f32_e32 v86, v86
	v_exp_f32_e32 v87, v87
	ds_read_b128 v[140:143], v128 offset:4096
	ds_read_b128 v[136:139], v128 offset:4608
	v_mfma_f32_32x32x16_bf16 v[48:63], v[148:151], v[124:127], v[48:63]
	ds_read_b64_tr_b16 v[120:121], v206 offset:34816
	ds_read_b64_tr_b16 v[122:123], v206 offset:35328
	v_exp_f32_e32 v88, v88
	v_exp_f32_e32 v89, v89
	ds_read_b128 v[132:135], v128 offset:6144
	ds_read_b128 v[128:131], v128 offset:6656
	s_waitcnt lgkmcnt(14)
	v_mfma_f32_32x32x16_bf16 v[32:47], v[148:151], v[198:201], v[32:47]
	ds_read_b64_tr_b16 v[124:125], v206 offset:38912
	ds_read_b64_tr_b16 v[126:127], v206 offset:39424
	v_exp_f32_e32 v90, v90
	v_exp_f32_e32 v91, v91
	v_mfma_f32_32x32x16_bf16 v[48:63], v[144:147], v[202:205], v[48:63]
	ds_read_b64_tr_b16 v[198:199], v206 offset:35840
	ds_read_b64_tr_b16 v[200:201], v206 offset:36352
	v_exp_f32_e32 v92, v92
	v_exp_f32_e32 v93, v93
	v_mfma_f32_32x32x16_bf16 v[32:47], v[144:147], v[104:107], v[32:47]
	ds_read_b64_tr_b16 v[202:203], v206 offset:39936
	ds_read_b64_tr_b16 v[204:205], v206 offset:40448
	v_exp_f32_e32 v94, v94
	v_exp_f32_e32 v95, v95
	s_waitcnt lgkmcnt(14)
	v_mfma_f32_32x32x16_bf16 v[16:31], v[156:159], v[108:111], v[16:31]
	v_exp_f32_e32 v64, v64
	v_exp_f32_e32 v65, v65
	v_mfma_f32_32x32x16_bf16 v[0:15], v[156:159], v[194:197], v[0:15]
	v_exp_f32_e32 v66, v66
	v_exp_f32_e32 v67, v67
	v_mfma_f32_32x32x16_bf16 v[16:31], v[152:155], v[112:115], v[16:31]
	v_exp_f32_e32 v68, v68
	v_exp_f32_e32 v69, v69
	s_waitcnt lgkmcnt(8)
	v_mfma_f32_32x32x16_bf16 v[0:15], v[152:155], v[116:119], v[0:15]
	v_exp_f32_e32 v70, v70
	v_exp_f32_e32 v71, v71
	v_mfma_f32_32x32x16_bf16 v[16:31], v[148:151], v[120:123], v[16:31]
	v_exp_f32_e32 v72, v72
	v_exp_f32_e32 v73, v73
	s_waitcnt lgkmcnt(2)
	v_mfma_f32_32x32x16_bf16 v[0:15], v[148:151], v[124:127], v[0:15]
	v_exp_f32_e32 v74, v74
	v_exp_f32_e32 v75, v75
	v_mfma_f32_32x32x16_bf16 v[16:31], v[144:147], v[198:201], v[16:31]
	v_exp_f32_e32 v76, v76
	v_exp_f32_e32 v77, v77
	s_waitcnt lgkmcnt(0)
	v_mfma_f32_32x32x16_bf16 v[0:15], v[144:147], v[202:205], v[0:15]
	ds_read_b128 v[242:245], v188
	v_exp_f32_e32 v78, v78
	v_exp_f32_e32 v79, v79
	s_add_i32 s90, s88, 0x2000
	s_waitcnt vmcnt(3) lgkmcnt(0)
	s_barrier
; #define WAIT_BAR(N) asm volatile("s_waitcnt vmcnt(" #N ") lgkmcnt(0)\n\ts_barrier":::"memory")
;   #define RESC() do{ if(!NOMAX&&resc){ asm volatile("s_waitcnt lgkmcnt(0)":::"memory"); \
;       _Pragma("unroll") for(int d_=0;d_<2*VM;++d_) _Pragma("unroll") for(int r=0;r<16;++r)o[d_][r]*=wsf[crow(r,hi)]; } }while(0)
;   #define ROT() do{sl_prev=sl_cur;sl_cur=sl_next;sl_next=(sl_next==(NSLOT-1)*SLOTB)?0:sl_next+SLOTB;}while(0)
;   #define ENDW(tt) do{ if((tt)+3<NT){ if constexpr(VM==2){WAIT_BAR(3);}else{WAIT_BAR(2);} } else if((tt)+2<NT){ if constexpr(VM==2){WAIT_BAR(2);}else{WAIT_BAR(1);} } else {WAIT_BAR(0);} }while(0)
; template<int THRL,int VM,bool NOMAX> __device__ __forceinline__ void attn_unit(const bf16*Qb,const bf16*__restrict__ Kh,const bf16*__restrict__ Vh,bf16*Ob,const int NT,const int sp,float*wscr,char*shm){
;     ...
;     STEP(pB0,pB1,pA0,pA1,t,true,true,true);     if constexpr(VM==2){WAIT_BAR(3);}else{WAIT_BAR(2);} RESC(); ROT();
;     STEP(pA0,pA1,pB0,pB1,t+1,true,true,true);   if constexpr(VM==2){WAIT_BAR(3);}else{WAIT_BAR(2);} RESC(); ROT();
;   }
;     ...
;   for(;t+1<NT;t+=2){
;     STEP(pB0,pB1,pA0,pA1,t,(t+3<NT),(t+1<NT),(t+1<NT));       ENDW(t);   RESC(); ROT();
	s_cmpk_lg_i32 s88, 0x4000
	s_mov_b32 s89, s86
	s_cselect_b32 s86, s90, 0
	s_add_i32 s85, s85, 2
	v_lshl_add_u64 v[176:177], v[176:177], 0, s[56:57]
	v_lshl_add_u64 v[178:179], v[178:179], 0, s[56:57]
	v_lshl_add_u64 v[180:181], v[180:181], 0, s[56:57]
	s_mov_b32 s87, s88
	s_cmpk_lt_u32 s85, 0x79
	s_cbranch_scc1 .LBB0_863
	s_and_b32 s34, s34, 0x3fffffc0
	s_lshl_b32 s34, s34, 2
	s_add_i32 s34, s34, 0
	s_add_i32 s34, s34, 0x12000
	s_cmp_lg_u32 0, -1
	s_cselect_b32 s85, 0, 0
	s_add_i32 s86, s85, 0x6000
	v_add_u32_e32 v104, s86, v191
	v_add3_u32 v176, v104, v190, v192
	v_add_u32_e32 v177, 0x6000, v168
	ds_read_b64_tr_b16 v[178:179], v168 offset:57344
	ds_read_b64_tr_b16 v[180:181], v168 offset:57856
	v_add_f32_e32 v108, v80, v81
	ds_read_b128 v[104:107], v188
	v_add_f32_e32 v108, v82, v108
	v_add_f32_e32 v108, v83, v108
	v_add_f32_e32 v108, v84, v108
	v_add_f32_e32 v108, v85, v108
	v_cvt_pk_bf16_f32 v156, v80, v81
	v_cvt_pk_bf16_f32 v157, v82, v83
	s_waitcnt lgkmcnt(0)
	v_mfma_f32_32x32x16_bf16 v[112:127], v[100:103], v[104:107], 0
	ds_read_b64_tr_b16 v[80:81], v168 offset:61440
	ds_read_b64_tr_b16 v[82:83], v168 offset:61952
	ds_read_b128 v[100:103], v188
	v_add_f32_e32 v104, v86, v108
	v_add_f32_e32 v104, v87, v104
	v_add_f32_e32 v104, v88, v104
	v_add_f32_e32 v144, v89, v104
	v_cvt_pk_bf16_f32 v158, v84, v85
	v_cvt_pk_bf16_f32 v159, v86, v87
	s_waitcnt lgkmcnt(0)
	v_mfma_f32_32x32x16_bf16 v[96:111], v[96:99], v[100:103], 0
	ds_read_b64_tr_b16 v[84:85], v168 offset:58368
	ds_read_b64_tr_b16 v[86:87], v168 offset:58880
	ds_read_b128 v[194:197], v188 offset:1024
	v_add_f32_e32 v144, v90, v144
	v_add_f32_e32 v144, v91, v144
	v_add_f32_e32 v144, v92, v144
	v_add_f32_e32 v144, v93, v144
	v_cvt_pk_bf16_f32 v152, v88, v89
	v_cvt_pk_bf16_f32 v153, v90, v91
	s_waitcnt lgkmcnt(0)
	v_mfma_f32_32x32x16_bf16 v[112:127], v[164:167], v[194:197], v[112:127]
	ds_read_b64_tr_b16 v[88:89], v168 offset:62464
	ds_read_b64_tr_b16 v[90:91], v168 offset:62976
	ds_read_b128 v[164:167], v188 offset:1024
	v_add_f32_e32 v144, v94, v144
	v_add_f32_e32 v144, v95, v144
	v_add_f32_e32 v144, v64, v144
	v_add_f32_e32 v144, v65, v144
	v_cvt_pk_bf16_f32 v154, v92, v93
	v_cvt_pk_bf16_f32 v155, v94, v95
	s_waitcnt lgkmcnt(0)
	v_mfma_f32_32x32x16_bf16 v[96:111], v[160:163], v[164:167], v[96:111]
	ds_read_b64_tr_b16 v[194:195], v168 offset:59392
	ds_read_b64_tr_b16 v[196:197], v168 offset:59904
	ds_read_b128 v[92:95], v188 offset:2048
	v_add_f32_e32 v144, v66, v144
	v_add_f32_e32 v144, v67, v144
	v_add_f32_e32 v144, v68, v144
	v_add_f32_e32 v144, v69, v144
	v_cvt_pk_bf16_f32 v148, v64, v65
	v_cvt_pk_bf16_f32 v149, v66, v67
	s_waitcnt lgkmcnt(0)
	v_mfma_f32_32x32x16_bf16 v[112:127], v[140:143], v[92:95], v[112:127]
	ds_read_b64_tr_b16 v[140:141], v168 offset:63488
	ds_read_b64_tr_b16 v[142:143], v168 offset:64000
	ds_read_b128 v[64:67], v188 offset:2048
	v_add_f32_e32 v92, v70, v144
	v_add_f32_e32 v92, v71, v92
	v_add_f32_e32 v92, v72, v92
	v_add_f32_e32 v92, v73, v92
	v_cvt_pk_bf16_f32 v150, v68, v69
	v_cvt_pk_bf16_f32 v151, v70, v71
	s_waitcnt lgkmcnt(0)
	v_mfma_f32_32x32x16_bf16 v[96:111], v[136:139], v[64:67], v[96:111]
	ds_read_b64_tr_b16 v[136:137], v168 offset:60416
	ds_read_b64_tr_b16 v[138:139], v168 offset:60928
	ds_read_b128 v[64:67], v188 offset:3072
	v_add_f32_e32 v68, v74, v92
	v_add_f32_e32 v68, v75, v68
	v_add_f32_e32 v68, v76, v68
	v_add_f32_e32 v68, v77, v68
	v_cvt_pk_bf16_f32 v144, v72, v73
	v_cvt_pk_bf16_f32 v145, v74, v75
	s_waitcnt lgkmcnt(0)
	v_mfma_f32_32x32x16_bf16 v[112:127], v[132:135], v[64:67], v[112:127]
	ds_read_b64_tr_b16 v[72:73], v168 offset:64512
	ds_read_b64_tr_b16 v[74:75], v168 offset:65024
	ds_read_b128 v[64:67], v188 offset:3072
	v_add_f32_e32 v68, v78, v68
	v_add_f32_e32 v68, v79, v68
	v_add_f32_e32 v68, 0, v68
	v_cvt_pk_bf16_f32 v146, v76, v77
	v_cvt_pk_bf16_f32 v147, v78, v79
	s_waitcnt lgkmcnt(0)
	v_mfma_f32_32x32x16_bf16 v[96:111], v[128:131], v[64:67], v[96:111]
	v_lshl_add_u64 v[64:65], v[174:175], 0, s[58:59]
	s_mov_b32 s86, m0
	s_mov_b32 m0, s35
	s_nop 0
	global_load_lds_dwordx4 v[64:65], off
	s_mov_b32 m0, s86
	s_add_i32 s85, s85, s17
	v_lshl_add_u64 v[64:65], v[170:171], 0, s[60:61]
	s_add_i32 s17, s85, 0xa000
	s_mov_b32 s35, m0
	s_mov_b32 m0, s17
	s_nop 0
	global_load_lds_dwordx4 v[64:65], off
	s_mov_b32 m0, s35
	v_lshl_add_u64 v[64:65], v[172:173], 0, s[60:61]
	s_add_i32 s35, s17, 0x2000
	s_mov_b32 s86, m0
	s_mov_b32 m0, s35
	s_nop 0
	global_load_lds_dwordx4 v[64:65], off
	s_mov_b32 m0, s86
	v_add_f32_e32 v198, v193, v68
	v_mfma_f32_32x32x16_bf16 v[48:63], v[156:159], v[178:181], v[48:63]
	ds_read_b64_tr_b16 v[76:77], v177 offset:40960
	ds_read_b64_tr_b16 v[78:79], v177 offset:41472
	v_exp_f32_e32 v112, v112
	v_exp_f32_e32 v113, v113
	v_mfma_f32_32x32x16_bf16 v[32:47], v[156:159], v[80:83], v[32:47]
	ds_read_b64_tr_b16 v[128:129], v177 offset:45056
	ds_read_b64_tr_b16 v[130:131], v177 offset:45568
	v_exp_f32_e32 v114, v114
	v_exp_f32_e32 v115, v115
	ds_read_b128 v[68:71], v189 offset:8192
	ds_read_b128 v[64:67], v189 offset:8704
	v_mfma_f32_32x32x16_bf16 v[48:63], v[152:155], v[84:87], v[48:63]
	ds_read_b64_tr_b16 v[132:133], v177 offset:41984
	ds_read_b64_tr_b16 v[134:135], v177 offset:42496
	v_exp_f32_e32 v116, v116
	v_exp_f32_e32 v117, v117
	ds_read_b128 v[164:167], v189 offset:10240
	ds_read_b128 v[92:95], v189 offset:10752
	v_mfma_f32_32x32x16_bf16 v[32:47], v[152:155], v[88:91], v[32:47]
	ds_read_b64_tr_b16 v[178:179], v177 offset:46080
	ds_read_b64_tr_b16 v[180:181], v177 offset:46592
	v_exp_f32_e32 v118, v118
	v_exp_f32_e32 v119, v119
	ds_read_b128 v[160:163], v189 offset:12288
	ds_read_b128 v[84:87], v189 offset:12800
	v_mfma_f32_32x32x16_bf16 v[48:63], v[148:151], v[194:197], v[48:63]
	ds_read_b64_tr_b16 v[190:191], v177 offset:43008
	ds_read_b64_tr_b16 v[192:193], v177 offset:43520
	v_exp_f32_e32 v120, v120
	v_exp_f32_e32 v121, v121
	ds_read_b128 v[88:91], v189 offset:14336
	ds_read_b128 v[80:83], v189 offset:14848
	v_mfma_f32_32x32x16_bf16 v[32:47], v[148:151], v[140:143], v[32:47]
	ds_read_b64_tr_b16 v[194:195], v177 offset:47104
	ds_read_b64_tr_b16 v[196:197], v177 offset:47616
	v_exp_f32_e32 v122, v122
	v_exp_f32_e32 v123, v123
	v_mfma_f32_32x32x16_bf16 v[48:63], v[144:147], v[136:139], v[48:63]
	ds_read_b64_tr_b16 v[140:141], v177 offset:44032
	ds_read_b64_tr_b16 v[142:143], v177 offset:44544
	v_exp_f32_e32 v124, v124
	v_exp_f32_e32 v125, v125
	v_mfma_f32_32x32x16_bf16 v[32:47], v[144:147], v[72:75], v[32:47]
	ds_read_b64_tr_b16 v[136:137], v177 offset:48128
	ds_read_b64_tr_b16 v[138:139], v177 offset:48640
	v_exp_f32_e32 v126, v126
	v_exp_f32_e32 v127, v127
	s_waitcnt lgkmcnt(14)
;   #define RESC() do{ if(!NOMAX&&resc){ asm volatile("s_waitcnt lgkmcnt(0)":::"memory"); \
;       _Pragma("unroll") for(int d_=0;d_<2*VM;++d_) _Pragma("unroll") for(int r=0;r<16;++r)o[d_][r]*=wsf[crow(r,hi)]; } }while(0)
;   #define ROT() do{sl_prev=sl_cur;sl_cur=sl_next;sl_next=(sl_next==(NSLOT-1)*SLOTB)?0:sl_next+SLOTB;}while(0)
;   #define ENDW(tt) do{ if((tt)+3<NT){ if constexpr(VM==2){WAIT_BAR(3);}else{WAIT_BAR(2);} } else if((tt)+2<NT){ if constexpr(VM==2){WAIT_BAR(2);}else{WAIT_BAR(1);} } else {WAIT_BAR(0);} }while(0)
; template<int THRL,int VM,bool NOMAX> __device__ __forceinline__ void attn_unit(const bf16*Qb,const bf16*__restrict__ Kh,const bf16*__restrict__ Vh,bf16*Ob,const int NT,const int sp,float*wscr,char*shm){
;     ...
;   for(;t+1<NT;t+=2){
;     STEP(pB0,pB1,pA0,pA1,t,(t+3<NT),(t+1<NT),(t+1<NT));       ENDW(t);   RESC(); ROT();
;     STEP(pA0,pA1,pB0,pB1,t+1,(t+4<NT),(t+2<NT),(t+2<NT));     ENDW(t+1); RESC(); ROT();
	v_mfma_f32_32x32x16_bf16 v[16:31], v[156:159], v[76:79], v[16:31]
	v_exp_f32_e32 v96, v96
	v_exp_f32_e32 v97, v97
	v_mfma_f32_32x32x16_bf16 v[0:15], v[156:159], v[128:131], v[0:15]
	v_exp_f32_e32 v98, v98
	v_exp_f32_e32 v99, v99
	v_mfma_f32_32x32x16_bf16 v[16:31], v[152:155], v[132:135], v[16:31]
	v_exp_f32_e32 v100, v100
	v_exp_f32_e32 v101, v101
	s_waitcnt lgkmcnt(12)
	v_mfma_f32_32x32x16_bf16 v[0:15], v[152:155], v[178:181], v[0:15]
	v_exp_f32_e32 v102, v102
	v_exp_f32_e32 v103, v103
	s_waitcnt lgkmcnt(8)
	v_mfma_f32_32x32x16_bf16 v[16:31], v[148:151], v[190:193], v[16:31]
	v_exp_f32_e32 v104, v104
	v_exp_f32_e32 v105, v105
	s_waitcnt lgkmcnt(4)
	v_mfma_f32_32x32x16_bf16 v[0:15], v[148:151], v[194:197], v[0:15]
	v_exp_f32_e32 v106, v106
	v_exp_f32_e32 v107, v107
	s_waitcnt lgkmcnt(2)
	v_mfma_f32_32x32x16_bf16 v[16:31], v[144:147], v[140:143], v[16:31]
	v_exp_f32_e32 v108, v108
	v_exp_f32_e32 v109, v109
	s_waitcnt lgkmcnt(0)
	v_mfma_f32_32x32x16_bf16 v[0:15], v[144:147], v[136:139], v[0:15]
	v_exp_f32_e32 v110, v110
	v_exp_f32_e32 v111, v111
	s_waitcnt vmcnt(3) lgkmcnt(0)
	s_barrier
	ds_read_b64_tr_b16 v[178:179], v168 offset:24576
	ds_read_b64_tr_b16 v[180:181], v168 offset:25088
	v_add_f32_e32 v76, v112, v113
	ds_read_b128 v[72:75], v188
	v_add_f32_e32 v76, v114, v76
	v_add_f32_e32 v76, v115, v76
	v_add_f32_e32 v76, v116, v76
	v_add_f32_e32 v76, v117, v76
	v_cvt_pk_bf16_f32 v156, v112, v113
	v_cvt_pk_bf16_f32 v157, v114, v115
	s_waitcnt lgkmcnt(0)
	v_mfma_f32_32x32x16_bf16 v[128:143], v[68:71], v[72:75], 0
	ds_read_b64_tr_b16 v[112:113], v168 offset:28672
	ds_read_b64_tr_b16 v[114:115], v168 offset:29184
	ds_read_b128 v[68:71], v188
	v_add_f32_e32 v72, v118, v76
	v_add_f32_e32 v72, v119, v72
	v_add_f32_e32 v72, v120, v72
	v_add_f32_e32 v144, v121, v72
	s_waitcnt lgkmcnt(0)
	v_mfma_f32_32x32x16_bf16 v[64:79], v[64:67], v[68:71], 0
	v_cvt_pk_bf16_f32 v158, v116, v117
	v_cvt_pk_bf16_f32 v159, v118, v119
	ds_read_b64_tr_b16 v[116:117], v168 offset:25600
	ds_read_b64_tr_b16 v[118:119], v168 offset:26112
	ds_read_b128 v[190:193], v188 offset:1024
	v_add_f32_e32 v144, v122, v144
	v_add_f32_e32 v144, v123, v144
	v_add_f32_e32 v144, v124, v144
	v_add_f32_e32 v144, v125, v144
	v_cvt_pk_bf16_f32 v152, v120, v121
	v_cvt_pk_bf16_f32 v153, v122, v123
	s_waitcnt lgkmcnt(0)
	v_mfma_f32_32x32x16_bf16 v[128:143], v[164:167], v[190:193], v[128:143]
	ds_read_b64_tr_b16 v[120:121], v168 offset:29696
	ds_read_b64_tr_b16 v[122:123], v168 offset:30208
	ds_read_b128 v[164:167], v188 offset:1024
	v_add_f32_e32 v144, v126, v144
	v_add_f32_e32 v144, v127, v144
	v_add_f32_e32 v144, v96, v144
	v_add_f32_e32 v144, v97, v144
	s_waitcnt lgkmcnt(0)
	v_mfma_f32_32x32x16_bf16 v[64:79], v[92:95], v[164:167], v[64:79]
	v_cvt_pk_bf16_f32 v154, v124, v125
	v_cvt_pk_bf16_f32 v155, v126, v127
	ds_read_b64_tr_b16 v[92:93], v168 offset:26624
	ds_read_b64_tr_b16 v[94:95], v168 offset:27136
	ds_read_b128 v[124:127], v188 offset:2048
	v_add_f32_e32 v144, v98, v144
	v_add_f32_e32 v144, v99, v144
	v_add_f32_e32 v144, v100, v144
	v_add_f32_e32 v144, v101, v144
	v_cvt_pk_bf16_f32 v148, v96, v97
	v_cvt_pk_bf16_f32 v149, v98, v99
	s_waitcnt lgkmcnt(0)
	v_mfma_f32_32x32x16_bf16 v[128:143], v[160:163], v[124:127], v[128:143]
	ds_read_b64_tr_b16 v[96:97], v168 offset:30720
	ds_read_b64_tr_b16 v[98:99], v168 offset:31232
	ds_read_b128 v[124:127], v188 offset:2048
	v_add_f32_e32 v144, v102, v144
	v_add_f32_e32 v144, v103, v144
	v_add_f32_e32 v144, v104, v144
	v_add_f32_e32 v144, v105, v144
	s_waitcnt lgkmcnt(0)
	v_mfma_f32_32x32x16_bf16 v[64:79], v[84:87], v[124:127], v[64:79]
	v_cvt_pk_bf16_f32 v150, v100, v101
	v_cvt_pk_bf16_f32 v151, v102, v103
	ds_read_b64_tr_b16 v[100:101], v168 offset:27648
	ds_read_b64_tr_b16 v[102:103], v168 offset:28160
	ds_read_b128 v[84:87], v188 offset:3072
	v_add_f32_e32 v124, v106, v144
	v_add_f32_e32 v124, v107, v124
	v_add_f32_e32 v124, v108, v124
	v_add_f32_e32 v124, v109, v124
	v_cvt_pk_bf16_f32 v144, v104, v105
	v_cvt_pk_bf16_f32 v145, v106, v107
	s_waitcnt lgkmcnt(0)
	v_mfma_f32_32x32x16_bf16 v[128:143], v[88:91], v[84:87], v[128:143]
	ds_read_b64_tr_b16 v[88:89], v168 offset:31744
	ds_read_b64_tr_b16 v[90:91], v168 offset:32256
	ds_read_b128 v[84:87], v188 offset:3072
	v_add_f32_e32 v104, v110, v124
	v_add_f32_e32 v104, v111, v104
	v_add_f32_e32 v104, 0, v104
	v_cvt_pk_bf16_f32 v146, v108, v109
	s_waitcnt lgkmcnt(0)
	v_mfma_f32_32x32x16_bf16 v[64:79], v[80:83], v[84:87], v[64:79]
	v_cvt_pk_bf16_f32 v147, v110, v111
	v_lshl_add_u64 v[80:81], v[174:175], 0, s[62:63]
	s_add_i32 s86, s85, 0x2000
	s_mov_b32 s87, m0
	s_mov_b32 m0, s86
	s_nop 0
	global_load_lds_dwordx4 v[80:81], off
	s_mov_b32 m0, s87
	v_lshl_add_u64 v[80:81], v[170:171], 0, s[64:65]
	s_add_i32 s86, s85, 0xe000
	s_mov_b32 s87, m0
	s_mov_b32 m0, s86
	s_nop 0
	global_load_lds_dwordx4 v[80:81], off
	s_mov_b32 m0, s87
	v_lshl_add_u64 v[80:81], v[172:173], 0, s[64:65]
	s_add_i32 s85, s85, 0x10000
	s_mov_b32 s86, m0
	s_mov_b32 m0, s85
	s_nop 0
	global_load_lds_dwordx4 v[80:81], off
	s_mov_b32 m0, s86
	v_add_f32_e32 v198, v198, v104
	v_mfma_f32_32x32x16_bf16 v[48:63], v[156:159], v[178:181], v[48:63]
	ds_read_b64_tr_b16 v[104:105], v168 offset:32768
	ds_read_b64_tr_b16 v[106:107], v168 offset:33280
	v_exp_f32_e32 v128, v128
	v_exp_f32_e32 v129, v129
	v_mfma_f32_32x32x16_bf16 v[32:47], v[156:159], v[112:115], v[32:47]
	ds_read_b64_tr_b16 v[108:109], v168 offset:36864
	ds_read_b64_tr_b16 v[110:111], v168 offset:37376
	v_exp_f32_e32 v130, v130
	v_exp_f32_e32 v131, v131
	ds_read_b128 v[84:87], v189 offset:16384
	ds_read_b128 v[80:83], v189 offset:16896
	v_mfma_f32_32x32x16_bf16 v[48:63], v[152:155], v[116:119], v[48:63]
	ds_read_b64_tr_b16 v[178:179], v168 offset:33792
	ds_read_b64_tr_b16 v[180:181], v168 offset:34304
	v_exp_f32_e32 v132, v132
	v_exp_f32_e32 v133, v133
	ds_read_b128 v[164:167], v189 offset:18432
	ds_read_b128 v[124:127], v189 offset:18944
	v_mfma_f32_32x32x16_bf16 v[32:47], v[152:155], v[120:123], v[32:47]
	ds_read_b64_tr_b16 v[190:191], v168 offset:37888
	ds_read_b64_tr_b16 v[192:193], v168 offset:38400
	v_exp_f32_e32 v134, v134
	v_exp_f32_e32 v135, v135
	ds_read_b128 v[160:163], v189 offset:20480
	ds_read_b128 v[116:119], v189 offset:20992
	v_mfma_f32_32x32x16_bf16 v[48:63], v[148:151], v[92:95], v[48:63]
	ds_read_b64_tr_b16 v[194:195], v168 offset:34816
	ds_read_b64_tr_b16 v[196:197], v168 offset:35328
	v_exp_f32_e32 v136, v136
	v_exp_f32_e32 v137, v137
	ds_read_b128 v[120:123], v189 offset:22528
	ds_read_b128 v[112:115], v189 offset:23040
	v_mfma_f32_32x32x16_bf16 v[32:47], v[148:151], v[96:99], v[32:47]
	ds_read_b64_tr_b16 v[92:93], v168 offset:38912
	ds_read_b64_tr_b16 v[94:95], v168 offset:39424
	v_exp_f32_e32 v138, v138
	v_exp_f32_e32 v139, v139
	v_mfma_f32_32x32x16_bf16 v[48:63], v[144:147], v[100:103], v[48:63]
	ds_read_b64_tr_b16 v[96:97], v168 offset:35840
	ds_read_b64_tr_b16 v[98:99], v168 offset:36352
	v_exp_f32_e32 v140, v140
	v_exp_f32_e32 v141, v141
	v_mfma_f32_32x32x16_bf16 v[32:47], v[144:147], v[88:91], v[32:47]
	ds_read_b64_tr_b16 v[100:101], v168 offset:39936
	ds_read_b64_tr_b16 v[102:103], v168 offset:40448
	v_exp_f32_e32 v142, v142
	v_exp_f32_e32 v143, v143
	s_waitcnt lgkmcnt(14)
	v_mfma_f32_32x32x16_bf16 v[16:31], v[156:159], v[104:107], v[16:31]
	v_exp_f32_e32 v64, v64
	v_exp_f32_e32 v65, v65
	v_mfma_f32_32x32x16_bf16 v[0:15], v[156:159], v[108:111], v[0:15]
	v_exp_f32_e32 v66, v66
	v_exp_f32_e32 v67, v67
	v_mfma_f32_32x32x16_bf16 v[16:31], v[152:155], v[178:181], v[16:31]
	v_exp_f32_e32 v68, v68
	v_exp_f32_e32 v69, v69
	s_waitcnt lgkmcnt(12)
	v_mfma_f32_32x32x16_bf16 v[0:15], v[152:155], v[190:193], v[0:15]
	v_exp_f32_e32 v70, v70
	v_exp_f32_e32 v71, v71
	s_waitcnt lgkmcnt(8)
	v_mfma_f32_32x32x16_bf16 v[16:31], v[148:151], v[194:197], v[16:31]
	v_exp_f32_e32 v72, v72
	v_exp_f32_e32 v73, v73
	s_waitcnt lgkmcnt(4)
	v_mfma_f32_32x32x16_bf16 v[0:15], v[148:151], v[92:95], v[0:15]
	v_exp_f32_e32 v74, v74
	v_exp_f32_e32 v75, v75
	s_waitcnt lgkmcnt(2)
	v_mfma_f32_32x32x16_bf16 v[16:31], v[144:147], v[96:99], v[16:31]
	v_exp_f32_e32 v76, v76
	v_exp_f32_e32 v77, v77
	s_waitcnt lgkmcnt(0)
	v_mfma_f32_32x32x16_bf16 v[0:15], v[144:147], v[100:103], v[0:15]
	v_exp_f32_e32 v78, v78
	v_exp_f32_e32 v79, v79
	s_waitcnt vmcnt(3) lgkmcnt(0)
	s_barrier
	ds_read_b64_tr_b16 v[178:179], v168 offset:40960
	ds_read_b64_tr_b16 v[180:181], v168 offset:41472
	v_add_f32_e32 v92, v128, v129
	ds_read_b128 v[88:91], v188
	v_add_f32_e32 v92, v130, v92
	v_add_f32_e32 v92, v131, v92
	v_add_f32_e32 v92, v132, v92
	v_add_f32_e32 v92, v133, v92
	v_cvt_pk_bf16_f32 v156, v128, v129
	v_cvt_pk_bf16_f32 v157, v130, v131
	s_waitcnt lgkmcnt(0)
	v_mfma_f32_32x32x16_bf16 v[96:111], v[84:87], v[88:91], 0
	ds_read_b64_tr_b16 v[128:129], v168 offset:45056
	ds_read_b64_tr_b16 v[130:131], v168 offset:45568
	ds_read_b128 v[84:87], v188
	v_add_f32_e32 v88, v134, v92
	v_add_f32_e32 v88, v135, v88
	v_add_f32_e32 v88, v136, v88
	v_add_f32_e32 v144, v137, v88
	v_cvt_pk_bf16_f32 v158, v132, v133
	v_cvt_pk_bf16_f32 v159, v134, v135
	s_waitcnt lgkmcnt(0)
	v_mfma_f32_32x32x16_bf16 v[80:95], v[80:83], v[84:87], 0
	ds_read_b64_tr_b16 v[132:133], v168 offset:41984
	ds_read_b64_tr_b16 v[134:135], v168 offset:42496
	ds_read_b128 v[190:193], v188 offset:1024
	v_add_f32_e32 v144, v138, v144
	v_add_f32_e32 v144, v139, v144
	v_add_f32_e32 v144, v140, v144
	v_add_f32_e32 v144, v141, v144
	v_cvt_pk_bf16_f32 v152, v136, v137
	v_cvt_pk_bf16_f32 v153, v138, v139
	s_waitcnt lgkmcnt(0)
	v_mfma_f32_32x32x16_bf16 v[96:111], v[164:167], v[190:193], v[96:111]
	ds_read_b64_tr_b16 v[136:137], v168 offset:46080
	ds_read_b64_tr_b16 v[138:139], v168 offset:46592
	ds_read_b128 v[164:167], v188 offset:1024
	v_add_f32_e32 v144, v142, v144
	v_add_f32_e32 v144, v143, v144
	v_add_f32_e32 v144, v64, v144
	v_add_f32_e32 v144, v65, v144
	v_cvt_pk_bf16_f32 v154, v140, v141
	v_cvt_pk_bf16_f32 v155, v142, v143
	s_waitcnt lgkmcnt(0)
;   #define RESC() do{ if(!NOMAX&&resc){ asm volatile("s_waitcnt lgkmcnt(0)":::"memory"); \
;       _Pragma("unroll") for(int d_=0;d_<2*VM;++d_) _Pragma("unroll") for(int r=0;r<16;++r)o[d_][r]*=wsf[crow(r,hi)]; } }while(0)
;   #define ROT() do{sl_prev=sl_cur;sl_cur=sl_next;sl_next=(sl_next==(NSLOT-1)*SLOTB)?0:sl_next+SLOTB;}while(0)
;   #define ENDW(tt) do{ if((tt)+3<NT){ if constexpr(VM==2){WAIT_BAR(3);}else{WAIT_BAR(2);} } else if((tt)+2<NT){ if constexpr(VM==2){WAIT_BAR(2);}else{WAIT_BAR(1);} } else {WAIT_BAR(0);} }while(0)
; template<int THRL,int VM,bool NOMAX> __device__ __forceinline__ void attn_unit(const bf16*Qb,const bf16*__restrict__ Kh,const bf16*__restrict__ Vh,bf16*Ob,const int NT,const int sp,float*wscr,char*shm){
;     ...
;   for(;t+1<NT;t+=2){
;     STEP(pB0,pB1,pA0,pA1,t,(t+3<NT),(t+1<NT),(t+1<NT));       ENDW(t);   RESC(); ROT();
;     STEP(pA0,pA1,pB0,pB1,t+1,(t+4<NT),(t+2<NT),(t+2<NT));     ENDW(t+1); RESC(); ROT();
	v_mfma_f32_32x32x16_bf16 v[80:95], v[124:127], v[164:167], v[80:95]
	ds_read_b64_tr_b16 v[124:125], v168 offset:43008
	ds_read_b64_tr_b16 v[126:127], v168 offset:43520
	ds_read_b128 v[140:143], v188 offset:2048
	v_add_f32_e32 v144, v66, v144
	v_add_f32_e32 v144, v67, v144
	v_add_f32_e32 v144, v68, v144
	v_add_f32_e32 v144, v69, v144
	v_cvt_pk_bf16_f32 v148, v64, v65
	v_cvt_pk_bf16_f32 v149, v66, v67
	s_waitcnt lgkmcnt(0)
	v_mfma_f32_32x32x16_bf16 v[96:111], v[160:163], v[140:143], v[96:111]
	ds_read_b64_tr_b16 v[190:191], v168 offset:47104
	ds_read_b64_tr_b16 v[192:193], v168 offset:47616
	ds_read_b128 v[64:67], v188 offset:2048
	v_add_f32_e32 v140, v70, v144
	v_add_f32_e32 v140, v71, v140
	v_add_f32_e32 v140, v72, v140
	v_add_f32_e32 v140, v73, v140
	v_cvt_pk_bf16_f32 v150, v68, v69
	v_cvt_pk_bf16_f32 v151, v70, v71
	s_waitcnt lgkmcnt(0)
	v_mfma_f32_32x32x16_bf16 v[80:95], v[116:119], v[64:67], v[80:95]
	ds_read_b64_tr_b16 v[116:117], v168 offset:44032
	ds_read_b64_tr_b16 v[118:119], v168 offset:44544
	ds_read_b128 v[64:67], v188 offset:3072
	v_add_f32_e32 v68, v74, v140
	v_add_f32_e32 v68, v75, v68
	v_add_f32_e32 v68, v76, v68
	v_add_f32_e32 v68, v77, v68
	v_cvt_pk_bf16_f32 v144, v72, v73
	v_cvt_pk_bf16_f32 v145, v74, v75
	s_waitcnt lgkmcnt(0)
	v_mfma_f32_32x32x16_bf16 v[96:111], v[120:123], v[64:67], v[96:111]
	ds_read_b64_tr_b16 v[72:73], v168 offset:48128
	ds_read_b64_tr_b16 v[74:75], v168 offset:48640
	ds_read_b128 v[64:67], v188 offset:3072
	v_add_f32_e32 v68, v78, v68
	v_add_f32_e32 v68, v79, v68
	v_add_f32_e32 v68, 0, v68
	v_cvt_pk_bf16_f32 v146, v76, v77
	v_cvt_pk_bf16_f32 v147, v78, v79
	s_waitcnt lgkmcnt(0)
	v_mfma_f32_32x32x16_bf16 v[80:95], v[112:115], v[64:67], v[80:95]
	v_lshl_add_u64 v[64:65], v[170:171], 0, s[58:59]
	s_mov_b32 s85, m0
	s_mov_b32 m0, s16
	s_nop 0
	global_load_lds_dwordx4 v[64:65], off
	s_mov_b32 m0, s85
	v_lshl_add_u64 v[64:65], v[172:173], 0, s[58:59]
	s_addk_i32 s16, 0x2000
	s_mov_b32 s85, m0
	s_mov_b32 m0, s16
	s_nop 0
	global_load_lds_dwordx4 v[64:65], off
	s_mov_b32 m0, s85
	v_add_f32_e32 v174, v198, v68
	v_mfma_f32_32x32x16_bf16 v[48:63], v[156:159], v[178:181], v[48:63]
	ds_read_b64_tr_b16 v[76:77], v168 offset:49152
	ds_read_b64_tr_b16 v[78:79], v168 offset:49664
	v_exp_f32_e32 v96, v96
	v_exp_f32_e32 v97, v97
	v_mfma_f32_32x32x16_bf16 v[32:47], v[156:159], v[128:131], v[32:47]
	ds_read_b64_tr_b16 v[112:113], v168 offset:53248
	ds_read_b64_tr_b16 v[114:115], v168 offset:53760
	v_exp_f32_e32 v98, v98
	v_exp_f32_e32 v99, v99
	ds_read_b128 v[68:71], v189
	ds_read_b128 v[64:67], v189 offset:512
	v_mfma_f32_32x32x16_bf16 v[48:63], v[152:155], v[132:135], v[48:63]
	ds_read_b64_tr_b16 v[120:121], v168 offset:50176
	ds_read_b64_tr_b16 v[122:123], v168 offset:50688
	v_exp_f32_e32 v100, v100
	v_exp_f32_e32 v101, v101
	ds_read_b128 v[164:167], v189 offset:2048
	ds_read_b128 v[140:143], v189 offset:2560
	v_mfma_f32_32x32x16_bf16 v[32:47], v[152:155], v[136:139], v[32:47]
	ds_read_b64_tr_b16 v[178:179], v168 offset:54272
	ds_read_b64_tr_b16 v[180:181], v168 offset:54784
	v_exp_f32_e32 v102, v102
	v_exp_f32_e32 v103, v103
	ds_read_b128 v[160:163], v189 offset:4096
	ds_read_b128 v[132:135], v189 offset:4608
	v_mfma_f32_32x32x16_bf16 v[48:63], v[148:151], v[124:127], v[48:63]
	ds_read_b64_tr_b16 v[194:195], v168 offset:51200
	ds_read_b64_tr_b16 v[196:197], v168 offset:51712
	v_exp_f32_e32 v104, v104
	v_exp_f32_e32 v105, v105
	ds_read_b128 v[136:139], v189 offset:6144
	ds_read_b128 v[128:131], v189 offset:6656
	v_mfma_f32_32x32x16_bf16 v[32:47], v[148:151], v[190:193], v[32:47]
	ds_read_b64_tr_b16 v[124:125], v168 offset:55296
	ds_read_b64_tr_b16 v[126:127], v168 offset:55808
	v_exp_f32_e32 v106, v106
	v_exp_f32_e32 v107, v107
	v_mfma_f32_32x32x16_bf16 v[48:63], v[144:147], v[116:119], v[48:63]
	ds_read_b64_tr_b16 v[190:191], v168 offset:52224
	ds_read_b64_tr_b16 v[192:193], v168 offset:52736
	v_exp_f32_e32 v108, v108
	v_exp_f32_e32 v109, v109
	v_mfma_f32_32x32x16_bf16 v[32:47], v[144:147], v[72:75], v[32:47]
	ds_read_b64_tr_b16 v[116:117], v168 offset:56320
	ds_read_b64_tr_b16 v[118:119], v168 offset:56832
	v_exp_f32_e32 v110, v110
	v_exp_f32_e32 v111, v111
	s_waitcnt lgkmcnt(14)
	v_mfma_f32_32x32x16_bf16 v[16:31], v[156:159], v[76:79], v[16:31]
	v_exp_f32_e32 v80, v80
	v_exp_f32_e32 v81, v81
	v_mfma_f32_32x32x16_bf16 v[0:15], v[156:159], v[112:115], v[0:15]
	v_exp_f32_e32 v82, v82
	v_exp_f32_e32 v83, v83
	v_mfma_f32_32x32x16_bf16 v[16:31], v[152:155], v[120:123], v[16:31]
	v_exp_f32_e32 v84, v84
	v_exp_f32_e32 v85, v85
	s_waitcnt lgkmcnt(12)
	v_mfma_f32_32x32x16_bf16 v[0:15], v[152:155], v[178:181], v[0:15]
	v_exp_f32_e32 v86, v86
	v_exp_f32_e32 v87, v87
	s_waitcnt lgkmcnt(8)
	v_mfma_f32_32x32x16_bf16 v[16:31], v[148:151], v[194:197], v[16:31]
	v_exp_f32_e32 v88, v88
	v_exp_f32_e32 v89, v89
	s_waitcnt lgkmcnt(4)
	v_mfma_f32_32x32x16_bf16 v[0:15], v[148:151], v[124:127], v[0:15]
	v_exp_f32_e32 v90, v90
	v_exp_f32_e32 v91, v91
	s_waitcnt lgkmcnt(2)
	v_mfma_f32_32x32x16_bf16 v[16:31], v[144:147], v[190:193], v[16:31]
	v_exp_f32_e32 v92, v92
	v_exp_f32_e32 v93, v93
	s_waitcnt lgkmcnt(0)
	v_mfma_f32_32x32x16_bf16 v[0:15], v[144:147], v[116:119], v[0:15]
	v_exp_f32_e32 v94, v94
	v_exp_f32_e32 v95, v95
	s_waitcnt vmcnt(2) lgkmcnt(0)
	s_barrier
;   #define RESC() do{ if(!NOMAX&&resc){ asm volatile("s_waitcnt lgkmcnt(0)":::"memory"); \
;       _Pragma("unroll") for(int d_=0;d_<2*VM;++d_) _Pragma("unroll") for(int r=0;r<16;++r)o[d_][r]*=wsf[crow(r,hi)]; } }while(0)
;   #define ROT() do{sl_prev=sl_cur;sl_cur=sl_next;sl_next=(sl_next==(NSLOT-1)*SLOTB)?0:sl_next+SLOTB;}while(0)
;   #define ENDW(tt) do{ if((tt)+3<NT){ if constexpr(VM==2){WAIT_BAR(3);}else{WAIT_BAR(2);} } else if((tt)+2<NT){ if constexpr(VM==2){WAIT_BAR(2);}else{WAIT_BAR(1);} } else {WAIT_BAR(0);} }while(0)
; template<int THRL,int VM,bool NOMAX> __device__ __forceinline__ void attn_unit(const bf16*Qb,const bf16*__restrict__ Kh,const bf16*__restrict__ Vh,bf16*Ob,const int NT,const int sp,float*wscr,char*shm){
;     ...
;   for(;t+1<NT;t+=2){
;     STEP(pB0,pB1,pA0,pA1,t,(t+3<NT),(t+1<NT),(t+1<NT));       ENDW(t);   RESC(); ROT();
;     STEP(pA0,pA1,pB0,pB1,t+1,(t+4<NT),(t+2<NT),(t+2<NT));     ENDW(t+1); RESC(); ROT();
;   }
;   STEP(pB0,pB1,pA0,pA1,NT-1,false,false,false); RESC();
	ds_read_b64_tr_b16 v[178:179], v168 offset:57344
	ds_read_b64_tr_b16 v[180:181], v168 offset:57856
	v_add_f32_e32 v76, v96, v97
	ds_read_b128 v[72:75], v188
	v_add_f32_e32 v76, v98, v76
	v_add_f32_e32 v76, v99, v76
	v_add_f32_e32 v76, v100, v76
	v_add_f32_e32 v76, v101, v76
	v_cvt_pk_bf16_f32 v156, v96, v97
	v_cvt_pk_bf16_f32 v157, v98, v99
	s_waitcnt lgkmcnt(0)
	v_mfma_f32_32x32x16_bf16 v[112:127], v[68:71], v[72:75], 0
	ds_read_b64_tr_b16 v[96:97], v168 offset:61440
	ds_read_b64_tr_b16 v[98:99], v168 offset:61952
	ds_read_b128 v[68:71], v188
	v_add_f32_e32 v72, v102, v76
	v_add_f32_e32 v72, v103, v72
	v_add_f32_e32 v72, v104, v72
	v_add_f32_e32 v144, v105, v72
	s_waitcnt lgkmcnt(0)
	v_mfma_f32_32x32x16_bf16 v[64:79], v[64:67], v[68:71], 0
	v_cvt_pk_bf16_f32 v158, v100, v101
	v_cvt_pk_bf16_f32 v159, v102, v103
	ds_read_b64_tr_b16 v[100:101], v168 offset:58368
	ds_read_b64_tr_b16 v[102:103], v168 offset:58880
	ds_read_b128 v[190:193], v188 offset:1024
	v_add_f32_e32 v144, v106, v144
	v_add_f32_e32 v144, v107, v144
	v_add_f32_e32 v144, v108, v144
	v_add_f32_e32 v144, v109, v144
	v_cvt_pk_bf16_f32 v152, v104, v105
	v_cvt_pk_bf16_f32 v153, v106, v107
	s_waitcnt lgkmcnt(0)
	v_mfma_f32_32x32x16_bf16 v[112:127], v[164:167], v[190:193], v[112:127]
	ds_read_b64_tr_b16 v[104:105], v168 offset:62464
	ds_read_b64_tr_b16 v[106:107], v168 offset:62976
	ds_read_b128 v[164:167], v188 offset:1024
	v_add_f32_e32 v144, v110, v144
	v_add_f32_e32 v144, v111, v144
	v_add_f32_e32 v144, v80, v144
	v_add_f32_e32 v144, v81, v144
	s_waitcnt lgkmcnt(0)
	v_mfma_f32_32x32x16_bf16 v[64:79], v[140:143], v[164:167], v[64:79]
	v_cvt_pk_bf16_f32 v154, v108, v109
	v_cvt_pk_bf16_f32 v155, v110, v111
	ds_read_b64_tr_b16 v[108:109], v168 offset:59392
	ds_read_b64_tr_b16 v[110:111], v168 offset:59904
	ds_read_b128 v[140:143], v188 offset:2048
	v_add_f32_e32 v144, v82, v144
	v_add_f32_e32 v144, v83, v144
	v_add_f32_e32 v144, v84, v144
	v_add_f32_e32 v144, v85, v144
	v_cvt_pk_bf16_f32 v148, v80, v81
	v_cvt_pk_bf16_f32 v149, v82, v83
	s_waitcnt lgkmcnt(0)
	v_mfma_f32_32x32x16_bf16 v[112:127], v[160:163], v[140:143], v[112:127]
	ds_read_b64_tr_b16 v[190:191], v168 offset:63488
	ds_read_b64_tr_b16 v[192:193], v168 offset:64000
	ds_read_b128 v[80:83], v188 offset:2048
	v_add_f32_e32 v140, v86, v144
	v_add_f32_e32 v140, v87, v140
	v_add_f32_e32 v140, v88, v140
	v_add_f32_e32 v140, v89, v140
	s_waitcnt lgkmcnt(0)
	v_mfma_f32_32x32x16_bf16 v[64:79], v[132:135], v[80:83], v[64:79]
	v_cvt_pk_bf16_f32 v150, v84, v85
	v_cvt_pk_bf16_f32 v151, v86, v87
	ds_read_b64_tr_b16 v[84:85], v168 offset:60416
	ds_read_b64_tr_b16 v[86:87], v168 offset:60928
	ds_read_b128 v[80:83], v188 offset:3072
	v_add_f32_e32 v132, v90, v140
	v_add_f32_e32 v132, v91, v132
	v_add_f32_e32 v132, v92, v132
	v_add_f32_e32 v132, v93, v132
	v_cvt_pk_bf16_f32 v144, v88, v89
	v_cvt_pk_bf16_f32 v145, v90, v91
	s_waitcnt lgkmcnt(0)
	v_mfma_f32_32x32x16_bf16 v[112:127], v[136:139], v[80:83], v[112:127]
	ds_read_b64_tr_b16 v[88:89], v168 offset:64512
	ds_read_b64_tr_b16 v[90:91], v168 offset:65024
	ds_read_b128 v[80:83], v188 offset:3072
	v_add_f32_e32 v132, v94, v132
	v_add_f32_e32 v132, v95, v132
	v_add_f32_e32 v132, 0, v132
	v_cvt_pk_bf16_f32 v146, v92, v93
	s_waitcnt lgkmcnt(0)
	v_mfma_f32_32x32x16_bf16 v[64:79], v[128:131], v[80:83], v[64:79]
	v_cvt_pk_bf16_f32 v147, v94, v95
	v_lshl_add_u64 v[80:81], v[170:171], 0, s[62:63]
	s_mov_b32 s16, m0
	s_mov_b32 m0, s17
	s_nop 0
	global_load_lds_dwordx4 v[80:81], off
	s_mov_b32 m0, s16
	v_lshl_add_u64 v[80:81], v[172:173], 0, s[62:63]
	s_mov_b32 s16, m0
	s_mov_b32 m0, s35
	s_nop 0
	global_load_lds_dwordx4 v[80:81], off
	s_mov_b32 m0, s16
	v_add_f32_e32 v174, v174, v132
	v_mfma_f32_32x32x16_bf16 v[48:63], v[156:159], v[178:181], v[48:63]
	ds_read_b64_tr_b16 v[92:93], v177 offset:40960
	ds_read_b64_tr_b16 v[94:95], v177 offset:41472
	v_exp_f32_e32 v112, v112
	v_exp_f32_e32 v113, v113
	v_mfma_f32_32x32x16_bf16 v[32:47], v[156:159], v[96:99], v[32:47]
	ds_read_b64_tr_b16 v[170:171], v177 offset:45056
	ds_read_b64_tr_b16 v[172:173], v177 offset:45568
	v_exp_f32_e32 v114, v114
	v_exp_f32_e32 v115, v115
	ds_read_b128 v[80:83], v189 offset:8192
	ds_read_b128 v[96:99], v189 offset:8704
	v_mfma_f32_32x32x16_bf16 v[48:63], v[152:155], v[100:103], v[48:63]
	ds_read_b64_tr_b16 v[178:179], v177 offset:41984
	ds_read_b64_tr_b16 v[180:181], v177 offset:42496
	v_exp_f32_e32 v116, v116
	v_exp_f32_e32 v117, v117
	ds_read_b128 v[164:167], v189 offset:10240
	ds_read_b128 v[140:143], v189 offset:10752
	v_mfma_f32_32x32x16_bf16 v[32:47], v[152:155], v[104:107], v[32:47]
	ds_read_b64_tr_b16 v[100:101], v177 offset:46080
	ds_read_b64_tr_b16 v[102:103], v177 offset:46592
	v_exp_f32_e32 v118, v118
	v_exp_f32_e32 v119, v119
	ds_read_b128 v[160:163], v189 offset:12288
	ds_read_b128 v[132:135], v189 offset:12800
	v_mfma_f32_32x32x16_bf16 v[48:63], v[148:151], v[108:111], v[48:63]
	ds_read_b64_tr_b16 v[104:105], v177 offset:43008
	ds_read_b64_tr_b16 v[106:107], v177 offset:43520
	v_exp_f32_e32 v120, v120
	v_exp_f32_e32 v121, v121
	ds_read_b128 v[136:139], v189 offset:14336
	ds_read_b128 v[128:131], v189 offset:14848
	v_mfma_f32_32x32x16_bf16 v[32:47], v[148:151], v[190:193], v[32:47]
	ds_read_b64_tr_b16 v[108:109], v177 offset:47104
	ds_read_b64_tr_b16 v[110:111], v177 offset:47616
	v_exp_f32_e32 v122, v122
	v_exp_f32_e32 v123, v123
	v_mfma_f32_32x32x16_bf16 v[48:63], v[144:147], v[84:87], v[48:63]
	ds_read_b64_tr_b16 v[190:191], v177 offset:44032
	ds_read_b64_tr_b16 v[192:193], v177 offset:44544
	v_exp_f32_e32 v124, v124
	v_exp_f32_e32 v125, v125
	v_mfma_f32_32x32x16_bf16 v[32:47], v[144:147], v[88:91], v[32:47]
	ds_read_b64_tr_b16 v[84:85], v177 offset:48128
	ds_read_b64_tr_b16 v[86:87], v177 offset:48640
	v_exp_f32_e32 v126, v126
	v_exp_f32_e32 v127, v127
	s_waitcnt lgkmcnt(14)
	v_mfma_f32_32x32x16_bf16 v[16:31], v[156:159], v[92:95], v[16:31]
	v_exp_f32_e32 v64, v64
	v_exp_f32_e32 v65, v65
	v_mfma_f32_32x32x16_bf16 v[0:15], v[156:159], v[170:173], v[0:15]
	v_exp_f32_e32 v66, v66
	v_exp_f32_e32 v67, v67
	v_mfma_f32_32x32x16_bf16 v[16:31], v[152:155], v[178:181], v[16:31]
	v_exp_f32_e32 v68, v68
	v_exp_f32_e32 v69, v69
	s_waitcnt lgkmcnt(12)
	v_mfma_f32_32x32x16_bf16 v[0:15], v[152:155], v[100:103], v[0:15]
	v_exp_f32_e32 v70, v70
	v_exp_f32_e32 v71, v71
	s_waitcnt lgkmcnt(8)
	v_mfma_f32_32x32x16_bf16 v[16:31], v[148:151], v[104:107], v[16:31]
	v_exp_f32_e32 v72, v72
	v_exp_f32_e32 v73, v73
	s_waitcnt lgkmcnt(4)
	v_mfma_f32_32x32x16_bf16 v[0:15], v[148:151], v[108:111], v[0:15]
	v_exp_f32_e32 v74, v74
	v_exp_f32_e32 v75, v75
	s_waitcnt lgkmcnt(2)
	v_mfma_f32_32x32x16_bf16 v[16:31], v[144:147], v[190:193], v[16:31]
	v_exp_f32_e32 v76, v76
	v_exp_f32_e32 v77, v77
	s_waitcnt lgkmcnt(0)
	v_mfma_f32_32x32x16_bf16 v[0:15], v[144:147], v[84:87], v[0:15]
	v_exp_f32_e32 v78, v78
	v_exp_f32_e32 v79, v79
	s_waitcnt vmcnt(0) lgkmcnt(0)
	s_barrier
	ds_read_b64_tr_b16 v[170:171], v168 offset:24576
	ds_read_b64_tr_b16 v[172:173], v168 offset:25088
	v_add_f32_e32 v88, v112, v113
	ds_read_b128 v[84:87], v188
	v_add_f32_e32 v88, v114, v88
	v_add_f32_e32 v88, v115, v88
	v_add_f32_e32 v88, v116, v88
	v_add_f32_e32 v104, v117, v88
	v_cvt_pk_bf16_f32 v156, v112, v113
	v_cvt_pk_bf16_f32 v157, v114, v115
	s_waitcnt lgkmcnt(0)
	v_mfma_f32_32x32x16_bf16 v[80:95], v[80:83], v[84:87], 0
	ds_read_b64_tr_b16 v[112:113], v168 offset:28672
	ds_read_b64_tr_b16 v[114:115], v168 offset:29184
	ds_read_b128 v[100:103], v188
	v_add_f32_e32 v104, v118, v104
	v_add_f32_e32 v104, v119, v104
	v_add_f32_e32 v104, v120, v104
	v_add_f32_e32 v144, v121, v104
	v_cvt_pk_bf16_f32 v158, v116, v117
	v_cvt_pk_bf16_f32 v159, v118, v119
	s_waitcnt lgkmcnt(0)
	v_mfma_f32_32x32x16_bf16 v[96:111], v[96:99], v[100:103], 0
	ds_read_b64_tr_b16 v[116:117], v168 offset:25600
	ds_read_b64_tr_b16 v[118:119], v168 offset:26112
	ds_read_b128 v[178:181], v188 offset:1024
	v_add_f32_e32 v144, v122, v144
	v_add_f32_e32 v144, v123, v144
	v_add_f32_e32 v144, v124, v144
	v_add_f32_e32 v144, v125, v144
	v_cvt_pk_bf16_f32 v152, v120, v121
	v_cvt_pk_bf16_f32 v153, v122, v123
	s_waitcnt lgkmcnt(0)
	v_mfma_f32_32x32x16_bf16 v[80:95], v[164:167], v[178:181], v[80:95]
	ds_read_b64_tr_b16 v[120:121], v168 offset:29696
	ds_read_b64_tr_b16 v[122:123], v168 offset:30208
	ds_read_b128 v[164:167], v188 offset:1024
	v_add_f32_e32 v144, v126, v144
	v_add_f32_e32 v144, v127, v144
	v_add_f32_e32 v144, v64, v144
	v_add_f32_e32 v144, v65, v144
	v_cvt_pk_bf16_f32 v154, v124, v125
	v_cvt_pk_bf16_f32 v155, v126, v127
	s_waitcnt lgkmcnt(0)
	v_mfma_f32_32x32x16_bf16 v[96:111], v[140:143], v[164:167], v[96:111]
	ds_read_b64_tr_b16 v[124:125], v168 offset:26624
	ds_read_b64_tr_b16 v[126:127], v168 offset:27136
	ds_read_b128 v[140:143], v188 offset:2048
	v_add_f32_e32 v144, v66, v144
	v_add_f32_e32 v144, v67, v144
	v_add_f32_e32 v144, v68, v144
	v_add_f32_e32 v144, v69, v144
	v_cvt_pk_bf16_f32 v148, v64, v65
	v_cvt_pk_bf16_f32 v149, v66, v67
	s_waitcnt lgkmcnt(0)
	v_mfma_f32_32x32x16_bf16 v[80:95], v[160:163], v[140:143], v[80:95]
	ds_read_b64_tr_b16 v[64:65], v168 offset:30720
	ds_read_b64_tr_b16 v[66:67], v168 offset:31232
	ds_read_b128 v[140:143], v188 offset:2048
	v_add_f32_e32 v144, v70, v144
	v_add_f32_e32 v144, v71, v144
	v_add_f32_e32 v144, v72, v144
	v_add_f32_e32 v144, v73, v144
	v_cvt_pk_bf16_f32 v150, v68, v69
	v_cvt_pk_bf16_f32 v151, v70, v71
	s_waitcnt lgkmcnt(0)
	v_mfma_f32_32x32x16_bf16 v[96:111], v[132:135], v[140:143], v[96:111]
	ds_read_b64_tr_b16 v[68:69], v168 offset:27648
	ds_read_b64_tr_b16 v[70:71], v168 offset:28160
	ds_read_b128 v[132:135], v188 offset:3072
	v_add_f32_e32 v140, v74, v144
	v_add_f32_e32 v140, v75, v140
	v_add_f32_e32 v140, v76, v140
	v_add_f32_e32 v140, v77, v140
	v_cvt_pk_bf16_f32 v144, v72, v73
	v_cvt_pk_bf16_f32 v145, v74, v75
	s_waitcnt lgkmcnt(0)
	v_mfma_f32_32x32x16_bf16 v[80:95], v[136:139], v[132:135], v[80:95]
	ds_read_b64_tr_b16 v[72:73], v168 offset:31744
	ds_read_b64_tr_b16 v[74:75], v168 offset:32256
	ds_read_b128 v[132:135], v188 offset:3072
	v_add_f32_e32 v136, v78, v140
	v_add_f32_e32 v136, v79, v136
	v_add_f32_e32 v136, 0, v136
	v_cvt_pk_bf16_f32 v146, v76, v77
	v_cvt_pk_bf16_f32 v147, v78, v79
	s_waitcnt lgkmcnt(0)
	v_mfma_f32_32x32x16_bf16 v[96:111], v[128:131], v[132:135], v[96:111]
	v_mfma_f32_32x32x16_bf16 v[48:63], v[156:159], v[170:173], v[48:63]
	ds_read_b64_tr_b16 v[76:77], v168 offset:32768
	ds_read_b64_tr_b16 v[78:79], v168 offset:33280
	v_exp_f32_e32 v80, v80
	v_exp_f32_e32 v81, v81
	v_mfma_f32_32x32x16_bf16 v[32:47], v[156:159], v[112:115], v[32:47]
	ds_read_b64_tr_b16 v[128:129], v168 offset:36864
	ds_read_b64_tr_b16 v[130:131], v168 offset:37376
	v_exp_f32_e32 v82, v82
	v_exp_f32_e32 v83, v83
	v_mfma_f32_32x32x16_bf16 v[48:63], v[152:155], v[116:119], v[48:63]
	ds_read_b64_tr_b16 v[112:113], v168 offset:33792
	ds_read_b64_tr_b16 v[114:115], v168 offset:34304
	v_exp_f32_e32 v84, v84
	v_exp_f32_e32 v85, v85
	v_mfma_f32_32x32x16_bf16 v[32:47], v[152:155], v[120:123], v[32:47]
	ds_read_b64_tr_b16 v[116:117], v168 offset:37888
	ds_read_b64_tr_b16 v[118:119], v168 offset:38400
	v_exp_f32_e32 v86, v86
	v_exp_f32_e32 v87, v87
	v_mfma_f32_32x32x16_bf16 v[48:63], v[148:151], v[124:127], v[48:63]
	ds_read_b64_tr_b16 v[120:121], v168 offset:34816
	ds_read_b64_tr_b16 v[122:123], v168 offset:35328
	v_exp_f32_e32 v88, v88
	v_exp_f32_e32 v89, v89
	v_mfma_f32_32x32x16_bf16 v[32:47], v[148:151], v[64:67], v[32:47]
	ds_read_b64_tr_b16 v[124:125], v168 offset:38912
	ds_read_b64_tr_b16 v[126:127], v168 offset:39424
	v_exp_f32_e32 v90, v90
	v_exp_f32_e32 v91, v91
	v_mfma_f32_32x32x16_bf16 v[48:63], v[144:147], v[68:71], v[48:63]
	ds_read_b64_tr_b16 v[64:65], v168 offset:35840
	ds_read_b64_tr_b16 v[66:67], v168 offset:36352
	v_exp_f32_e32 v92, v92
	v_exp_f32_e32 v93, v93
	v_mfma_f32_32x32x16_bf16 v[32:47], v[144:147], v[72:75], v[32:47]
	ds_read_b64_tr_b16 v[68:69], v168 offset:39936
	ds_read_b64_tr_b16 v[70:71], v168 offset:40448
	v_exp_f32_e32 v94, v94
	v_exp_f32_e32 v95, v95
	s_waitcnt lgkmcnt(14)
	v_mfma_f32_32x32x16_bf16 v[16:31], v[156:159], v[76:79], v[16:31]
	v_exp_f32_e32 v96, v96
	v_exp_f32_e32 v97, v97
	s_waitcnt lgkmcnt(12)
; #define SBAR() __builtin_amdgcn_sched_barrier(0)
;   #define PKW(P,B) cvtpk_s(P[B],P[B+1])
; __device__ __forceinline__ void pv(f32x16*o,int vb,bf16x8 pa0,bf16x8 pa1,bf16x8 pa2,bf16x8 pa3){
;   #pragma unroll
;   for(int d0=0;d0<2;++d0){s16x4 lo[4],hi[4];
;     #pragma unroll
;     for(int ks=0;ks<4;++ks){
;       asm volatile("ds_read_b64_tr_b16 %0,%1 offset:%c2":"=&v"(lo[ks]):"v"(vb),"i"(d0*4096+ks*1024):"memory");
;       asm volatile("ds_read_b64_tr_b16 %0,%1 offset:%c2":"=&v"(hi[ks]):"v"(vb),"i"(d0*4096+ks*1024+512):"memory");}
;     asm volatile("s_waitcnt lgkmcnt(0)":::"memory");SBAR();
;     ...
;     o[d0]=__builtin_amdgcn_mfma_f32_32x32x16_bf16(pa0,PK(0),o[d0],0,0,0);
;     o[d0]=__builtin_amdgcn_mfma_f32_32x32x16_bf16(pa1,PK(1),o[d0],0,0,0);
;     o[d0]=__builtin_amdgcn_mfma_f32_32x32x16_bf16(pa2,PK(2),o[d0],0,0,0);
;     o[d0]=__builtin_amdgcn_mfma_f32_32x32x16_bf16(pa3,PK(3),o[d0],0,0,0);
;     ...
;   }
; }
; template<int THRL,int VM,bool NOMAX> __device__ __forceinline__ void attn_unit(const bf16*Qb,const bf16*__restrict__ Kh,const bf16*__restrict__ Vh,bf16*Ob,const int NT,const int sp,float*wscr,char*shm){
;     ...
;   { float sacc=pB0[0]+pB0[1]; _Pragma("unroll") for(int r=2;r<16;++r)sacc+=pB0[r]; _Pragma("unroll") for(int r=0;r<16;++r)sacc+=pB1[r]; l_reg+=sacc;
;     pw0=(u32x4){PKW(pB0,0),PKW(pB0,2),PKW(pB0,4),PKW(pB0,6)};pw1=(u32x4){PKW(pB0,8),PKW(pB0,10),PKW(pB0,12),PKW(pB0,14)};pw2=(u32x4){PKW(pB1,0),PKW(pB1,2),PKW(pB1,4),PKW(pB1,6)};pw3=(u32x4){PKW(pB1,8),PKW(pB1,10),PKW(pB1,12),PKW(pB1,14)};
;     SBAR(); pv(o,vb0+VM*sl_cur,PAF(0),PAF(1),PAF(2),PAF(3)); if constexpr(VM==2) pv(o+2,vb0+VM*sl_cur+8192,PAF(0),PAF(1),PAF(2),PAF(3)); }
;     ...
;   {auto rr=__builtin_amdgcn_permlane32_swap(__float_as_uint(l_reg),__float_as_uint(l_reg),false,false);l_reg=__uint_as_float(rr[0])+__uint_as_float(rr[1]);}
;   if(hi==0)wsf[32+r32]=l_reg;asm volatile("s_waitcnt lgkmcnt(0)":::"memory");
	v_mfma_f32_32x32x16_bf16 v[0:15], v[156:159], v[128:131], v[0:15]
	v_exp_f32_e32 v98, v98
	v_exp_f32_e32 v99, v99
	s_waitcnt lgkmcnt(10)
	v_mfma_f32_32x32x16_bf16 v[16:31], v[152:155], v[112:115], v[16:31]
	v_exp_f32_e32 v100, v100
	v_exp_f32_e32 v101, v101
	s_waitcnt lgkmcnt(8)
	v_mfma_f32_32x32x16_bf16 v[0:15], v[152:155], v[116:119], v[0:15]
	v_exp_f32_e32 v102, v102
	v_exp_f32_e32 v103, v103
	s_waitcnt lgkmcnt(6)
	v_mfma_f32_32x32x16_bf16 v[16:31], v[148:151], v[120:123], v[16:31]
	v_exp_f32_e32 v104, v104
	v_exp_f32_e32 v105, v105
	s_waitcnt lgkmcnt(4)
	v_mfma_f32_32x32x16_bf16 v[0:15], v[148:151], v[124:127], v[0:15]
	v_exp_f32_e32 v106, v106
	v_exp_f32_e32 v107, v107
	s_waitcnt lgkmcnt(2)
	v_mfma_f32_32x32x16_bf16 v[16:31], v[144:147], v[64:67], v[16:31]
	v_exp_f32_e32 v108, v108
	v_exp_f32_e32 v109, v109
	s_waitcnt lgkmcnt(0)
	v_mfma_f32_32x32x16_bf16 v[0:15], v[144:147], v[68:71], v[0:15]
	v_exp_f32_e32 v110, v110
	v_exp_f32_e32 v111, v111
	v_add_f32_e32 v64, v80, v81
	v_add_f32_e32 v64, v82, v64
	v_add_f32_e32 v64, v83, v64
	v_add_f32_e32 v64, v84, v64
	v_add_f32_e32 v64, v85, v64
	v_add_f32_e32 v64, v86, v64
	v_add_f32_e32 v64, v87, v64
	v_add_f32_e32 v64, v88, v64
	v_add_f32_e32 v64, v89, v64
	v_add_f32_e32 v64, v90, v64
	v_add_f32_e32 v64, v91, v64
	v_add_f32_e32 v64, v92, v64
	v_add_f32_e32 v64, v93, v64
	v_add_f32_e32 v64, v94, v64
	v_add_f32_e32 v64, v95, v64
	v_add_f32_e32 v64, v64, v96
	v_add_f32_e32 v64, v97, v64
	v_add_f32_e32 v64, v98, v64
	v_add_f32_e32 v64, v99, v64
	v_add_f32_e32 v64, v100, v64
	v_add_f32_e32 v64, v101, v64
	v_add_f32_e32 v64, v102, v64
	v_add_f32_e32 v64, v103, v64
	v_add_f32_e32 v64, v104, v64
	v_add_f32_e32 v64, v105, v64
	v_add_f32_e32 v64, v106, v64
	v_add_f32_e32 v64, v107, v64
	v_add_f32_e32 v64, v108, v64
	v_add_f32_e32 v64, v109, v64
	v_add_f32_e32 v64, v110, v64
	v_add_f32_e32 v64, v111, v64
	v_add_f32_e32 v65, v174, v136
	v_add_f32_e32 v64, v65, v64
	v_cvt_pk_bf16_f32 v66, v80, v81
	v_cvt_pk_bf16_f32 v67, v82, v83
	v_cvt_pk_bf16_f32 v68, v84, v85
	v_cvt_pk_bf16_f32 v69, v86, v87
	v_cvt_pk_bf16_f32 v70, v88, v89
	v_cvt_pk_bf16_f32 v71, v90, v91
	v_cvt_pk_bf16_f32 v72, v92, v93
	v_cvt_pk_bf16_f32 v73, v94, v95
	v_cvt_pk_bf16_f32 v74, v96, v97
	v_cvt_pk_bf16_f32 v75, v98, v99
	v_cvt_pk_bf16_f32 v76, v100, v101
	v_cvt_pk_bf16_f32 v77, v102, v103
	v_cvt_pk_bf16_f32 v78, v104, v105
	v_cvt_pk_bf16_f32 v79, v106, v107
	v_cvt_pk_bf16_f32 v80, v108, v109
	v_cvt_pk_bf16_f32 v81, v110, v111
	v_add_u32_e32 v65, 0x4000, v176
	ds_read_b64_tr_b16 v[82:83],v65 offset:0
	ds_read_b64_tr_b16 v[84:85],v65 offset:512
	ds_read_b64_tr_b16 v[86:87],v65 offset:1024
	ds_read_b64_tr_b16 v[88:89],v65 offset:1536
	ds_read_b64_tr_b16 v[90:91],v65 offset:2048
	ds_read_b64_tr_b16 v[92:93],v65 offset:2560
	ds_read_b64_tr_b16 v[94:95],v65 offset:3072
	ds_read_b64_tr_b16 v[96:97],v65 offset:3584
	s_waitcnt lgkmcnt(0)
	s_nop 0
	v_mfma_f32_32x32x16_bf16 v[48:63], v[66:69], v[82:85], v[48:63]
	ds_read_b64_tr_b16 v[82:83],v65 offset:4096
	ds_read_b64_tr_b16 v[84:85],v65 offset:4608
	v_mfma_f32_32x32x16_bf16 v[48:63], v[70:73], v[86:89], v[48:63]
	ds_read_b64_tr_b16 v[86:87],v65 offset:5120
	ds_read_b64_tr_b16 v[88:89],v65 offset:5632
	v_mfma_f32_32x32x16_bf16 v[48:63], v[74:77], v[90:93], v[48:63]
	ds_read_b64_tr_b16 v[90:91],v65 offset:6144
	ds_read_b64_tr_b16 v[92:93],v65 offset:6656
	ds_read_b64_tr_b16 v[98:99],v65 offset:7168
	ds_read_b64_tr_b16 v[100:101],v65 offset:7680
	s_waitcnt lgkmcnt(0)
	v_mfma_f32_32x32x16_bf16 v[48:63], v[78:81], v[94:97], v[48:63]
	v_mfma_f32_32x32x16_bf16 v[32:47], v[66:69], v[82:85], v[32:47]
	v_add_u32_e32 v65, 0x6000, v176
	ds_read_b64_tr_b16 v[82:83],v65 offset:0
	ds_read_b64_tr_b16 v[84:85],v65 offset:512
	v_mfma_f32_32x32x16_bf16 v[32:47], v[70:73], v[86:89], v[32:47]
	ds_read_b64_tr_b16 v[86:87],v65 offset:1024
	ds_read_b64_tr_b16 v[88:89],v65 offset:1536
	v_mfma_f32_32x32x16_bf16 v[32:47], v[74:77], v[90:93], v[32:47]
	ds_read_b64_tr_b16 v[90:91],v65 offset:2048
	ds_read_b64_tr_b16 v[92:93],v65 offset:2560
	ds_read_b64_tr_b16 v[94:95],v65 offset:3072
	ds_read_b64_tr_b16 v[96:97],v65 offset:3584
	s_waitcnt lgkmcnt(0)
	v_mfma_f32_32x32x16_bf16 v[32:47], v[78:81], v[98:101], v[32:47]
	v_mfma_f32_32x32x16_bf16 v[16:31], v[66:69], v[82:85], v[16:31]
	ds_read_b64_tr_b16 v[82:83],v65 offset:4096
	ds_read_b64_tr_b16 v[84:85],v65 offset:4608
	v_mfma_f32_32x32x16_bf16 v[16:31], v[70:73], v[86:89], v[16:31]
	ds_read_b64_tr_b16 v[86:87],v65 offset:5120
	ds_read_b64_tr_b16 v[88:89],v65 offset:5632
	v_mfma_f32_32x32x16_bf16 v[16:31], v[74:77], v[90:93], v[16:31]
	ds_read_b64_tr_b16 v[90:91],v65 offset:6144
	ds_read_b64_tr_b16 v[92:93],v65 offset:6656
	ds_read_b64_tr_b16 v[98:99],v65 offset:7168
	ds_read_b64_tr_b16 v[100:101],v65 offset:7680
	s_waitcnt lgkmcnt(0)
	v_mfma_f32_32x32x16_bf16 v[16:31], v[78:81], v[94:97], v[16:31]
	v_mfma_f32_32x32x16_bf16 v[0:15], v[66:69], v[82:85], v[0:15]
	v_mov_b32_e32 v65, v64
	s_nop 1
	v_permlane32_swap_b32_e32 v64, v65
	v_cmp_gt_u32_e32 vcc, 32, v187
	v_mfma_f32_32x32x16_bf16 v[0:15], v[70:73], v[86:89], v[0:15]
	v_mfma_f32_32x32x16_bf16 v[0:15], v[74:77], v[90:93], v[0:15]
	v_mfma_f32_32x32x16_bf16 v[0:15], v[78:81], v[98:101], v[0:15]
	s_and_saveexec_b64 s[16:17], vcc
	s_cbranch_execz .LBB0_859
	v_add_f32_e32 v64, v64, v65
	v_lshl_add_u32 v65, v186, 2, s34
	ds_write_b32 v65, v64 offset:128
	s_branch .LBB0_859

; __device__ __forceinline__ void glds16(const void*gsrc,unsigned lds_dst){unsigned keep;
;   asm volatile("s_mov_b32 %0, m0\n\ts_mov_b32 m0, %2\n\ts_nop 0\n\tglobal_load_lds_dwordx4 %1, off\n\ts_mov_b32 m0, %0":"=&s"(keep):"v"(gsrc),"s"(lds_dst):"memory");}
.LBB0_874:
	v_lshl_add_u32 v206, s89, 1, v188
	ds_read_b64_tr_b16 v[194:195], v206 offset:24576
	ds_read_b64_tr_b16 v[196:197], v206 offset:25088
	v_add_f32_e32 v108, v80, v81
	ds_read_b128 v[246:249], v168 offset:1024
	v_add_f32_e32 v108, v82, v108
	v_add_f32_e32 v108, v83, v108
	v_add_f32_e32 v108, v84, v108
	v_add_f32_e32 v108, v85, v108
	v_cvt_pk_bf16_f32 v156, v80, v81
	v_cvt_pk_bf16_f32 v157, v82, v83
	v_mfma_f32_32x32x16_bf16 v[112:127], v[100:103], v[242:245], 0
	ds_read_b64_tr_b16 v[80:81], v206 offset:28672
	ds_read_b64_tr_b16 v[82:83], v206 offset:29184
	v_add_f32_e32 v104, v86, v108
	v_add_f32_e32 v104, v87, v104
	v_add_f32_e32 v104, v88, v104
	v_add_f32_e32 v144, v89, v104
	v_mfma_f32_32x32x16_bf16 v[96:111], v[96:99], v[242:245], 0
	v_cvt_pk_bf16_f32 v158, v84, v85
	v_cvt_pk_bf16_f32 v159, v86, v87
	ds_read_b64_tr_b16 v[84:85], v206 offset:25600
	ds_read_b64_tr_b16 v[86:87], v206 offset:26112
	ds_read_b128 v[242:245], v168 offset:2048
	v_add_f32_e32 v144, v90, v144
	v_add_f32_e32 v144, v91, v144
	v_add_f32_e32 v144, v92, v144
	v_add_f32_e32 v144, v93, v144
	v_cvt_pk_bf16_f32 v152, v88, v89
	v_cvt_pk_bf16_f32 v153, v90, v91
	s_waitcnt lgkmcnt(5)
	v_mfma_f32_32x32x16_bf16 v[112:127], v[164:167], v[246:249], v[112:127]
	ds_read_b64_tr_b16 v[88:89], v206 offset:29696
	ds_read_b64_tr_b16 v[90:91], v206 offset:30208
	v_add_f32_e32 v144, v94, v144
	v_add_f32_e32 v144, v95, v144
	v_add_f32_e32 v144, v64, v144
	v_add_f32_e32 v144, v65, v144
	v_mfma_f32_32x32x16_bf16 v[96:111], v[160:163], v[246:249], v[96:111]
	v_cvt_pk_bf16_f32 v154, v92, v93
	v_cvt_pk_bf16_f32 v155, v94, v95
	ds_read_b64_tr_b16 v[92:93], v206 offset:26624
	ds_read_b64_tr_b16 v[94:95], v206 offset:27136
	ds_read_b128 v[246:249], v168 offset:3072
	v_add_f32_e32 v144, v66, v144
	v_add_f32_e32 v144, v67, v144
	v_add_f32_e32 v144, v68, v144
	v_add_f32_e32 v144, v69, v144
	v_cvt_pk_bf16_f32 v148, v64, v65
	v_cvt_pk_bf16_f32 v149, v66, v67
	s_waitcnt lgkmcnt(5)
	v_mfma_f32_32x32x16_bf16 v[112:127], v[140:143], v[242:245], v[112:127]
	ds_read_b64_tr_b16 v[198:199], v206 offset:30720
	ds_read_b64_tr_b16 v[200:201], v206 offset:31232
	v_add_f32_e32 v140, v70, v144
	v_add_f32_e32 v140, v71, v140
	v_add_f32_e32 v140, v72, v140
	v_add_f32_e32 v140, v73, v140
	v_mfma_f32_32x32x16_bf16 v[96:111], v[136:139], v[242:245], v[96:111]
	v_cvt_pk_bf16_f32 v150, v68, v69
	v_cvt_pk_bf16_f32 v151, v70, v71
	ds_read_b64_tr_b16 v[202:203], v206 offset:27648
	ds_read_b64_tr_b16 v[204:205], v206 offset:28160
	v_add_f32_e32 v68, v74, v140
	v_add_f32_e32 v68, v75, v68
	v_add_f32_e32 v68, v76, v68
	v_add_f32_e32 v68, v77, v68
	v_cvt_pk_bf16_f32 v144, v72, v73
	v_cvt_pk_bf16_f32 v145, v74, v75
	s_waitcnt lgkmcnt(4)
	v_mfma_f32_32x32x16_bf16 v[112:127], v[132:135], v[246:249], v[112:127]
	ds_read_b64_tr_b16 v[72:73], v206 offset:31744
	ds_read_b64_tr_b16 v[74:75], v206 offset:32256
	v_add_f32_e32 v68, v78, v68
	v_add_f32_e32 v68, v79, v68
	v_cvt_pk_bf16_f32 v146, v76, v77
	v_mfma_f32_32x32x16_bf16 v[96:111], v[128:131], v[246:249], v[96:111]
	v_cvt_pk_bf16_f32 v147, v78, v79
	s_add_i32 m0, s87, s17
	v_lshl_add_u64 v[64:65], v[180:181], 0, s[56:57]
	global_load_lds_dwordx4 v[64:65], off
	s_lshl_b32 s88, s86, 1
	s_add_i32 s88, s88, s16
	s_mov_b32 m0, s88
	v_lshl_add_u64 v[64:65], v[178:179], 0, s[56:57]
	global_load_lds_dwordx4 v[64:65], off
	s_addk_i32 m0, 0x2000
	v_lshl_add_u64 v[64:65], v[176:177], 0, s[56:57]
	global_load_lds_dwordx4 v[64:65], off
	v_add_f32_e32 v193, v193, v68
	v_mfma_f32_32x32x16_bf16 v[48:63], v[156:159], v[194:197], v[48:63]
	ds_read_b64_tr_b16 v[76:77], v206 offset:32768
	ds_read_b64_tr_b16 v[78:79], v206 offset:33280
	v_exp_f32_e32 v112, v112
	v_exp_f32_e32 v113, v113
	v_mfma_f32_32x32x16_bf16 v[32:47], v[156:159], v[80:83], v[32:47]
	ds_read_b64_tr_b16 v[194:195], v206 offset:36864
	ds_read_b64_tr_b16 v[196:197], v206 offset:37376
	v_exp_f32_e32 v114, v114
	v_exp_f32_e32 v115, v115
	v_add_u32_e32 v128, s86, v189
	ds_read_b128 v[68:71], v128
	ds_read_b128 v[64:67], v128 offset:512
	v_mfma_f32_32x32x16_bf16 v[48:63], v[152:155], v[84:87], v[48:63]
	ds_read_b64_tr_b16 v[80:81], v206 offset:33792
	ds_read_b64_tr_b16 v[82:83], v206 offset:34304
	v_exp_f32_e32 v116, v116
	v_exp_f32_e32 v117, v117
	ds_read_b128 v[164:167], v128 offset:2048
	ds_read_b128 v[140:143], v128 offset:2560
	v_mfma_f32_32x32x16_bf16 v[32:47], v[152:155], v[88:91], v[32:47]
	ds_read_b64_tr_b16 v[84:85], v206 offset:37888
	ds_read_b64_tr_b16 v[86:87], v206 offset:38400
	v_exp_f32_e32 v118, v118
	v_exp_f32_e32 v119, v119
	ds_read_b128 v[160:163], v128 offset:4096
	ds_read_b128 v[132:135], v128 offset:4608
	v_mfma_f32_32x32x16_bf16 v[48:63], v[148:151], v[92:95], v[48:63]
	ds_read_b64_tr_b16 v[88:89], v206 offset:34816
	ds_read_b64_tr_b16 v[90:91], v206 offset:35328
	v_exp_f32_e32 v120, v120
	v_exp_f32_e32 v121, v121
	ds_read_b128 v[136:139], v128 offset:6144
	ds_read_b128 v[128:131], v128 offset:6656
	s_waitcnt lgkmcnt(14)
	v_mfma_f32_32x32x16_bf16 v[32:47], v[148:151], v[198:201], v[32:47]
	ds_read_b64_tr_b16 v[92:93], v206 offset:38912
	ds_read_b64_tr_b16 v[94:95], v206 offset:39424
	v_exp_f32_e32 v122, v122
	v_exp_f32_e32 v123, v123
	v_mfma_f32_32x32x16_bf16 v[48:63], v[144:147], v[202:205], v[48:63]
	ds_read_b64_tr_b16 v[198:199], v206 offset:35840
	ds_read_b64_tr_b16 v[200:201], v206 offset:36352
	v_exp_f32_e32 v124, v124
	v_exp_f32_e32 v125, v125
	v_mfma_f32_32x32x16_bf16 v[32:47], v[144:147], v[72:75], v[32:47]
	ds_read_b64_tr_b16 v[202:203], v206 offset:39936
	ds_read_b64_tr_b16 v[204:205], v206 offset:40448
	v_exp_f32_e32 v126, v126
	v_exp_f32_e32 v127, v127
	s_waitcnt lgkmcnt(14)
	v_mfma_f32_32x32x16_bf16 v[16:31], v[156:159], v[76:79], v[16:31]
	v_exp_f32_e32 v96, v96
	v_exp_f32_e32 v97, v97
	v_mfma_f32_32x32x16_bf16 v[0:15], v[156:159], v[194:197], v[0:15]
	v_exp_f32_e32 v98, v98
	v_exp_f32_e32 v99, v99
	v_mfma_f32_32x32x16_bf16 v[16:31], v[152:155], v[80:83], v[16:31]
	v_exp_f32_e32 v100, v100
	v_exp_f32_e32 v101, v101
	s_waitcnt lgkmcnt(8)
	v_mfma_f32_32x32x16_bf16 v[0:15], v[152:155], v[84:87], v[0:15]
	v_exp_f32_e32 v102, v102
	v_exp_f32_e32 v103, v103
	v_mfma_f32_32x32x16_bf16 v[16:31], v[148:151], v[88:91], v[16:31]
	v_exp_f32_e32 v104, v104
	v_exp_f32_e32 v105, v105
	s_waitcnt lgkmcnt(2)
	v_mfma_f32_32x32x16_bf16 v[0:15], v[148:151], v[92:95], v[0:15]
	v_exp_f32_e32 v106, v106
	v_exp_f32_e32 v107, v107
	v_mfma_f32_32x32x16_bf16 v[16:31], v[144:147], v[198:201], v[16:31]
	v_exp_f32_e32 v108, v108
	v_exp_f32_e32 v109, v109
	s_waitcnt lgkmcnt(0)
	v_mfma_f32_32x32x16_bf16 v[0:15], v[144:147], v[202:205], v[0:15]
	ds_read_b128 v[242:245], v168
	v_exp_f32_e32 v110, v110
	v_exp_f32_e32 v111, v111
	s_waitcnt vmcnt(3) lgkmcnt(0)
	s_barrier
; __device__ __forceinline__ void glds16(const void*gsrc,unsigned lds_dst){unsigned keep;
;   asm volatile("s_mov_b32 %0, m0\n\ts_mov_b32 m0, %2\n\ts_nop 0\n\tglobal_load_lds_dwordx4 %1, off\n\ts_mov_b32 m0, %0":"=&s"(keep):"v"(gsrc),"s"(lds_dst):"memory");}
	s_add_i32 s88, s86, 0x2000
	s_cmpk_lg_i32 s86, 0x4000
	s_cselect_b32 s88, s88, 0
	v_lshl_add_u32 v206, s87, 1, v188
	ds_read_b64_tr_b16 v[194:195], v206 offset:24576
	ds_read_b64_tr_b16 v[196:197], v206 offset:25088
	ds_read_b128 v[246:249], v168 offset:1024
	v_add_f32_e32 v76, v112, v113
	v_add_f32_e32 v76, v114, v76
	v_add_f32_e32 v76, v115, v76
	v_add_f32_e32 v76, v116, v76
	v_mfma_f32_32x32x16_bf16 v[80:95], v[68:71], v[242:245], 0
	v_add_f32_e32 v76, v117, v76
	v_cvt_pk_bf16_f32 v156, v112, v113
	v_cvt_pk_bf16_f32 v157, v114, v115
	ds_read_b64_tr_b16 v[112:113], v206 offset:28672
	ds_read_b64_tr_b16 v[114:115], v206 offset:29184
	v_add_f32_e32 v72, v118, v76
	v_add_f32_e32 v72, v119, v72
	v_add_f32_e32 v72, v120, v72
	v_add_f32_e32 v144, v121, v72
	v_mfma_f32_32x32x16_bf16 v[64:79], v[64:67], v[242:245], 0
	v_cvt_pk_bf16_f32 v158, v116, v117
	v_cvt_pk_bf16_f32 v159, v118, v119
	ds_read_b64_tr_b16 v[116:117], v206 offset:25600
	ds_read_b64_tr_b16 v[118:119], v206 offset:26112
	ds_read_b128 v[242:245], v168 offset:2048
	v_add_f32_e32 v144, v122, v144
	v_add_f32_e32 v144, v123, v144
	v_add_f32_e32 v144, v124, v144
	v_add_f32_e32 v144, v125, v144
	s_waitcnt lgkmcnt(5)
	v_mfma_f32_32x32x16_bf16 v[80:95], v[164:167], v[246:249], v[80:95]
	v_cvt_pk_bf16_f32 v152, v120, v121
	v_cvt_pk_bf16_f32 v153, v122, v123
	ds_read_b64_tr_b16 v[120:121], v206 offset:29696
	ds_read_b64_tr_b16 v[122:123], v206 offset:30208
	v_add_f32_e32 v144, v126, v144
	v_add_f32_e32 v144, v127, v144
	v_add_f32_e32 v144, v96, v144
	v_add_f32_e32 v144, v97, v144
	v_mfma_f32_32x32x16_bf16 v[64:79], v[140:143], v[246:249], v[64:79]
	v_cvt_pk_bf16_f32 v154, v124, v125
	v_cvt_pk_bf16_f32 v155, v126, v127
	ds_read_b64_tr_b16 v[124:125], v206 offset:26624
	ds_read_b64_tr_b16 v[126:127], v206 offset:27136
	ds_read_b128 v[246:249], v168 offset:3072
	v_add_f32_e32 v144, v98, v144
	v_add_f32_e32 v144, v99, v144
	v_add_f32_e32 v144, v100, v144
	v_add_f32_e32 v144, v101, v144
	s_waitcnt lgkmcnt(5)
	v_mfma_f32_32x32x16_bf16 v[80:95], v[160:163], v[242:245], v[80:95]
	v_cvt_pk_bf16_f32 v148, v96, v97
	v_cvt_pk_bf16_f32 v149, v98, v99
	ds_read_b64_tr_b16 v[198:199], v206 offset:30720
	ds_read_b64_tr_b16 v[200:201], v206 offset:31232
	v_add_f32_e32 v140, v102, v144
	v_add_f32_e32 v140, v103, v140
	v_add_f32_e32 v140, v104, v140
	v_add_f32_e32 v140, v105, v140
	v_mfma_f32_32x32x16_bf16 v[64:79], v[132:135], v[242:245], v[64:79]
	v_cvt_pk_bf16_f32 v150, v100, v101
	v_cvt_pk_bf16_f32 v151, v102, v103
	ds_read_b64_tr_b16 v[202:203], v206 offset:27648
	ds_read_b64_tr_b16 v[204:205], v206 offset:28160
	v_add_f32_e32 v100, v106, v140
	v_add_f32_e32 v100, v107, v100
	v_add_f32_e32 v100, v108, v100
	v_add_f32_e32 v100, v109, v100
	s_waitcnt lgkmcnt(4)
	v_mfma_f32_32x32x16_bf16 v[80:95], v[136:139], v[246:249], v[80:95]
	v_cvt_pk_bf16_f32 v144, v104, v105
	v_cvt_pk_bf16_f32 v145, v106, v107
	ds_read_b64_tr_b16 v[104:105], v206 offset:31744
	ds_read_b64_tr_b16 v[106:107], v206 offset:32256
	v_add_f32_e32 v100, v110, v100
	v_add_f32_e32 v100, v111, v100
	v_cvt_pk_bf16_f32 v146, v108, v109
	v_mfma_f32_32x32x16_bf16 v[64:79], v[128:131], v[246:249], v[64:79]
	v_cvt_pk_bf16_f32 v147, v110, v111
	s_add_i32 m0, s86, s17
	s_nop 0
	global_load_lds_dwordx4 v[180:181], off
	s_lshl_b32 s87, s88, 1
	s_add_i32 s87, s87, s16
	s_mov_b32 m0, s87
	s_nop 0
	global_load_lds_dwordx4 v[178:179], off
	s_addk_i32 m0, 0x2000
	s_nop 0
	global_load_lds_dwordx4 v[176:177], off
	v_add_f32_e32 v193, v193, v100
	v_mfma_f32_32x32x16_bf16 v[48:63], v[156:159], v[194:197], v[48:63]
	ds_read_b64_tr_b16 v[108:109], v206 offset:32768
	ds_read_b64_tr_b16 v[110:111], v206 offset:33280
	v_exp_f32_e32 v80, v80
	v_exp_f32_e32 v81, v81
	v_mfma_f32_32x32x16_bf16 v[32:47], v[156:159], v[112:115], v[32:47]
	ds_read_b64_tr_b16 v[194:195], v206 offset:36864
	ds_read_b64_tr_b16 v[196:197], v206 offset:37376
	v_exp_f32_e32 v82, v82
	v_exp_f32_e32 v83, v83
	v_add_u32_e32 v128, s88, v189
	ds_read_b128 v[100:103], v128
	ds_read_b128 v[96:99], v128 offset:512
	v_mfma_f32_32x32x16_bf16 v[48:63], v[152:155], v[116:119], v[48:63]
	ds_read_b64_tr_b16 v[112:113], v206 offset:33792
	ds_read_b64_tr_b16 v[114:115], v206 offset:34304
	v_exp_f32_e32 v84, v84
	v_exp_f32_e32 v85, v85
	ds_read_b128 v[164:167], v128 offset:2048
	ds_read_b128 v[160:163], v128 offset:2560
	v_mfma_f32_32x32x16_bf16 v[32:47], v[152:155], v[120:123], v[32:47]
	ds_read_b64_tr_b16 v[116:117], v206 offset:37888
	ds_read_b64_tr_b16 v[118:119], v206 offset:38400
	v_exp_f32_e32 v86, v86
	v_exp_f32_e32 v87, v87
	ds_read_b128 v[140:143], v128 offset:4096
	ds_read_b128 v[136:139], v128 offset:4608
	v_mfma_f32_32x32x16_bf16 v[48:63], v[148:151], v[124:127], v[48:63]
	ds_read_b64_tr_b16 v[120:121], v206 offset:34816
	ds_read_b64_tr_b16 v[122:123], v206 offset:35328
	v_exp_f32_e32 v88, v88
	v_exp_f32_e32 v89, v89
	ds_read_b128 v[132:135], v128 offset:6144
	ds_read_b128 v[128:131], v128 offset:6656
	s_waitcnt lgkmcnt(14)
	v_mfma_f32_32x32x16_bf16 v[32:47], v[148:151], v[198:201], v[32:47]
	ds_read_b64_tr_b16 v[124:125], v206 offset:38912
	ds_read_b64_tr_b16 v[126:127], v206 offset:39424
	v_exp_f32_e32 v90, v90
	v_exp_f32_e32 v91, v91
	v_mfma_f32_32x32x16_bf16 v[48:63], v[144:147], v[202:205], v[48:63]
	ds_read_b64_tr_b16 v[198:199], v206 offset:35840
	ds_read_b64_tr_b16 v[200:201], v206 offset:36352
	v_exp_f32_e32 v92, v92
	v_exp_f32_e32 v93, v93
	v_mfma_f32_32x32x16_bf16 v[32:47], v[144:147], v[104:107], v[32:47]
	ds_read_b64_tr_b16 v[202:203], v206 offset:39936
	ds_read_b64_tr_b16 v[204:205], v206 offset:40448
	v_exp_f32_e32 v94, v94
	v_exp_f32_e32 v95, v95
	s_waitcnt lgkmcnt(14)
	v_mfma_f32_32x32x16_bf16 v[16:31], v[156:159], v[108:111], v[16:31]
	v_exp_f32_e32 v64, v64
	v_exp_f32_e32 v65, v65
	v_mfma_f32_32x32x16_bf16 v[0:15], v[156:159], v[194:197], v[0:15]
	v_exp_f32_e32 v66, v66
	v_exp_f32_e32 v67, v67
	v_mfma_f32_32x32x16_bf16 v[16:31], v[152:155], v[112:115], v[16:31]
	v_exp_f32_e32 v68, v68
	v_exp_f32_e32 v69, v69
	s_waitcnt lgkmcnt(8)
	v_mfma_f32_32x32x16_bf16 v[0:15], v[152:155], v[116:119], v[0:15]
	v_exp_f32_e32 v70, v70
	v_exp_f32_e32 v71, v71
	v_mfma_f32_32x32x16_bf16 v[16:31], v[148:151], v[120:123], v[16:31]
	v_exp_f32_e32 v72, v72
	v_exp_f32_e32 v73, v73
	s_waitcnt lgkmcnt(2)
	v_mfma_f32_32x32x16_bf16 v[0:15], v[148:151], v[124:127], v[0:15]
	v_exp_f32_e32 v74, v74
	v_exp_f32_e32 v75, v75
	v_mfma_f32_32x32x16_bf16 v[16:31], v[144:147], v[198:201], v[16:31]
	v_exp_f32_e32 v76, v76
	v_exp_f32_e32 v77, v77
	s_waitcnt lgkmcnt(0)
	v_mfma_f32_32x32x16_bf16 v[0:15], v[144:147], v[202:205], v[0:15]
	ds_read_b128 v[242:245], v168
	v_exp_f32_e32 v78, v78
	v_exp_f32_e32 v79, v79
	s_add_i32 s90, s88, 0x2000
	s_waitcnt vmcnt(3) lgkmcnt(0)
	s_barrier
; #define WAIT_BAR(N) asm volatile("s_waitcnt vmcnt(" #N ") lgkmcnt(0)\n\ts_barrier":::"memory")
;   #define RESC() do{ if(!NOMAX&&resc){ asm volatile("s_waitcnt lgkmcnt(0)":::"memory"); \
;       _Pragma("unroll") for(int d_=0;d_<2*VM;++d_) _Pragma("unroll") for(int r=0;r<16;++r)o[d_][r]*=wsf[crow(r,hi)]; } }while(0)
;   #define ROT() do{sl_prev=sl_cur;sl_cur=sl_next;sl_next=(sl_next==(NSLOT-1)*SLOTB)?0:sl_next+SLOTB;}while(0)
;   #define ENDW(tt) do{ if((tt)+3<NT){ if constexpr(VM==2){WAIT_BAR(3);}else{WAIT_BAR(2);} } else if((tt)+2<NT){ if constexpr(VM==2){WAIT_BAR(2);}else{WAIT_BAR(1);} } else {WAIT_BAR(0);} }while(0)
; template<int THRL,int VM,bool NOMAX> __device__ __forceinline__ void attn_unit(const bf16*Qb,const bf16*__restrict__ Kh,const bf16*__restrict__ Vh,bf16*Ob,const int NT,const int sp,float*wscr,char*shm){
;     ...
;     STEP(pB0,pB1,pA0,pA1,t,true,true,true);     if constexpr(VM==2){WAIT_BAR(3);}else{WAIT_BAR(2);} RESC(); ROT();
;     STEP(pA0,pA1,pB0,pB1,t+1,true,true,true);   if constexpr(VM==2){WAIT_BAR(3);}else{WAIT_BAR(2);} RESC(); ROT();
;   }
;     ...
;   for(;t+1<NT;t+=2){
;     STEP(pB0,pB1,pA0,pA1,t,(t+3<NT),(t+1<NT),(t+1<NT));       ENDW(t);   RESC(); ROT();
	s_cmpk_lg_i32 s88, 0x4000
	s_mov_b32 s89, s86
	s_cselect_b32 s86, s90, 0
	s_add_i32 s85, s85, 2
	v_lshl_add_u64 v[176:177], v[176:177], 0, s[58:59]
	v_lshl_add_u64 v[178:179], v[178:179], 0, s[58:59]
	v_lshl_add_u64 v[180:181], v[180:181], 0, s[58:59]
	s_mov_b32 s87, s88
	s_cmp_lt_u32 s85, 57
	s_cbranch_scc1 .LBB0_874
	s_and_b32 s34, s34, 0x3fffffc0
	s_lshl_b32 s34, s34, 2
	s_add_i32 s34, s34, 0
	s_add_i32 s34, s34, 0x12000
	s_cmp_lg_u32 0, -1
	s_cselect_b32 s85, 0, 0
	s_add_i32 s86, s85, 0x6000
	v_add_u32_e32 v104, s86, v191
	v_add3_u32 v176, v104, v190, v192
	v_add_u32_e32 v177, 0x6000, v188
	ds_read_b64_tr_b16 v[178:179], v188 offset:40960
	ds_read_b64_tr_b16 v[180:181], v188 offset:41472
	v_add_f32_e32 v108, v80, v81
	ds_read_b128 v[104:107], v168
	v_add_f32_e32 v108, v82, v108
	v_add_f32_e32 v108, v83, v108
	v_add_f32_e32 v108, v84, v108
	v_add_f32_e32 v108, v85, v108
	v_cvt_pk_bf16_f32 v156, v80, v81
	v_cvt_pk_bf16_f32 v157, v82, v83
	s_waitcnt lgkmcnt(0)
	v_mfma_f32_32x32x16_bf16 v[112:127], v[100:103], v[104:107], 0
	ds_read_b64_tr_b16 v[80:81], v188 offset:45056
	ds_read_b64_tr_b16 v[82:83], v188 offset:45568
	ds_read_b128 v[100:103], v168
	v_add_f32_e32 v104, v86, v108
	v_add_f32_e32 v104, v87, v104
	v_add_f32_e32 v104, v88, v104
	v_add_f32_e32 v144, v89, v104
	v_cvt_pk_bf16_f32 v158, v84, v85
	v_cvt_pk_bf16_f32 v159, v86, v87
	s_waitcnt lgkmcnt(0)
	v_mfma_f32_32x32x16_bf16 v[96:111], v[96:99], v[100:103], 0
	ds_read_b64_tr_b16 v[84:85], v188 offset:41984
	ds_read_b64_tr_b16 v[86:87], v188 offset:42496
	ds_read_b128 v[194:197], v168 offset:1024
	v_add_f32_e32 v144, v90, v144
	v_add_f32_e32 v144, v91, v144
	v_add_f32_e32 v144, v92, v144
	v_add_f32_e32 v144, v93, v144
	v_cvt_pk_bf16_f32 v152, v88, v89
	v_cvt_pk_bf16_f32 v153, v90, v91
	s_waitcnt lgkmcnt(0)
	v_mfma_f32_32x32x16_bf16 v[112:127], v[164:167], v[194:197], v[112:127]
	ds_read_b64_tr_b16 v[88:89], v188 offset:46080
	ds_read_b64_tr_b16 v[90:91], v188 offset:46592
	ds_read_b128 v[164:167], v168 offset:1024
	v_add_f32_e32 v144, v94, v144
	v_add_f32_e32 v144, v95, v144
	v_add_f32_e32 v144, v64, v144
	v_add_f32_e32 v144, v65, v144
	v_cvt_pk_bf16_f32 v154, v92, v93
	v_cvt_pk_bf16_f32 v155, v94, v95
	s_waitcnt lgkmcnt(0)
	v_mfma_f32_32x32x16_bf16 v[96:111], v[160:163], v[164:167], v[96:111]
	ds_read_b64_tr_b16 v[194:195], v188 offset:43008
	ds_read_b64_tr_b16 v[196:197], v188 offset:43520
	ds_read_b128 v[92:95], v168 offset:2048
	v_add_f32_e32 v144, v66, v144
	v_add_f32_e32 v144, v67, v144
	v_add_f32_e32 v144, v68, v144
	v_add_f32_e32 v144, v69, v144
	v_cvt_pk_bf16_f32 v148, v64, v65
	v_cvt_pk_bf16_f32 v149, v66, v67
	s_waitcnt lgkmcnt(0)
	v_mfma_f32_32x32x16_bf16 v[112:127], v[140:143], v[92:95], v[112:127]
	ds_read_b64_tr_b16 v[140:141], v188 offset:47104
	ds_read_b64_tr_b16 v[142:143], v188 offset:47616
	ds_read_b128 v[64:67], v168 offset:2048
	v_add_f32_e32 v92, v70, v144
	v_add_f32_e32 v92, v71, v92
	v_add_f32_e32 v92, v72, v92
	v_add_f32_e32 v92, v73, v92
	v_cvt_pk_bf16_f32 v150, v68, v69
	v_cvt_pk_bf16_f32 v151, v70, v71
	s_waitcnt lgkmcnt(0)
	v_mfma_f32_32x32x16_bf16 v[96:111], v[136:139], v[64:67], v[96:111]
	ds_read_b64_tr_b16 v[136:137], v188 offset:44032
	ds_read_b64_tr_b16 v[138:139], v188 offset:44544
	ds_read_b128 v[64:67], v168 offset:3072
	v_add_f32_e32 v68, v74, v92
	v_add_f32_e32 v68, v75, v68
	v_add_f32_e32 v68, v76, v68
	v_add_f32_e32 v68, v77, v68
	v_cvt_pk_bf16_f32 v144, v72, v73
	v_cvt_pk_bf16_f32 v145, v74, v75
	s_waitcnt lgkmcnt(0)
	v_mfma_f32_32x32x16_bf16 v[112:127], v[132:135], v[64:67], v[112:127]
	ds_read_b64_tr_b16 v[72:73], v188 offset:48128
	ds_read_b64_tr_b16 v[74:75], v188 offset:48640
	ds_read_b128 v[64:67], v168 offset:3072
	v_add_f32_e32 v68, v78, v68
	v_add_f32_e32 v68, v79, v68
	v_add_f32_e32 v68, 0, v68
	v_cvt_pk_bf16_f32 v146, v76, v77
	v_cvt_pk_bf16_f32 v147, v78, v79
	s_waitcnt lgkmcnt(0)
	v_mfma_f32_32x32x16_bf16 v[96:111], v[128:131], v[64:67], v[96:111]
	s_add_i32 s85, s85, s35
	v_lshl_add_u64 v[64:65], v[174:175], 0, s[60:61]
	s_add_i32 s35, s85, 0x4000
	s_mov_b32 s86, m0
	s_mov_b32 m0, s35
	s_nop 0
	global_load_lds_dwordx4 v[64:65], off
	s_mov_b32 m0, s86
	v_lshl_add_u64 v[64:65], v[170:171], 0, s[62:63]
	s_mov_b32 s35, m0
	s_mov_b32 m0, s16
	s_nop 0
	global_load_lds_dwordx4 v[64:65], off
	s_mov_b32 m0, s35
	v_lshl_add_u64 v[64:65], v[172:173], 0, s[62:63]
	s_add_i32 s35, s16, 0x2000
	s_mov_b32 s86, m0
	s_mov_b32 m0, s35
	s_nop 0
	global_load_lds_dwordx4 v[64:65], off
	s_mov_b32 m0, s86
	v_add_f32_e32 v198, v193, v68
	v_mfma_f32_32x32x16_bf16 v[48:63], v[156:159], v[178:181], v[48:63]
	ds_read_b64_tr_b16 v[76:77], v188 offset:49152
	ds_read_b64_tr_b16 v[78:79], v188 offset:49664
	v_exp_f32_e32 v112, v112
	v_exp_f32_e32 v113, v113
	v_mfma_f32_32x32x16_bf16 v[32:47], v[156:159], v[80:83], v[32:47]
	ds_read_b64_tr_b16 v[128:129], v188 offset:53248
	ds_read_b64_tr_b16 v[130:131], v188 offset:53760
	v_exp_f32_e32 v114, v114
	v_exp_f32_e32 v115, v115
	ds_read_b128 v[68:71], v189
	ds_read_b128 v[64:67], v189 offset:512
	v_mfma_f32_32x32x16_bf16 v[48:63], v[152:155], v[84:87], v[48:63]
	ds_read_b64_tr_b16 v[132:133], v188 offset:50176
	ds_read_b64_tr_b16 v[134:135], v188 offset:50688
	v_exp_f32_e32 v116, v116
	v_exp_f32_e32 v117, v117
	ds_read_b128 v[164:167], v189 offset:2048
	ds_read_b128 v[92:95], v189 offset:2560
	v_mfma_f32_32x32x16_bf16 v[32:47], v[152:155], v[88:91], v[32:47]
	ds_read_b64_tr_b16 v[178:179], v188 offset:54272
	ds_read_b64_tr_b16 v[180:181], v188 offset:54784
	v_exp_f32_e32 v118, v118
	v_exp_f32_e32 v119, v119
	ds_read_b128 v[160:163], v189 offset:4096
	ds_read_b128 v[84:87], v189 offset:4608
	v_mfma_f32_32x32x16_bf16 v[48:63], v[148:151], v[194:197], v[48:63]
	ds_read_b64_tr_b16 v[190:191], v188 offset:51200
	ds_read_b64_tr_b16 v[192:193], v188 offset:51712
	v_exp_f32_e32 v120, v120
	v_exp_f32_e32 v121, v121
	ds_read_b128 v[88:91], v189 offset:6144
	ds_read_b128 v[80:83], v189 offset:6656
	v_mfma_f32_32x32x16_bf16 v[32:47], v[148:151], v[140:143], v[32:47]
	ds_read_b64_tr_b16 v[194:195], v188 offset:55296
	ds_read_b64_tr_b16 v[196:197], v188 offset:55808
	v_exp_f32_e32 v122, v122
	v_exp_f32_e32 v123, v123
	v_mfma_f32_32x32x16_bf16 v[48:63], v[144:147], v[136:139], v[48:63]
	ds_read_b64_tr_b16 v[140:141], v188 offset:52224
	ds_read_b64_tr_b16 v[142:143], v188 offset:52736
	v_exp_f32_e32 v124, v124
	v_exp_f32_e32 v125, v125
	v_mfma_f32_32x32x16_bf16 v[32:47], v[144:147], v[72:75], v[32:47]
	ds_read_b64_tr_b16 v[136:137], v188 offset:56320
	ds_read_b64_tr_b16 v[138:139], v188 offset:56832
	v_exp_f32_e32 v126, v126
	v_exp_f32_e32 v127, v127
	s_waitcnt lgkmcnt(14)
;   #define RESC() do{ if(!NOMAX&&resc){ asm volatile("s_waitcnt lgkmcnt(0)":::"memory"); \
;       _Pragma("unroll") for(int d_=0;d_<2*VM;++d_) _Pragma("unroll") for(int r=0;r<16;++r)o[d_][r]*=wsf[crow(r,hi)]; } }while(0)
;   #define ROT() do{sl_prev=sl_cur;sl_cur=sl_next;sl_next=(sl_next==(NSLOT-1)*SLOTB)?0:sl_next+SLOTB;}while(0)
;   #define ENDW(tt) do{ if((tt)+3<NT){ if constexpr(VM==2){WAIT_BAR(3);}else{WAIT_BAR(2);} } else if((tt)+2<NT){ if constexpr(VM==2){WAIT_BAR(2);}else{WAIT_BAR(1);} } else {WAIT_BAR(0);} }while(0)
; template<int THRL,int VM,bool NOMAX> __device__ __forceinline__ void attn_unit(const bf16*Qb,const bf16*__restrict__ Kh,const bf16*__restrict__ Vh,bf16*Ob,const int NT,const int sp,float*wscr,char*shm){
;     ...
;   for(;t+1<NT;t+=2){
;     STEP(pB0,pB1,pA0,pA1,t,(t+3<NT),(t+1<NT),(t+1<NT));       ENDW(t);   RESC(); ROT();
;     STEP(pA0,pA1,pB0,pB1,t+1,(t+4<NT),(t+2<NT),(t+2<NT));     ENDW(t+1); RESC(); ROT();
	v_mfma_f32_32x32x16_bf16 v[16:31], v[156:159], v[76:79], v[16:31]
	v_exp_f32_e32 v96, v96
	v_exp_f32_e32 v97, v97
	v_mfma_f32_32x32x16_bf16 v[0:15], v[156:159], v[128:131], v[0:15]
	v_exp_f32_e32 v98, v98
	v_exp_f32_e32 v99, v99
	v_mfma_f32_32x32x16_bf16 v[16:31], v[152:155], v[132:135], v[16:31]
	v_exp_f32_e32 v100, v100
	v_exp_f32_e32 v101, v101
	s_waitcnt lgkmcnt(12)
	v_mfma_f32_32x32x16_bf16 v[0:15], v[152:155], v[178:181], v[0:15]
	v_exp_f32_e32 v102, v102
	v_exp_f32_e32 v103, v103
	s_waitcnt lgkmcnt(8)
	v_mfma_f32_32x32x16_bf16 v[16:31], v[148:151], v[190:193], v[16:31]
	v_exp_f32_e32 v104, v104
	v_exp_f32_e32 v105, v105
	s_waitcnt lgkmcnt(4)
	v_mfma_f32_32x32x16_bf16 v[0:15], v[148:151], v[194:197], v[0:15]
	v_exp_f32_e32 v106, v106
	v_exp_f32_e32 v107, v107
	s_waitcnt lgkmcnt(2)
	v_mfma_f32_32x32x16_bf16 v[16:31], v[144:147], v[140:143], v[16:31]
	v_exp_f32_e32 v108, v108
	v_exp_f32_e32 v109, v109
	s_waitcnt lgkmcnt(0)
	v_mfma_f32_32x32x16_bf16 v[0:15], v[144:147], v[136:139], v[0:15]
	v_exp_f32_e32 v110, v110
	v_exp_f32_e32 v111, v111
	s_waitcnt vmcnt(3) lgkmcnt(0)
	s_barrier
	ds_read_b64_tr_b16 v[178:179], v188 offset:57344
	ds_read_b64_tr_b16 v[180:181], v188 offset:57856
	v_add_f32_e32 v76, v112, v113
	ds_read_b128 v[72:75], v168
	v_add_f32_e32 v76, v114, v76
	v_add_f32_e32 v76, v115, v76
	v_add_f32_e32 v76, v116, v76
	v_add_f32_e32 v76, v117, v76
	v_cvt_pk_bf16_f32 v156, v112, v113
	v_cvt_pk_bf16_f32 v157, v114, v115
	s_waitcnt lgkmcnt(0)
	v_mfma_f32_32x32x16_bf16 v[128:143], v[68:71], v[72:75], 0
	ds_read_b64_tr_b16 v[112:113], v188 offset:61440
	ds_read_b64_tr_b16 v[114:115], v188 offset:61952
	ds_read_b128 v[68:71], v168
	v_add_f32_e32 v72, v118, v76
	v_add_f32_e32 v72, v119, v72
	v_add_f32_e32 v72, v120, v72
	v_add_f32_e32 v144, v121, v72
	s_waitcnt lgkmcnt(0)
	v_mfma_f32_32x32x16_bf16 v[64:79], v[64:67], v[68:71], 0
	v_cvt_pk_bf16_f32 v158, v116, v117
	v_cvt_pk_bf16_f32 v159, v118, v119
	ds_read_b64_tr_b16 v[116:117], v188 offset:58368
	ds_read_b64_tr_b16 v[118:119], v188 offset:58880
	ds_read_b128 v[190:193], v168 offset:1024
	v_add_f32_e32 v144, v122, v144
	v_add_f32_e32 v144, v123, v144
	v_add_f32_e32 v144, v124, v144
	v_add_f32_e32 v144, v125, v144
	v_cvt_pk_bf16_f32 v152, v120, v121
	v_cvt_pk_bf16_f32 v153, v122, v123
	s_waitcnt lgkmcnt(0)
	v_mfma_f32_32x32x16_bf16 v[128:143], v[164:167], v[190:193], v[128:143]
	ds_read_b64_tr_b16 v[120:121], v188 offset:62464
	ds_read_b64_tr_b16 v[122:123], v188 offset:62976
	ds_read_b128 v[164:167], v168 offset:1024
	v_add_f32_e32 v144, v126, v144
	v_add_f32_e32 v144, v127, v144
	v_add_f32_e32 v144, v96, v144
	v_add_f32_e32 v144, v97, v144
	s_waitcnt lgkmcnt(0)
	v_mfma_f32_32x32x16_bf16 v[64:79], v[92:95], v[164:167], v[64:79]
	v_cvt_pk_bf16_f32 v154, v124, v125
	v_cvt_pk_bf16_f32 v155, v126, v127
	ds_read_b64_tr_b16 v[92:93], v188 offset:59392
	ds_read_b64_tr_b16 v[94:95], v188 offset:59904
	ds_read_b128 v[124:127], v168 offset:2048
	v_add_f32_e32 v144, v98, v144
	v_add_f32_e32 v144, v99, v144
	v_add_f32_e32 v144, v100, v144
	v_add_f32_e32 v144, v101, v144
	v_cvt_pk_bf16_f32 v148, v96, v97
	v_cvt_pk_bf16_f32 v149, v98, v99
	s_waitcnt lgkmcnt(0)
	v_mfma_f32_32x32x16_bf16 v[128:143], v[160:163], v[124:127], v[128:143]
	ds_read_b64_tr_b16 v[96:97], v188 offset:63488
	ds_read_b64_tr_b16 v[98:99], v188 offset:64000
	ds_read_b128 v[124:127], v168 offset:2048
	v_add_f32_e32 v144, v102, v144
	v_add_f32_e32 v144, v103, v144
	v_add_f32_e32 v144, v104, v144
	v_add_f32_e32 v144, v105, v144
	s_waitcnt lgkmcnt(0)
	v_mfma_f32_32x32x16_bf16 v[64:79], v[84:87], v[124:127], v[64:79]
	v_cvt_pk_bf16_f32 v150, v100, v101
	v_cvt_pk_bf16_f32 v151, v102, v103
	ds_read_b64_tr_b16 v[100:101], v188 offset:60416
	ds_read_b64_tr_b16 v[102:103], v188 offset:60928
	ds_read_b128 v[84:87], v168 offset:3072
	v_add_f32_e32 v124, v106, v144
	v_add_f32_e32 v124, v107, v124
	v_add_f32_e32 v124, v108, v124
	v_add_f32_e32 v124, v109, v124
	v_cvt_pk_bf16_f32 v144, v104, v105
	v_cvt_pk_bf16_f32 v145, v106, v107
	s_waitcnt lgkmcnt(0)
	v_mfma_f32_32x32x16_bf16 v[128:143], v[88:91], v[84:87], v[128:143]
	ds_read_b64_tr_b16 v[88:89], v188 offset:64512
	ds_read_b64_tr_b16 v[90:91], v188 offset:65024
	ds_read_b128 v[84:87], v168 offset:3072
	v_add_f32_e32 v104, v110, v124
	v_add_f32_e32 v104, v111, v104
	v_add_f32_e32 v104, 0, v104
	v_cvt_pk_bf16_f32 v146, v108, v109
	s_waitcnt lgkmcnt(0)
;   #define RESC() do{ if(!NOMAX&&resc){ asm volatile("s_waitcnt lgkmcnt(0)":::"memory"); \
;       _Pragma("unroll") for(int d_=0;d_<2*VM;++d_) _Pragma("unroll") for(int r=0;r<16;++r)o[d_][r]*=wsf[crow(r,hi)]; } }while(0)
;   #define ROT() do{sl_prev=sl_cur;sl_cur=sl_next;sl_next=(sl_next==(NSLOT-1)*SLOTB)?0:sl_next+SLOTB;}while(0)
;   #define ENDW(tt) do{ if((tt)+3<NT){ if constexpr(VM==2){WAIT_BAR(3);}else{WAIT_BAR(2);} } else if((tt)+2<NT){ if constexpr(VM==2){WAIT_BAR(2);}else{WAIT_BAR(1);} } else {WAIT_BAR(0);} }while(0)
; template<int THRL,int VM,bool NOMAX> __device__ __forceinline__ void attn_unit(const bf16*Qb,const bf16*__restrict__ Kh,const bf16*__restrict__ Vh,bf16*Ob,const int NT,const int sp,float*wscr,char*shm){
;     ...
;   for(;t+1<NT;t+=2){
;     STEP(pB0,pB1,pA0,pA1,t,(t+3<NT),(t+1<NT),(t+1<NT));       ENDW(t);   RESC(); ROT();
;     STEP(pA0,pA1,pB0,pB1,t+1,(t+4<NT),(t+2<NT),(t+2<NT));     ENDW(t+1); RESC(); ROT();
	v_mfma_f32_32x32x16_bf16 v[64:79], v[80:83], v[84:87], v[64:79]
	v_cvt_pk_bf16_f32 v147, v110, v111
	v_lshl_add_u64 v[80:81], v[174:175], 0, s[64:65]
	s_mov_b32 s86, m0
	s_mov_b32 m0, s17
	s_nop 0
	global_load_lds_dwordx4 v[80:81], off
	s_mov_b32 m0, s86
	v_lshl_add_u64 v[80:81], v[170:171], 0, s[66:67]
	s_add_i32 s17, s85, 0xa000
	s_mov_b32 s86, m0
	s_mov_b32 m0, s17
	s_nop 0
	global_load_lds_dwordx4 v[80:81], off
	s_mov_b32 m0, s86
	v_lshl_add_u64 v[80:81], v[172:173], 0, s[66:67]
	s_add_i32 s17, s85, 0xc000
	s_mov_b32 s86, m0
	s_mov_b32 m0, s17
	s_nop 0
	global_load_lds_dwordx4 v[80:81], off
	s_mov_b32 m0, s86
	v_add_f32_e32 v198, v198, v104
	v_mfma_f32_32x32x16_bf16 v[48:63], v[156:159], v[178:181], v[48:63]
	ds_read_b64_tr_b16 v[104:105], v177 offset:40960
	ds_read_b64_tr_b16 v[106:107], v177 offset:41472
	v_exp_f32_e32 v128, v128
	v_exp_f32_e32 v129, v129
	v_mfma_f32_32x32x16_bf16 v[32:47], v[156:159], v[112:115], v[32:47]
	ds_read_b64_tr_b16 v[108:109], v177 offset:45056
	ds_read_b64_tr_b16 v[110:111], v177 offset:45568
	v_exp_f32_e32 v130, v130
	v_exp_f32_e32 v131, v131
	ds_read_b128 v[84:87], v189 offset:8192
	ds_read_b128 v[80:83], v189 offset:8704
	v_mfma_f32_32x32x16_bf16 v[48:63], v[152:155], v[116:119], v[48:63]
	ds_read_b64_tr_b16 v[178:179], v177 offset:41984
	ds_read_b64_tr_b16 v[180:181], v177 offset:42496
	v_exp_f32_e32 v132, v132
	v_exp_f32_e32 v133, v133
	ds_read_b128 v[164:167], v189 offset:10240
	ds_read_b128 v[124:127], v189 offset:10752
	v_mfma_f32_32x32x16_bf16 v[32:47], v[152:155], v[120:123], v[32:47]
	ds_read_b64_tr_b16 v[190:191], v177 offset:46080
	ds_read_b64_tr_b16 v[192:193], v177 offset:46592
	v_exp_f32_e32 v134, v134
	v_exp_f32_e32 v135, v135
	ds_read_b128 v[160:163], v189 offset:12288
	ds_read_b128 v[116:119], v189 offset:12800
	v_mfma_f32_32x32x16_bf16 v[48:63], v[148:151], v[92:95], v[48:63]
	ds_read_b64_tr_b16 v[194:195], v177 offset:43008
	ds_read_b64_tr_b16 v[196:197], v177 offset:43520
	v_exp_f32_e32 v136, v136
	v_exp_f32_e32 v137, v137
	ds_read_b128 v[120:123], v189 offset:14336
	ds_read_b128 v[112:115], v189 offset:14848
	v_mfma_f32_32x32x16_bf16 v[32:47], v[148:151], v[96:99], v[32:47]
	ds_read_b64_tr_b16 v[92:93], v177 offset:47104
	ds_read_b64_tr_b16 v[94:95], v177 offset:47616
	v_exp_f32_e32 v138, v138
	v_exp_f32_e32 v139, v139
	v_mfma_f32_32x32x16_bf16 v[48:63], v[144:147], v[100:103], v[48:63]
	ds_read_b64_tr_b16 v[96:97], v177 offset:44032
	ds_read_b64_tr_b16 v[98:99], v177 offset:44544
	v_exp_f32_e32 v140, v140
	v_exp_f32_e32 v141, v141
	v_mfma_f32_32x32x16_bf16 v[32:47], v[144:147], v[88:91], v[32:47]
	ds_read_b64_tr_b16 v[100:101], v177 offset:48128
	ds_read_b64_tr_b16 v[102:103], v177 offset:48640
	v_exp_f32_e32 v142, v142
	v_exp_f32_e32 v143, v143
	s_waitcnt lgkmcnt(14)
	v_mfma_f32_32x32x16_bf16 v[16:31], v[156:159], v[104:107], v[16:31]
	v_exp_f32_e32 v64, v64
	v_exp_f32_e32 v65, v65
	v_mfma_f32_32x32x16_bf16 v[0:15], v[156:159], v[108:111], v[0:15]
	v_exp_f32_e32 v66, v66
	v_exp_f32_e32 v67, v67
	v_mfma_f32_32x32x16_bf16 v[16:31], v[152:155], v[178:181], v[16:31]
	v_exp_f32_e32 v68, v68
	v_exp_f32_e32 v69, v69
	s_waitcnt lgkmcnt(12)
	v_mfma_f32_32x32x16_bf16 v[0:15], v[152:155], v[190:193], v[0:15]
	v_exp_f32_e32 v70, v70
	v_exp_f32_e32 v71, v71
	s_waitcnt lgkmcnt(8)
	v_mfma_f32_32x32x16_bf16 v[16:31], v[148:151], v[194:197], v[16:31]
	v_exp_f32_e32 v72, v72
	v_exp_f32_e32 v73, v73
	s_waitcnt lgkmcnt(4)
	v_mfma_f32_32x32x16_bf16 v[0:15], v[148:151], v[92:95], v[0:15]
	v_exp_f32_e32 v74, v74
	v_exp_f32_e32 v75, v75
	s_waitcnt lgkmcnt(2)
	v_mfma_f32_32x32x16_bf16 v[16:31], v[144:147], v[96:99], v[16:31]
	v_exp_f32_e32 v76, v76
	v_exp_f32_e32 v77, v77
	s_waitcnt lgkmcnt(0)
	v_mfma_f32_32x32x16_bf16 v[0:15], v[144:147], v[100:103], v[0:15]
	v_exp_f32_e32 v78, v78
	v_exp_f32_e32 v79, v79
	s_waitcnt vmcnt(3) lgkmcnt(0)
	s_barrier
	ds_read_b64_tr_b16 v[178:179], v188 offset:24576
	ds_read_b64_tr_b16 v[180:181], v188 offset:25088
	v_add_f32_e32 v92, v128, v129
	ds_read_b128 v[88:91], v168
	v_add_f32_e32 v92, v130, v92
	v_add_f32_e32 v92, v131, v92
	v_add_f32_e32 v92, v132, v92
	v_add_f32_e32 v92, v133, v92
	v_cvt_pk_bf16_f32 v156, v128, v129
	v_cvt_pk_bf16_f32 v157, v130, v131
	s_waitcnt lgkmcnt(0)
	v_mfma_f32_32x32x16_bf16 v[96:111], v[84:87], v[88:91], 0
	ds_read_b64_tr_b16 v[128:129], v188 offset:28672
	ds_read_b64_tr_b16 v[130:131], v188 offset:29184
	ds_read_b128 v[84:87], v168
	v_add_f32_e32 v88, v134, v92
	v_add_f32_e32 v88, v135, v88
	v_add_f32_e32 v88, v136, v88
	v_add_f32_e32 v144, v137, v88
	v_cvt_pk_bf16_f32 v158, v132, v133
	v_cvt_pk_bf16_f32 v159, v134, v135
	s_waitcnt lgkmcnt(0)
	v_mfma_f32_32x32x16_bf16 v[80:95], v[80:83], v[84:87], 0
	ds_read_b64_tr_b16 v[132:133], v188 offset:25600
	ds_read_b64_tr_b16 v[134:135], v188 offset:26112
	ds_read_b128 v[190:193], v168 offset:1024
	v_add_f32_e32 v144, v138, v144
	v_add_f32_e32 v144, v139, v144
	v_add_f32_e32 v144, v140, v144
	v_add_f32_e32 v144, v141, v144
	v_cvt_pk_bf16_f32 v152, v136, v137
	v_cvt_pk_bf16_f32 v153, v138, v139
	s_waitcnt lgkmcnt(0)
	v_mfma_f32_32x32x16_bf16 v[96:111], v[164:167], v[190:193], v[96:111]
	ds_read_b64_tr_b16 v[136:137], v188 offset:29696
	ds_read_b64_tr_b16 v[138:139], v188 offset:30208
	ds_read_b128 v[164:167], v168 offset:1024
	v_add_f32_e32 v144, v142, v144
	v_add_f32_e32 v144, v143, v144
	v_add_f32_e32 v144, v64, v144
	v_add_f32_e32 v144, v65, v144
	v_cvt_pk_bf16_f32 v154, v140, v141
	v_cvt_pk_bf16_f32 v155, v142, v143
	s_waitcnt lgkmcnt(0)
;   #define RESC() do{ if(!NOMAX&&resc){ asm volatile("s_waitcnt lgkmcnt(0)":::"memory"); \
;       _Pragma("unroll") for(int d_=0;d_<2*VM;++d_) _Pragma("unroll") for(int r=0;r<16;++r)o[d_][r]*=wsf[crow(r,hi)]; } }while(0)
;   #define ROT() do{sl_prev=sl_cur;sl_cur=sl_next;sl_next=(sl_next==(NSLOT-1)*SLOTB)?0:sl_next+SLOTB;}while(0)
;   #define ENDW(tt) do{ if((tt)+3<NT){ if constexpr(VM==2){WAIT_BAR(3);}else{WAIT_BAR(2);} } else if((tt)+2<NT){ if constexpr(VM==2){WAIT_BAR(2);}else{WAIT_BAR(1);} } else {WAIT_BAR(0);} }while(0)
; template<int THRL,int VM,bool NOMAX> __device__ __forceinline__ void attn_unit(const bf16*Qb,const bf16*__restrict__ Kh,const bf16*__restrict__ Vh,bf16*Ob,const int NT,const int sp,float*wscr,char*shm){
;     ...
;   for(;t+1<NT;t+=2){
;     STEP(pB0,pB1,pA0,pA1,t,(t+3<NT),(t+1<NT),(t+1<NT));       ENDW(t);   RESC(); ROT();
;     STEP(pA0,pA1,pB0,pB1,t+1,(t+4<NT),(t+2<NT),(t+2<NT));     ENDW(t+1); RESC(); ROT();
	v_mfma_f32_32x32x16_bf16 v[80:95], v[124:127], v[164:167], v[80:95]
	ds_read_b64_tr_b16 v[124:125], v188 offset:26624
	ds_read_b64_tr_b16 v[126:127], v188 offset:27136
	ds_read_b128 v[140:143], v168 offset:2048
	v_add_f32_e32 v144, v66, v144
	v_add_f32_e32 v144, v67, v144
	v_add_f32_e32 v144, v68, v144
	v_add_f32_e32 v144, v69, v144
	v_cvt_pk_bf16_f32 v148, v64, v65
	v_cvt_pk_bf16_f32 v149, v66, v67
	s_waitcnt lgkmcnt(0)
	v_mfma_f32_32x32x16_bf16 v[96:111], v[160:163], v[140:143], v[96:111]
	ds_read_b64_tr_b16 v[190:191], v188 offset:30720
	ds_read_b64_tr_b16 v[192:193], v188 offset:31232
	ds_read_b128 v[64:67], v168 offset:2048
	v_add_f32_e32 v140, v70, v144
	v_add_f32_e32 v140, v71, v140
	v_add_f32_e32 v140, v72, v140
	v_add_f32_e32 v140, v73, v140
	v_cvt_pk_bf16_f32 v150, v68, v69
	v_cvt_pk_bf16_f32 v151, v70, v71
	s_waitcnt lgkmcnt(0)
	v_mfma_f32_32x32x16_bf16 v[80:95], v[116:119], v[64:67], v[80:95]
	ds_read_b64_tr_b16 v[116:117], v188 offset:27648
	ds_read_b64_tr_b16 v[118:119], v188 offset:28160
	ds_read_b128 v[64:67], v168 offset:3072
	v_add_f32_e32 v68, v74, v140
	v_add_f32_e32 v68, v75, v68
	v_add_f32_e32 v68, v76, v68
	v_add_f32_e32 v68, v77, v68
	v_cvt_pk_bf16_f32 v144, v72, v73
	v_cvt_pk_bf16_f32 v145, v74, v75
	s_waitcnt lgkmcnt(0)
	v_mfma_f32_32x32x16_bf16 v[96:111], v[120:123], v[64:67], v[96:111]
	ds_read_b64_tr_b16 v[72:73], v188 offset:31744
	ds_read_b64_tr_b16 v[74:75], v188 offset:32256
	ds_read_b128 v[64:67], v168 offset:3072
	v_add_f32_e32 v68, v78, v68
	v_add_f32_e32 v68, v79, v68
	v_add_f32_e32 v68, 0, v68
	v_cvt_pk_bf16_f32 v146, v76, v77
	v_cvt_pk_bf16_f32 v147, v78, v79
	s_waitcnt lgkmcnt(0)
	v_mfma_f32_32x32x16_bf16 v[80:95], v[112:115], v[64:67], v[80:95]
	v_lshl_add_u64 v[64:65], v[170:171], 0, s[60:61]
	s_add_i32 s17, s85, 0xe000
	s_mov_b32 s86, m0
	s_mov_b32 m0, s17
	s_nop 0
	global_load_lds_dwordx4 v[64:65], off
	s_mov_b32 m0, s86
	v_lshl_add_u64 v[64:65], v[172:173], 0, s[60:61]
	s_add_i32 s85, s85, 0x10000
	s_mov_b32 s17, m0
	s_mov_b32 m0, s85
	s_nop 0
	global_load_lds_dwordx4 v[64:65], off
	s_mov_b32 m0, s17
	v_add_f32_e32 v174, v198, v68
	v_mfma_f32_32x32x16_bf16 v[48:63], v[156:159], v[178:181], v[48:63]
	ds_read_b64_tr_b16 v[76:77], v188 offset:32768
	ds_read_b64_tr_b16 v[78:79], v188 offset:33280
	v_exp_f32_e32 v96, v96
	v_exp_f32_e32 v97, v97
	v_mfma_f32_32x32x16_bf16 v[32:47], v[156:159], v[128:131], v[32:47]
	ds_read_b64_tr_b16 v[112:113], v188 offset:36864
	ds_read_b64_tr_b16 v[114:115], v188 offset:37376
	v_exp_f32_e32 v98, v98
	v_exp_f32_e32 v99, v99
	ds_read_b128 v[68:71], v189 offset:16384
	ds_read_b128 v[64:67], v189 offset:16896
	v_mfma_f32_32x32x16_bf16 v[48:63], v[152:155], v[132:135], v[48:63]
	ds_read_b64_tr_b16 v[120:121], v188 offset:33792
	ds_read_b64_tr_b16 v[122:123], v188 offset:34304
	v_exp_f32_e32 v100, v100
	v_exp_f32_e32 v101, v101
	ds_read_b128 v[164:167], v189 offset:18432
	ds_read_b128 v[140:143], v189 offset:18944
	v_mfma_f32_32x32x16_bf16 v[32:47], v[152:155], v[136:139], v[32:47]
	ds_read_b64_tr_b16 v[178:179], v188 offset:37888
	ds_read_b64_tr_b16 v[180:181], v188 offset:38400
	v_exp_f32_e32 v102, v102
	v_exp_f32_e32 v103, v103
	ds_read_b128 v[160:163], v189 offset:20480
	ds_read_b128 v[132:135], v189 offset:20992
	v_mfma_f32_32x32x16_bf16 v[48:63], v[148:151], v[124:127], v[48:63]
	ds_read_b64_tr_b16 v[194:195], v188 offset:34816
	ds_read_b64_tr_b16 v[196:197], v188 offset:35328
	v_exp_f32_e32 v104, v104
	v_exp_f32_e32 v105, v105
	ds_read_b128 v[136:139], v189 offset:22528
	ds_read_b128 v[128:131], v189 offset:23040
	v_mfma_f32_32x32x16_bf16 v[32:47], v[148:151], v[190:193], v[32:47]
	ds_read_b64_tr_b16 v[124:125], v188 offset:38912
	ds_read_b64_tr_b16 v[126:127], v188 offset:39424
	v_exp_f32_e32 v106, v106
	v_exp_f32_e32 v107, v107
	v_mfma_f32_32x32x16_bf16 v[48:63], v[144:147], v[116:119], v[48:63]
	ds_read_b64_tr_b16 v[190:191], v188 offset:35840
	ds_read_b64_tr_b16 v[192:193], v188 offset:36352
	v_exp_f32_e32 v108, v108
	v_exp_f32_e32 v109, v109
	v_mfma_f32_32x32x16_bf16 v[32:47], v[144:147], v[72:75], v[32:47]
	ds_read_b64_tr_b16 v[116:117], v188 offset:39936
	ds_read_b64_tr_b16 v[118:119], v188 offset:40448
	v_exp_f32_e32 v110, v110
	v_exp_f32_e32 v111, v111
	s_waitcnt lgkmcnt(14)
	v_mfma_f32_32x32x16_bf16 v[16:31], v[156:159], v[76:79], v[16:31]
	v_exp_f32_e32 v80, v80
	v_exp_f32_e32 v81, v81
	v_mfma_f32_32x32x16_bf16 v[0:15], v[156:159], v[112:115], v[0:15]
	v_exp_f32_e32 v82, v82
	v_exp_f32_e32 v83, v83
	v_mfma_f32_32x32x16_bf16 v[16:31], v[152:155], v[120:123], v[16:31]
	v_exp_f32_e32 v84, v84
	v_exp_f32_e32 v85, v85
	s_waitcnt lgkmcnt(12)
	v_mfma_f32_32x32x16_bf16 v[0:15], v[152:155], v[178:181], v[0:15]
	v_exp_f32_e32 v86, v86
	v_exp_f32_e32 v87, v87
	s_waitcnt lgkmcnt(8)
	v_mfma_f32_32x32x16_bf16 v[16:31], v[148:151], v[194:197], v[16:31]
	v_exp_f32_e32 v88, v88
	v_exp_f32_e32 v89, v89
	s_waitcnt lgkmcnt(4)
	v_mfma_f32_32x32x16_bf16 v[0:15], v[148:151], v[124:127], v[0:15]
	v_exp_f32_e32 v90, v90
	v_exp_f32_e32 v91, v91
	s_waitcnt lgkmcnt(2)
	v_mfma_f32_32x32x16_bf16 v[16:31], v[144:147], v[190:193], v[16:31]
	v_exp_f32_e32 v92, v92
	v_exp_f32_e32 v93, v93
	s_waitcnt lgkmcnt(0)
	v_mfma_f32_32x32x16_bf16 v[0:15], v[144:147], v[116:119], v[0:15]
	v_exp_f32_e32 v94, v94
	v_exp_f32_e32 v95, v95
	s_waitcnt vmcnt(2) lgkmcnt(0)
	s_barrier
;   #define RESC() do{ if(!NOMAX&&resc){ asm volatile("s_waitcnt lgkmcnt(0)":::"memory"); \
;       _Pragma("unroll") for(int d_=0;d_<2*VM;++d_) _Pragma("unroll") for(int r=0;r<16;++r)o[d_][r]*=wsf[crow(r,hi)]; } }while(0)
;   #define ROT() do{sl_prev=sl_cur;sl_cur=sl_next;sl_next=(sl_next==(NSLOT-1)*SLOTB)?0:sl_next+SLOTB;}while(0)
;   #define ENDW(tt) do{ if((tt)+3<NT){ if constexpr(VM==2){WAIT_BAR(3);}else{WAIT_BAR(2);} } else if((tt)+2<NT){ if constexpr(VM==2){WAIT_BAR(2);}else{WAIT_BAR(1);} } else {WAIT_BAR(0);} }while(0)
; template<int THRL,int VM,bool NOMAX> __device__ __forceinline__ void attn_unit(const bf16*Qb,const bf16*__restrict__ Kh,const bf16*__restrict__ Vh,bf16*Ob,const int NT,const int sp,float*wscr,char*shm){
;     ...
;   for(;t+1<NT;t+=2){
;     STEP(pB0,pB1,pA0,pA1,t,(t+3<NT),(t+1<NT),(t+1<NT));       ENDW(t);   RESC(); ROT();
;     STEP(pA0,pA1,pB0,pB1,t+1,(t+4<NT),(t+2<NT),(t+2<NT));     ENDW(t+1); RESC(); ROT();
	ds_read_b64_tr_b16 v[178:179], v188 offset:40960
	ds_read_b64_tr_b16 v[180:181], v188 offset:41472
	v_add_f32_e32 v76, v96, v97
	ds_read_b128 v[72:75], v168
	v_add_f32_e32 v76, v98, v76
	v_add_f32_e32 v76, v99, v76
	v_add_f32_e32 v76, v100, v76
	v_add_f32_e32 v76, v101, v76
	v_cvt_pk_bf16_f32 v156, v96, v97
	v_cvt_pk_bf16_f32 v157, v98, v99
	s_waitcnt lgkmcnt(0)
	v_mfma_f32_32x32x16_bf16 v[112:127], v[68:71], v[72:75], 0
	ds_read_b64_tr_b16 v[96:97], v188 offset:45056
	ds_read_b64_tr_b16 v[98:99], v188 offset:45568
	ds_read_b128 v[68:71], v168
	v_add_f32_e32 v72, v102, v76
	v_add_f32_e32 v72, v103, v72
	v_add_f32_e32 v72, v104, v72
	v_add_f32_e32 v144, v105, v72
	s_waitcnt lgkmcnt(0)
	v_mfma_f32_32x32x16_bf16 v[64:79], v[64:67], v[68:71], 0
	v_cvt_pk_bf16_f32 v158, v100, v101
	v_cvt_pk_bf16_f32 v159, v102, v103
	ds_read_b64_tr_b16 v[100:101], v188 offset:41984
	ds_read_b64_tr_b16 v[102:103], v188 offset:42496
	ds_read_b128 v[190:193], v168 offset:1024
	v_add_f32_e32 v144, v106, v144
	v_add_f32_e32 v144, v107, v144
	v_add_f32_e32 v144, v108, v144
	v_add_f32_e32 v144, v109, v144
	v_cvt_pk_bf16_f32 v152, v104, v105
	v_cvt_pk_bf16_f32 v153, v106, v107
	s_waitcnt lgkmcnt(0)
	v_mfma_f32_32x32x16_bf16 v[112:127], v[164:167], v[190:193], v[112:127]
	ds_read_b64_tr_b16 v[104:105], v188 offset:46080
	ds_read_b64_tr_b16 v[106:107], v188 offset:46592
	ds_read_b128 v[164:167], v168 offset:1024
	v_add_f32_e32 v144, v110, v144
	v_add_f32_e32 v144, v111, v144
	v_add_f32_e32 v144, v80, v144
	v_add_f32_e32 v144, v81, v144
	s_waitcnt lgkmcnt(0)
	v_mfma_f32_32x32x16_bf16 v[64:79], v[140:143], v[164:167], v[64:79]
	v_cvt_pk_bf16_f32 v154, v108, v109
	v_cvt_pk_bf16_f32 v155, v110, v111
	ds_read_b64_tr_b16 v[108:109], v188 offset:43008
	ds_read_b64_tr_b16 v[110:111], v188 offset:43520
	ds_read_b128 v[140:143], v168 offset:2048
	v_add_f32_e32 v144, v82, v144
	v_add_f32_e32 v144, v83, v144
	v_add_f32_e32 v144, v84, v144
	v_add_f32_e32 v144, v85, v144
	v_cvt_pk_bf16_f32 v148, v80, v81
	v_cvt_pk_bf16_f32 v149, v82, v83
	s_waitcnt lgkmcnt(0)
	v_mfma_f32_32x32x16_bf16 v[112:127], v[160:163], v[140:143], v[112:127]
	ds_read_b64_tr_b16 v[190:191], v188 offset:47104
	ds_read_b64_tr_b16 v[192:193], v188 offset:47616
	ds_read_b128 v[80:83], v168 offset:2048
	v_add_f32_e32 v140, v86, v144
	v_add_f32_e32 v140, v87, v140
	v_add_f32_e32 v140, v88, v140
	v_add_f32_e32 v140, v89, v140
	s_waitcnt lgkmcnt(0)
	v_mfma_f32_32x32x16_bf16 v[64:79], v[132:135], v[80:83], v[64:79]
	v_cvt_pk_bf16_f32 v150, v84, v85
	v_cvt_pk_bf16_f32 v151, v86, v87
	ds_read_b64_tr_b16 v[84:85], v188 offset:44032
	ds_read_b64_tr_b16 v[86:87], v188 offset:44544
	ds_read_b128 v[80:83], v168 offset:3072
	v_add_f32_e32 v132, v90, v140
	v_add_f32_e32 v132, v91, v132
	v_add_f32_e32 v132, v92, v132
	v_add_f32_e32 v132, v93, v132
	v_cvt_pk_bf16_f32 v144, v88, v89
	v_cvt_pk_bf16_f32 v145, v90, v91
	s_waitcnt lgkmcnt(0)
	v_mfma_f32_32x32x16_bf16 v[112:127], v[136:139], v[80:83], v[112:127]
	ds_read_b64_tr_b16 v[88:89], v188 offset:48128
	ds_read_b64_tr_b16 v[90:91], v188 offset:48640
	ds_read_b128 v[80:83], v168 offset:3072
	v_add_f32_e32 v132, v94, v132
	v_add_f32_e32 v132, v95, v132
	v_add_f32_e32 v132, 0, v132
	v_cvt_pk_bf16_f32 v146, v92, v93
	s_waitcnt lgkmcnt(0)
	v_mfma_f32_32x32x16_bf16 v[64:79], v[128:131], v[80:83], v[64:79]
	v_cvt_pk_bf16_f32 v147, v94, v95
	v_lshl_add_u64 v[80:81], v[170:171], 0, s[64:65]
	s_mov_b32 s17, m0
	s_mov_b32 m0, s16
	s_nop 0
	global_load_lds_dwordx4 v[80:81], off
	s_mov_b32 m0, s17
	v_lshl_add_u64 v[80:81], v[172:173], 0, s[64:65]
	s_mov_b32 s16, m0
	s_mov_b32 m0, s35
	s_nop 0
	global_load_lds_dwordx4 v[80:81], off
	s_mov_b32 m0, s16
	v_add_f32_e32 v174, v174, v132
	v_mfma_f32_32x32x16_bf16 v[48:63], v[156:159], v[178:181], v[48:63]
	ds_read_b64_tr_b16 v[92:93], v188 offset:49152
	ds_read_b64_tr_b16 v[94:95], v188 offset:49664
	v_exp_f32_e32 v112, v112
	v_exp_f32_e32 v113, v113
	v_mfma_f32_32x32x16_bf16 v[32:47], v[156:159], v[96:99], v[32:47]
	ds_read_b64_tr_b16 v[170:171], v188 offset:53248
	ds_read_b64_tr_b16 v[172:173], v188 offset:53760
	v_exp_f32_e32 v114, v114
	v_exp_f32_e32 v115, v115
	ds_read_b128 v[80:83], v189
	ds_read_b128 v[96:99], v189 offset:512
	v_mfma_f32_32x32x16_bf16 v[48:63], v[152:155], v[100:103], v[48:63]
	ds_read_b64_tr_b16 v[178:179], v188 offset:50176
	ds_read_b64_tr_b16 v[180:181], v188 offset:50688
	v_exp_f32_e32 v116, v116
	v_exp_f32_e32 v117, v117
	ds_read_b128 v[164:167], v189 offset:2048
	ds_read_b128 v[140:143], v189 offset:2560
	v_mfma_f32_32x32x16_bf16 v[32:47], v[152:155], v[104:107], v[32:47]
	ds_read_b64_tr_b16 v[100:101], v188 offset:54272
	ds_read_b64_tr_b16 v[102:103], v188 offset:54784
	v_exp_f32_e32 v118, v118
	v_exp_f32_e32 v119, v119
	ds_read_b128 v[160:163], v189 offset:4096
	ds_read_b128 v[132:135], v189 offset:4608
	v_mfma_f32_32x32x16_bf16 v[48:63], v[148:151], v[108:111], v[48:63]
	ds_read_b64_tr_b16 v[104:105], v188 offset:51200
	ds_read_b64_tr_b16 v[106:107], v188 offset:51712
	v_exp_f32_e32 v120, v120
	v_exp_f32_e32 v121, v121
	ds_read_b128 v[136:139], v189 offset:6144
	ds_read_b128 v[128:131], v189 offset:6656
	v_mfma_f32_32x32x16_bf16 v[32:47], v[148:151], v[190:193], v[32:47]
	ds_read_b64_tr_b16 v[108:109], v188 offset:55296
	ds_read_b64_tr_b16 v[110:111], v188 offset:55808
	v_exp_f32_e32 v122, v122
	v_exp_f32_e32 v123, v123
	v_mfma_f32_32x32x16_bf16 v[48:63], v[144:147], v[84:87], v[48:63]
	ds_read_b64_tr_b16 v[190:191], v188 offset:52224
	ds_read_b64_tr_b16 v[192:193], v188 offset:52736
	v_exp_f32_e32 v124, v124
	v_exp_f32_e32 v125, v125
	v_mfma_f32_32x32x16_bf16 v[32:47], v[144:147], v[88:91], v[32:47]
	ds_read_b64_tr_b16 v[84:85], v188 offset:56320
	ds_read_b64_tr_b16 v[86:87], v188 offset:56832
	v_exp_f32_e32 v126, v126
	v_exp_f32_e32 v127, v127
	s_waitcnt lgkmcnt(14)
	v_mfma_f32_32x32x16_bf16 v[16:31], v[156:159], v[92:95], v[16:31]
	v_exp_f32_e32 v64, v64
	v_exp_f32_e32 v65, v65
	v_mfma_f32_32x32x16_bf16 v[0:15], v[156:159], v[170:173], v[0:15]
	v_exp_f32_e32 v66, v66
	v_exp_f32_e32 v67, v67
	v_mfma_f32_32x32x16_bf16 v[16:31], v[152:155], v[178:181], v[16:31]
	v_exp_f32_e32 v68, v68
	v_exp_f32_e32 v69, v69
	s_waitcnt lgkmcnt(12)
	v_mfma_f32_32x32x16_bf16 v[0:15], v[152:155], v[100:103], v[0:15]
	v_exp_f32_e32 v70, v70
	v_exp_f32_e32 v71, v71
	s_waitcnt lgkmcnt(8)
	v_mfma_f32_32x32x16_bf16 v[16:31], v[148:151], v[104:107], v[16:31]
	v_exp_f32_e32 v72, v72
	v_exp_f32_e32 v73, v73
	s_waitcnt lgkmcnt(4)
	v_mfma_f32_32x32x16_bf16 v[0:15], v[148:151], v[108:111], v[0:15]
	v_exp_f32_e32 v74, v74
	v_exp_f32_e32 v75, v75
	s_waitcnt lgkmcnt(2)
	v_mfma_f32_32x32x16_bf16 v[16:31], v[144:147], v[190:193], v[16:31]
	v_exp_f32_e32 v76, v76
	v_exp_f32_e32 v77, v77
	s_waitcnt lgkmcnt(0)
	v_mfma_f32_32x32x16_bf16 v[0:15], v[144:147], v[84:87], v[0:15]
	v_exp_f32_e32 v78, v78
	v_exp_f32_e32 v79, v79
	s_waitcnt vmcnt(0) lgkmcnt(0)
	s_barrier
	ds_read_b64_tr_b16 v[170:171], v188 offset:57344
	ds_read_b64_tr_b16 v[172:173], v188 offset:57856
	v_add_f32_e32 v88, v112, v113
	ds_read_b128 v[84:87], v168
	v_add_f32_e32 v88, v114, v88
	v_add_f32_e32 v88, v115, v88
	v_add_f32_e32 v88, v116, v88
	v_add_f32_e32 v104, v117, v88
	v_cvt_pk_bf16_f32 v156, v112, v113
	v_cvt_pk_bf16_f32 v157, v114, v115
	s_waitcnt lgkmcnt(0)
	v_mfma_f32_32x32x16_bf16 v[80:95], v[80:83], v[84:87], 0
	ds_read_b64_tr_b16 v[112:113], v188 offset:61440
	ds_read_b64_tr_b16 v[114:115], v188 offset:61952
	ds_read_b128 v[100:103], v168
	v_add_f32_e32 v104, v118, v104
	v_add_f32_e32 v104, v119, v104
	v_add_f32_e32 v104, v120, v104
	v_add_f32_e32 v144, v121, v104
	v_cvt_pk_bf16_f32 v158, v116, v117
	v_cvt_pk_bf16_f32 v159, v118, v119
	s_waitcnt lgkmcnt(0)
	v_mfma_f32_32x32x16_bf16 v[96:111], v[96:99], v[100:103], 0
	ds_read_b64_tr_b16 v[116:117], v188 offset:58368
	ds_read_b64_tr_b16 v[118:119], v188 offset:58880
	ds_read_b128 v[178:181], v168 offset:1024
	v_add_f32_e32 v144, v122, v144
	v_add_f32_e32 v144, v123, v144
	v_add_f32_e32 v144, v124, v144
	v_add_f32_e32 v144, v125, v144
	v_cvt_pk_bf16_f32 v152, v120, v121
	v_cvt_pk_bf16_f32 v153, v122, v123
	s_waitcnt lgkmcnt(0)
	v_mfma_f32_32x32x16_bf16 v[80:95], v[164:167], v[178:181], v[80:95]
	ds_read_b64_tr_b16 v[120:121], v188 offset:62464
	ds_read_b64_tr_b16 v[122:123], v188 offset:62976
	ds_read_b128 v[164:167], v168 offset:1024
	v_add_f32_e32 v144, v126, v144
	v_add_f32_e32 v144, v127, v144
	v_add_f32_e32 v144, v64, v144
	v_add_f32_e32 v144, v65, v144
	v_cvt_pk_bf16_f32 v154, v124, v125
	v_cvt_pk_bf16_f32 v155, v126, v127
	s_waitcnt lgkmcnt(0)
	v_mfma_f32_32x32x16_bf16 v[96:111], v[140:143], v[164:167], v[96:111]
	ds_read_b64_tr_b16 v[124:125], v188 offset:59392
	ds_read_b64_tr_b16 v[126:127], v188 offset:59904
	ds_read_b128 v[140:143], v168 offset:2048
	v_add_f32_e32 v144, v66, v144
	v_add_f32_e32 v144, v67, v144
	v_add_f32_e32 v144, v68, v144
	v_add_f32_e32 v144, v69, v144
	v_cvt_pk_bf16_f32 v148, v64, v65
	v_cvt_pk_bf16_f32 v149, v66, v67
	s_waitcnt lgkmcnt(0)
	v_mfma_f32_32x32x16_bf16 v[80:95], v[160:163], v[140:143], v[80:95]
	ds_read_b64_tr_b16 v[64:65], v188 offset:63488
	ds_read_b64_tr_b16 v[66:67], v188 offset:64000
	ds_read_b128 v[140:143], v168 offset:2048
	v_add_f32_e32 v144, v70, v144
	v_add_f32_e32 v144, v71, v144
	v_add_f32_e32 v144, v72, v144
	v_add_f32_e32 v144, v73, v144
	v_cvt_pk_bf16_f32 v150, v68, v69
	v_cvt_pk_bf16_f32 v151, v70, v71
	s_waitcnt lgkmcnt(0)
	v_mfma_f32_32x32x16_bf16 v[96:111], v[132:135], v[140:143], v[96:111]
	ds_read_b64_tr_b16 v[68:69], v188 offset:60416
	ds_read_b64_tr_b16 v[70:71], v188 offset:60928
	ds_read_b128 v[132:135], v168 offset:3072
	v_add_f32_e32 v140, v74, v144
	v_add_f32_e32 v140, v75, v140
	v_add_f32_e32 v140, v76, v140
	v_add_f32_e32 v140, v77, v140
	v_cvt_pk_bf16_f32 v144, v72, v73
	v_cvt_pk_bf16_f32 v145, v74, v75
	s_waitcnt lgkmcnt(0)
	v_mfma_f32_32x32x16_bf16 v[80:95], v[136:139], v[132:135], v[80:95]
	ds_read_b64_tr_b16 v[72:73], v188 offset:64512
	ds_read_b64_tr_b16 v[74:75], v188 offset:65024
	ds_read_b128 v[132:135], v168 offset:3072
	v_add_f32_e32 v136, v78, v140
	v_add_f32_e32 v136, v79, v136
	v_add_f32_e32 v136, 0, v136
	v_cvt_pk_bf16_f32 v146, v76, v77
	v_cvt_pk_bf16_f32 v147, v78, v79
	s_waitcnt lgkmcnt(0)
	v_mfma_f32_32x32x16_bf16 v[96:111], v[128:131], v[132:135], v[96:111]
	v_mfma_f32_32x32x16_bf16 v[48:63], v[156:159], v[170:173], v[48:63]
	ds_read_b64_tr_b16 v[76:77], v177 offset:40960
	ds_read_b64_tr_b16 v[78:79], v177 offset:41472
	v_exp_f32_e32 v80, v80
	v_exp_f32_e32 v81, v81
	v_mfma_f32_32x32x16_bf16 v[32:47], v[156:159], v[112:115], v[32:47]
	ds_read_b64_tr_b16 v[128:129], v177 offset:45056
	ds_read_b64_tr_b16 v[130:131], v177 offset:45568
	v_exp_f32_e32 v82, v82
	v_exp_f32_e32 v83, v83
	v_mfma_f32_32x32x16_bf16 v[48:63], v[152:155], v[116:119], v[48:63]
	ds_read_b64_tr_b16 v[112:113], v177 offset:41984
	ds_read_b64_tr_b16 v[114:115], v177 offset:42496
	v_exp_f32_e32 v84, v84
	v_exp_f32_e32 v85, v85
	v_mfma_f32_32x32x16_bf16 v[32:47], v[152:155], v[120:123], v[32:47]
	ds_read_b64_tr_b16 v[116:117], v177 offset:46080
	ds_read_b64_tr_b16 v[118:119], v177 offset:46592
	v_exp_f32_e32 v86, v86
	v_exp_f32_e32 v87, v87
	v_mfma_f32_32x32x16_bf16 v[48:63], v[148:151], v[124:127], v[48:63]
	ds_read_b64_tr_b16 v[120:121], v177 offset:43008
	ds_read_b64_tr_b16 v[122:123], v177 offset:43520
	v_exp_f32_e32 v88, v88
	v_exp_f32_e32 v89, v89
	v_mfma_f32_32x32x16_bf16 v[32:47], v[148:151], v[64:67], v[32:47]
	ds_read_b64_tr_b16 v[124:125], v177 offset:47104
	ds_read_b64_tr_b16 v[126:127], v177 offset:47616
	v_exp_f32_e32 v90, v90
	v_exp_f32_e32 v91, v91
	v_mfma_f32_32x32x16_bf16 v[48:63], v[144:147], v[68:71], v[48:63]
	ds_read_b64_tr_b16 v[64:65], v177 offset:44032
	ds_read_b64_tr_b16 v[66:67], v177 offset:44544
	v_exp_f32_e32 v92, v92
	v_exp_f32_e32 v93, v93
	v_mfma_f32_32x32x16_bf16 v[32:47], v[144:147], v[72:75], v[32:47]
	ds_read_b64_tr_b16 v[68:69], v177 offset:48128
	ds_read_b64_tr_b16 v[70:71], v177 offset:48640
	v_exp_f32_e32 v94, v94
	v_exp_f32_e32 v95, v95
	s_waitcnt lgkmcnt(14)
	v_mfma_f32_32x32x16_bf16 v[16:31], v[156:159], v[76:79], v[16:31]
	v_exp_f32_e32 v96, v96
	v_exp_f32_e32 v97, v97
	s_waitcnt lgkmcnt(12)
; #define SBAR() __builtin_amdgcn_sched_barrier(0)
;   #define RESC() do{ if(!NOMAX&&resc){ asm volatile("s_waitcnt lgkmcnt(0)":::"memory"); \
;       _Pragma("unroll") for(int d_=0;d_<2*VM;++d_) _Pragma("unroll") for(int r=0;r<16;++r)o[d_][r]*=wsf[crow(r,hi)]; } }while(0)
;   #define PKW(P,B) cvtpk_s(P[B],P[B+1])
; __device__ __forceinline__ void pv(f32x16*o,int vb,bf16x8 pa0,bf16x8 pa1,bf16x8 pa2,bf16x8 pa3){
;   #pragma unroll
;   for(int d0=0;d0<2;++d0){s16x4 lo[4],hi[4];
;     #pragma unroll
;     for(int ks=0;ks<4;++ks){
;       asm volatile("ds_read_b64_tr_b16 %0,%1 offset:%c2":"=&v"(lo[ks]):"v"(vb),"i"(d0*4096+ks*1024):"memory");
;       asm volatile("ds_read_b64_tr_b16 %0,%1 offset:%c2":"=&v"(hi[ks]):"v"(vb),"i"(d0*4096+ks*1024+512):"memory");}
;     asm volatile("s_waitcnt lgkmcnt(0)":::"memory");SBAR();
;     ...
;     o[d0]=__builtin_amdgcn_mfma_f32_32x32x16_bf16(pa0,PK(0),o[d0],0,0,0);
;     o[d0]=__builtin_amdgcn_mfma_f32_32x32x16_bf16(pa1,PK(1),o[d0],0,0,0);
;     o[d0]=__builtin_amdgcn_mfma_f32_32x32x16_bf16(pa2,PK(2),o[d0],0,0,0);
;     o[d0]=__builtin_amdgcn_mfma_f32_32x32x16_bf16(pa3,PK(3),o[d0],0,0,0);
;     ...
;   }
; }
; template<int THRL,int VM,bool NOMAX> __device__ __forceinline__ void attn_unit(const bf16*Qb,const bf16*__restrict__ Kh,const bf16*__restrict__ Vh,bf16*Ob,const int NT,const int sp,float*wscr,char*shm){
;     ...
;   STEP(pB0,pB1,pA0,pA1,NT-1,false,false,false); RESC();
;   { float sacc=pB0[0]+pB0[1]; _Pragma("unroll") for(int r=2;r<16;++r)sacc+=pB0[r]; _Pragma("unroll") for(int r=0;r<16;++r)sacc+=pB1[r]; l_reg+=sacc;
;     pw0=(u32x4){PKW(pB0,0),PKW(pB0,2),PKW(pB0,4),PKW(pB0,6)};pw1=(u32x4){PKW(pB0,8),PKW(pB0,10),PKW(pB0,12),PKW(pB0,14)};pw2=(u32x4){PKW(pB1,0),PKW(pB1,2),PKW(pB1,4),PKW(pB1,6)};pw3=(u32x4){PKW(pB1,8),PKW(pB1,10),PKW(pB1,12),PKW(pB1,14)};
;     SBAR(); pv(o,vb0+VM*sl_cur,PAF(0),PAF(1),PAF(2),PAF(3)); if constexpr(VM==2) pv(o+2,vb0+VM*sl_cur+8192,PAF(0),PAF(1),PAF(2),PAF(3)); }
;     ...
;   {auto rr=__builtin_amdgcn_permlane32_swap(__float_as_uint(l_reg),__float_as_uint(l_reg),false,false);l_reg=__uint_as_float(rr[0])+__uint_as_float(rr[1]);}
;   if(hi==0)wsf[32+r32]=l_reg;asm volatile("s_waitcnt lgkmcnt(0)":::"memory");
	v_mfma_f32_32x32x16_bf16 v[0:15], v[156:159], v[128:131], v[0:15]
	v_exp_f32_e32 v98, v98
	v_exp_f32_e32 v99, v99
	s_waitcnt lgkmcnt(10)
	v_mfma_f32_32x32x16_bf16 v[16:31], v[152:155], v[112:115], v[16:31]
	v_exp_f32_e32 v100, v100
	v_exp_f32_e32 v101, v101
	s_waitcnt lgkmcnt(8)
	v_mfma_f32_32x32x16_bf16 v[0:15], v[152:155], v[116:119], v[0:15]
	v_exp_f32_e32 v102, v102
	v_exp_f32_e32 v103, v103
	s_waitcnt lgkmcnt(6)
	v_mfma_f32_32x32x16_bf16 v[16:31], v[148:151], v[120:123], v[16:31]
	v_exp_f32_e32 v104, v104
	v_exp_f32_e32 v105, v105
	s_waitcnt lgkmcnt(4)
	v_mfma_f32_32x32x16_bf16 v[0:15], v[148:151], v[124:127], v[0:15]
	v_exp_f32_e32 v106, v106
	v_exp_f32_e32 v107, v107
	s_waitcnt lgkmcnt(2)
	v_mfma_f32_32x32x16_bf16 v[16:31], v[144:147], v[64:67], v[16:31]
	v_exp_f32_e32 v108, v108
	v_exp_f32_e32 v109, v109
	s_waitcnt lgkmcnt(0)
	v_mfma_f32_32x32x16_bf16 v[0:15], v[144:147], v[68:71], v[0:15]
	v_exp_f32_e32 v110, v110
	v_exp_f32_e32 v111, v111
	v_add_f32_e32 v64, v80, v81
	v_add_f32_e32 v64, v82, v64
	v_add_f32_e32 v64, v83, v64
	v_add_f32_e32 v64, v84, v64
	v_add_f32_e32 v64, v85, v64
	v_add_f32_e32 v64, v86, v64
	v_add_f32_e32 v64, v87, v64
	v_add_f32_e32 v64, v88, v64
	v_add_f32_e32 v64, v89, v64
	v_add_f32_e32 v64, v90, v64
	v_add_f32_e32 v64, v91, v64
	v_add_f32_e32 v64, v92, v64
	v_add_f32_e32 v64, v93, v64
	v_add_f32_e32 v64, v94, v64
	v_add_f32_e32 v64, v95, v64
	v_add_f32_e32 v64, v64, v96
	v_add_f32_e32 v64, v97, v64
	v_add_f32_e32 v64, v98, v64
	v_add_f32_e32 v64, v99, v64
	v_add_f32_e32 v64, v100, v64
	v_add_f32_e32 v64, v101, v64
	v_add_f32_e32 v64, v102, v64
	v_add_f32_e32 v64, v103, v64
	v_add_f32_e32 v64, v104, v64
	v_add_f32_e32 v64, v105, v64
	v_add_f32_e32 v64, v106, v64
	v_add_f32_e32 v64, v107, v64
	v_add_f32_e32 v64, v108, v64
	v_add_f32_e32 v64, v109, v64
	v_add_f32_e32 v64, v110, v64
	v_add_f32_e32 v64, v111, v64
	v_add_f32_e32 v65, v174, v136
	v_add_f32_e32 v64, v65, v64
	v_cvt_pk_bf16_f32 v66, v80, v81
	v_cvt_pk_bf16_f32 v67, v82, v83
	v_cvt_pk_bf16_f32 v68, v84, v85
	v_cvt_pk_bf16_f32 v69, v86, v87
	v_cvt_pk_bf16_f32 v70, v88, v89
	v_cvt_pk_bf16_f32 v71, v90, v91
	v_cvt_pk_bf16_f32 v72, v92, v93
	v_cvt_pk_bf16_f32 v73, v94, v95
	v_cvt_pk_bf16_f32 v74, v96, v97
	v_cvt_pk_bf16_f32 v75, v98, v99
	v_cvt_pk_bf16_f32 v76, v100, v101
	v_cvt_pk_bf16_f32 v77, v102, v103
	v_cvt_pk_bf16_f32 v78, v104, v105
	v_cvt_pk_bf16_f32 v79, v106, v107
	v_cvt_pk_bf16_f32 v80, v108, v109
	v_cvt_pk_bf16_f32 v81, v110, v111
	ds_read_b64_tr_b16 v[82:83],v176 offset:0
	ds_read_b64_tr_b16 v[84:85],v176 offset:512
	ds_read_b64_tr_b16 v[86:87],v176 offset:1024
	ds_read_b64_tr_b16 v[88:89],v176 offset:1536
	ds_read_b64_tr_b16 v[90:91],v176 offset:2048
	ds_read_b64_tr_b16 v[92:93],v176 offset:2560
	ds_read_b64_tr_b16 v[94:95],v176 offset:3072
	ds_read_b64_tr_b16 v[96:97],v176 offset:3584
	s_waitcnt lgkmcnt(0)
	s_nop 0
	v_mfma_f32_32x32x16_bf16 v[48:63], v[66:69], v[82:85], v[48:63]
	ds_read_b64_tr_b16 v[82:83],v176 offset:4096
	ds_read_b64_tr_b16 v[84:85],v176 offset:4608
	v_mfma_f32_32x32x16_bf16 v[48:63], v[70:73], v[86:89], v[48:63]
	ds_read_b64_tr_b16 v[86:87],v176 offset:5120
	ds_read_b64_tr_b16 v[88:89],v176 offset:5632
	v_mfma_f32_32x32x16_bf16 v[48:63], v[74:77], v[90:93], v[48:63]
	ds_read_b64_tr_b16 v[90:91],v176 offset:6144
	ds_read_b64_tr_b16 v[92:93],v176 offset:6656
	ds_read_b64_tr_b16 v[98:99],v176 offset:7168
	ds_read_b64_tr_b16 v[100:101],v176 offset:7680
	s_waitcnt lgkmcnt(0)
	v_mfma_f32_32x32x16_bf16 v[48:63], v[78:81], v[94:97], v[48:63]
	v_mfma_f32_32x32x16_bf16 v[32:47], v[66:69], v[82:85], v[32:47]
	v_add_u32_e32 v65, 0x2000, v176
	ds_read_b64_tr_b16 v[82:83],v65 offset:0
	ds_read_b64_tr_b16 v[84:85],v65 offset:512
	v_mfma_f32_32x32x16_bf16 v[32:47], v[70:73], v[86:89], v[32:47]
	ds_read_b64_tr_b16 v[86:87],v65 offset:1024
	ds_read_b64_tr_b16 v[88:89],v65 offset:1536
	v_mfma_f32_32x32x16_bf16 v[32:47], v[74:77], v[90:93], v[32:47]
	ds_read_b64_tr_b16 v[90:91],v65 offset:2048
	ds_read_b64_tr_b16 v[92:93],v65 offset:2560
	ds_read_b64_tr_b16 v[94:95],v65 offset:3072
	ds_read_b64_tr_b16 v[96:97],v65 offset:3584
	s_waitcnt lgkmcnt(0)
	v_mfma_f32_32x32x16_bf16 v[32:47], v[78:81], v[98:101], v[32:47]
	v_mfma_f32_32x32x16_bf16 v[16:31], v[66:69], v[82:85], v[16:31]
	ds_read_b64_tr_b16 v[82:83],v65 offset:4096
	ds_read_b64_tr_b16 v[84:85],v65 offset:4608
	v_mfma_f32_32x32x16_bf16 v[16:31], v[70:73], v[86:89], v[16:31]
	ds_read_b64_tr_b16 v[86:87],v65 offset:5120
	ds_read_b64_tr_b16 v[88:89],v65 offset:5632
	v_mfma_f32_32x32x16_bf16 v[16:31], v[74:77], v[90:93], v[16:31]
	ds_read_b64_tr_b16 v[90:91],v65 offset:6144
	ds_read_b64_tr_b16 v[92:93],v65 offset:6656
	ds_read_b64_tr_b16 v[98:99],v65 offset:7168
	ds_read_b64_tr_b16 v[100:101],v65 offset:7680
	s_waitcnt lgkmcnt(0)
	v_mfma_f32_32x32x16_bf16 v[16:31], v[78:81], v[94:97], v[16:31]
	v_mfma_f32_32x32x16_bf16 v[0:15], v[66:69], v[82:85], v[0:15]
	v_mov_b32_e32 v65, v64
	s_nop 1
	v_permlane32_swap_b32_e32 v64, v65
	v_cmp_gt_u32_e32 vcc, 32, v187
	v_mfma_f32_32x32x16_bf16 v[0:15], v[70:73], v[86:89], v[0:15]
	v_mfma_f32_32x32x16_bf16 v[0:15], v[74:77], v[90:93], v[0:15]
	v_mfma_f32_32x32x16_bf16 v[0:15], v[78:81], v[98:101], v[0:15]
	s_and_saveexec_b64 s[16:17], vcc
	s_cbranch_execz .LBB0_870
	v_add_f32_e32 v64, v64, v65
	v_lshl_add_u32 v65, v186, 2, s34
	ds_write_b32 v65, v64 offset:128
	s_branch .LBB0_870

; __device__ __forceinline__ void glds16(const void*gsrc,unsigned lds_dst){unsigned keep;
;   asm volatile("s_mov_b32 %0, m0\n\ts_mov_b32 m0, %2\n\ts_nop 0\n\tglobal_load_lds_dwordx4 %1, off\n\ts_mov_b32 m0, %0":"=&s"(keep):"v"(gsrc),"s"(lds_dst):"memory");}
.LBB0_882:
	v_add_u32_e32 v187, s54, v182
	ds_read_b64_tr_b16 v[188:189], v187 offset:24576
	ds_read_b64_tr_b16 v[190:191], v187 offset:25088
	v_add_f32_e32 v88, v64, v65
	v_add_f32_e32 v88, v66, v88
	v_add_f32_e32 v88, v67, v88
	v_add_f32_e32 v88, v68, v88
	v_add_f32_e32 v88, v69, v88
	v_cvt_pk_bf16_f32 v140, v64, v65
	v_cvt_pk_bf16_f32 v141, v66, v67
	v_mfma_f32_32x32x16_bf16 v[96:111], v[84:87], v[156:159], 0
	ds_read_b64_tr_b16 v[64:65], v187 offset:28672
	ds_read_b64_tr_b16 v[66:67], v187 offset:29184
	v_add_f32_e32 v84, v70, v88
	v_add_f32_e32 v84, v71, v84
	v_add_f32_e32 v84, v72, v84
	v_add_f32_e32 v128, v73, v84
	v_mfma_f32_32x32x16_bf16 v[80:95], v[80:83], v[156:159], 0
	v_cvt_pk_bf16_f32 v142, v68, v69
	v_cvt_pk_bf16_f32 v143, v70, v71
	ds_read_b64_tr_b16 v[68:69], v187 offset:25600
	ds_read_b64_tr_b16 v[70:71], v187 offset:26112
	v_add_f32_e32 v128, v74, v128
	v_add_f32_e32 v128, v75, v128
	v_add_f32_e32 v128, v76, v128
	v_add_f32_e32 v128, v77, v128
	v_cvt_pk_bf16_f32 v136, v72, v73
	v_cvt_pk_bf16_f32 v137, v74, v75
	v_mfma_f32_32x32x16_bf16 v[96:111], v[164:167], v[152:155], v[96:111]
	ds_read_b64_tr_b16 v[72:73], v187 offset:29696
	ds_read_b64_tr_b16 v[74:75], v187 offset:30208
	v_mfma_f32_32x32x16_bf16 v[80:95], v[160:163], v[152:155], v[80:95]
	v_add_f32_e32 v128, v78, v128
	v_add_f32_e32 v128, v79, v128
	v_add_f32_e32 v128, v48, v128
	v_add_f32_e32 v128, v49, v128
	v_cvt_pk_bf16_f32 v138, v76, v77
	v_cvt_pk_bf16_f32 v139, v78, v79
	ds_read_b64_tr_b16 v[76:77], v187 offset:26624
	ds_read_b64_tr_b16 v[78:79], v187 offset:27136
	v_add_f32_e32 v128, v50, v128
	v_add_f32_e32 v128, v51, v128
	v_add_f32_e32 v128, v52, v128
	v_add_f32_e32 v128, v53, v128
	v_cvt_pk_bf16_f32 v132, v48, v49
	v_cvt_pk_bf16_f32 v133, v50, v51
	v_mfma_f32_32x32x16_bf16 v[96:111], v[124:127], v[148:151], v[96:111]
	ds_read_b64_tr_b16 v[48:49], v187 offset:30720
	ds_read_b64_tr_b16 v[50:51], v187 offset:31232
	v_mfma_f32_32x32x16_bf16 v[80:95], v[120:123], v[148:151], v[80:95]
	v_add_f32_e32 v124, v54, v128
	v_add_f32_e32 v124, v55, v124
	v_add_f32_e32 v124, v56, v124
	v_add_f32_e32 v124, v57, v124
	v_cvt_pk_bf16_f32 v134, v52, v53
	v_cvt_pk_bf16_f32 v135, v54, v55
	ds_read_b64_tr_b16 v[52:53], v187 offset:27648
	ds_read_b64_tr_b16 v[54:55], v187 offset:28160
	v_add_f32_e32 v120, v58, v124
	v_add_f32_e32 v120, v59, v120
	v_add_f32_e32 v120, v60, v120
	v_add_f32_e32 v120, v61, v120
	v_cvt_pk_bf16_f32 v128, v56, v57
	v_cvt_pk_bf16_f32 v129, v58, v59
	v_mfma_f32_32x32x16_bf16 v[96:111], v[116:119], v[144:147], v[96:111]
	ds_read_b64_tr_b16 v[56:57], v187 offset:31744
	ds_read_b64_tr_b16 v[58:59], v187 offset:32256
	v_mfma_f32_32x32x16_bf16 v[80:95], v[112:115], v[144:147], v[80:95]
	v_add_f32_e32 v116, v62, v120
	v_add_f32_e32 v116, v63, v116
	v_cvt_pk_bf16_f32 v130, v60, v61
	v_cvt_pk_bf16_f32 v131, v62, v63
	s_add_i32 m0, s52, s33
	v_lshl_add_u64 v[60:61], v[176:177], 0, s[38:39]
	global_load_lds_dwordx4 v[60:61], off
	s_add_i32 m0, s35, s16
	v_lshl_add_u64 v[60:61], v[174:175], 0, s[38:39]
	global_load_lds_dwordx4 v[60:61], off
	v_add_f32_e32 v202, v186, v116
	s_waitcnt lgkmcnt(12)
	v_mfma_f32_32x32x16_bf16 v[16:31], v[140:143], v[188:191], v[16:31]
	v_exp_f32_e32 v96, v96
	v_exp_f32_e32 v97, v97
	v_exp_f32_e32 v98, v98
	v_exp_f32_e32 v99, v99
	v_mfma_f32_32x32x16_bf16 v[32:47], v[140:143], v[64:67], v[32:47]
	v_exp_f32_e32 v100, v100
	v_exp_f32_e32 v101, v101
	v_exp_f32_e32 v102, v102
	v_exp_f32_e32 v103, v103
	v_add_u32_e32 v64, s35, v183
	ds_read_b128 v[60:63], v64
	ds_read_b128 v[112:115], v64 offset:512
	s_waitcnt lgkmcnt(10)
	v_mfma_f32_32x32x16_bf16 v[16:31], v[136:139], v[68:71], v[16:31]
	v_exp_f32_e32 v104, v104
	v_exp_f32_e32 v105, v105
	v_exp_f32_e32 v106, v106
	v_exp_f32_e32 v107, v107
	ds_read_b128 v[116:119], v64 offset:2048
	ds_read_b128 v[120:123], v64 offset:2560
	v_mfma_f32_32x32x16_bf16 v[32:47], v[136:139], v[72:75], v[32:47]
	v_exp_f32_e32 v108, v108
	v_exp_f32_e32 v109, v109
	v_exp_f32_e32 v110, v110
	v_exp_f32_e32 v111, v111
	ds_read_b128 v[124:127], v64 offset:4096
	ds_read_b128 v[160:163], v64 offset:4608
	s_waitcnt lgkmcnt(10)
	v_mfma_f32_32x32x16_bf16 v[16:31], v[132:135], v[76:79], v[16:31]
	v_exp_f32_e32 v80, v80
	v_exp_f32_e32 v81, v81
	v_exp_f32_e32 v82, v82
	v_exp_f32_e32 v83, v83
	ds_read_b128 v[164:167], v64 offset:6144
	ds_read_b128 v[186:189], v64 offset:6656
	v_mfma_f32_32x32x16_bf16 v[32:47], v[132:135], v[48:51], v[32:47]
	v_exp_f32_e32 v84, v84
	v_exp_f32_e32 v85, v85
	v_exp_f32_e32 v86, v86
	v_exp_f32_e32 v87, v87
	s_waitcnt lgkmcnt(8)
	v_mfma_f32_32x32x16_bf16 v[16:31], v[128:131], v[52:55], v[16:31]
	v_exp_f32_e32 v88, v88
	v_exp_f32_e32 v89, v89
	v_exp_f32_e32 v90, v90
	v_exp_f32_e32 v91, v91
	v_mfma_f32_32x32x16_bf16 v[32:47], v[128:131], v[56:59], v[32:47]
	v_exp_f32_e32 v92, v92
	v_exp_f32_e32 v93, v93
	v_exp_f32_e32 v94, v94
	v_exp_f32_e32 v95, v95
	s_waitcnt vmcnt(2) lgkmcnt(0)
	s_barrier
; #define WAIT_BAR(N) asm volatile("s_waitcnt vmcnt(" #N ") lgkmcnt(0)\n\ts_barrier":::"memory")
;   #define RESC() do{ if(!NOMAX&&resc){ asm volatile("s_waitcnt lgkmcnt(0)":::"memory"); \
;       _Pragma("unroll") for(int d_=0;d_<2*VM;++d_) _Pragma("unroll") for(int r=0;r<16;++r)o[d_][r]*=wsf[crow(r,hi)]; } }while(0)
;   #define ROT() do{sl_prev=sl_cur;sl_cur=sl_next;sl_next=(sl_next==(NSLOT-1)*SLOTB)?0:sl_next+SLOTB;}while(0)
; __device__ __forceinline__ void glds16(const void*gsrc,unsigned lds_dst){unsigned keep;
;   asm volatile("s_mov_b32 %0, m0\n\ts_mov_b32 m0, %2\n\ts_nop 0\n\tglobal_load_lds_dwordx4 %1, off\n\ts_mov_b32 m0, %0":"=&s"(keep):"v"(gsrc),"s"(lds_dst):"memory");}
; template<int THRL,int VM,bool NOMAX> __device__ __forceinline__ void attn_unit(const bf16*Qb,const bf16*__restrict__ Kh,const bf16*__restrict__ Vh,bf16*Ob,const int NT,const int sp,float*wscr,char*shm){
;     ...
;   int t=1;
;   for(;t+5<NT;t+=2){
;     STEP(pB0,pB1,pA0,pA1,t,true,true,true);     if constexpr(VM==2){WAIT_BAR(3);}else{WAIT_BAR(2);} RESC(); ROT();
;     STEP(pA0,pA1,pB0,pB1,t+1,true,true,true);   if constexpr(VM==2){WAIT_BAR(3);}else{WAIT_BAR(2);} RESC(); ROT();
	s_add_i32 s53, s35, 0x2000
	s_cmpk_lg_i32 s35, 0x4000
	s_cselect_b32 s53, s53, 0
	v_add_u32_e32 v203, s52, v182
	ds_read_b64_tr_b16 v[190:191], v203 offset:24576
	ds_read_b64_tr_b16 v[192:193], v203 offset:25088
	v_mfma_f32_32x32x16_bf16 v[64:79], v[60:63], v[156:159], 0
	v_add_f32_e32 v48, v96, v97
	v_add_f32_e32 v48, v98, v48
	v_add_f32_e32 v48, v99, v48
	v_add_f32_e32 v48, v100, v48
	v_add_f32_e32 v48, v101, v48
	v_cvt_pk_bf16_f32 v140, v96, v97
	v_cvt_pk_bf16_f32 v141, v98, v99
	ds_read_b64_tr_b16 v[96:97], v203 offset:28672
	ds_read_b64_tr_b16 v[98:99], v203 offset:29184
	v_add_f32_e32 v48, v102, v48
	v_add_f32_e32 v48, v103, v48
	v_add_f32_e32 v48, v104, v48
	v_add_f32_e32 v128, v105, v48
	v_mfma_f32_32x32x16_bf16 v[48:63], v[112:115], v[156:159], 0
	v_cvt_pk_bf16_f32 v142, v100, v101
	v_cvt_pk_bf16_f32 v143, v102, v103
	ds_read_b64_tr_b16 v[100:101], v203 offset:25600
	ds_read_b64_tr_b16 v[102:103], v203 offset:26112
	v_mfma_f32_32x32x16_bf16 v[64:79], v[116:119], v[152:155], v[64:79]
	v_add_f32_e32 v112, v106, v128
	v_add_f32_e32 v112, v107, v112
	v_add_f32_e32 v112, v108, v112
	v_add_f32_e32 v112, v109, v112
	v_cvt_pk_bf16_f32 v136, v104, v105
	v_cvt_pk_bf16_f32 v137, v106, v107
	ds_read_b64_tr_b16 v[104:105], v203 offset:29696
	ds_read_b64_tr_b16 v[106:107], v203 offset:30208
	v_mfma_f32_32x32x16_bf16 v[48:63], v[120:123], v[152:155], v[48:63]
	v_add_f32_e32 v112, v110, v112
	v_add_f32_e32 v112, v111, v112
	v_add_f32_e32 v112, v80, v112
	v_add_f32_e32 v112, v81, v112
	v_cvt_pk_bf16_f32 v138, v108, v109
	v_cvt_pk_bf16_f32 v139, v110, v111
	ds_read_b64_tr_b16 v[108:109], v203 offset:26624
	ds_read_b64_tr_b16 v[110:111], v203 offset:27136
	v_mfma_f32_32x32x16_bf16 v[64:79], v[124:127], v[148:151], v[64:79]
	v_add_f32_e32 v112, v82, v112
	v_add_f32_e32 v112, v83, v112
	v_add_f32_e32 v112, v84, v112
	v_add_f32_e32 v112, v85, v112
	v_cvt_pk_bf16_f32 v132, v80, v81
	v_cvt_pk_bf16_f32 v133, v82, v83
	ds_read_b64_tr_b16 v[194:195], v203 offset:30720
	ds_read_b64_tr_b16 v[196:197], v203 offset:31232
	v_mfma_f32_32x32x16_bf16 v[48:63], v[160:163], v[148:151], v[48:63]
	v_add_f32_e32 v80, v86, v112
	v_add_f32_e32 v80, v87, v80
	v_add_f32_e32 v80, v88, v80
	v_add_f32_e32 v80, v89, v80
	v_cvt_pk_bf16_f32 v134, v84, v85
	v_cvt_pk_bf16_f32 v135, v86, v87
	ds_read_b64_tr_b16 v[198:199], v203 offset:27648
	ds_read_b64_tr_b16 v[200:201], v203 offset:28160
	v_mfma_f32_32x32x16_bf16 v[64:79], v[164:167], v[144:147], v[64:79]
	v_add_f32_e32 v80, v90, v80
	v_add_f32_e32 v80, v91, v80
	v_add_f32_e32 v80, v92, v80
	v_add_f32_e32 v80, v93, v80
	v_cvt_pk_bf16_f32 v128, v88, v89
	v_cvt_pk_bf16_f32 v129, v90, v91
	ds_read_b64_tr_b16 v[88:89], v203 offset:31744
	ds_read_b64_tr_b16 v[90:91], v203 offset:32256
	v_mfma_f32_32x32x16_bf16 v[48:63], v[186:189], v[144:147], v[48:63]
	v_add_f32_e32 v80, v94, v80
	v_add_f32_e32 v80, v95, v80
	v_cvt_pk_bf16_f32 v130, v92, v93
	v_cvt_pk_bf16_f32 v131, v94, v95
	s_add_i32 m0, s35, s33
	s_nop 0
	global_load_lds_dwordx4 v[176:177], off
	s_add_i32 m0, s53, s16
	s_nop 0
	global_load_lds_dwordx4 v[174:175], off
	v_add_f32_e32 v186, v202, v80
	s_waitcnt lgkmcnt(12)
	v_mfma_f32_32x32x16_bf16 v[16:31], v[140:143], v[190:193], v[16:31]
	v_exp_f32_e32 v64, v64
	v_exp_f32_e32 v65, v65
	v_exp_f32_e32 v66, v66
	v_exp_f32_e32 v67, v67
	v_mfma_f32_32x32x16_bf16 v[32:47], v[140:143], v[96:99], v[32:47]
	v_exp_f32_e32 v68, v68
	v_exp_f32_e32 v69, v69
	v_exp_f32_e32 v70, v70
	v_exp_f32_e32 v71, v71
	v_add_u32_e32 v92, s53, v183
	ds_read_b128 v[84:87], v92
	ds_read_b128 v[80:83], v92 offset:512
	s_waitcnt lgkmcnt(10)
	v_mfma_f32_32x32x16_bf16 v[16:31], v[136:139], v[100:103], v[16:31]
	v_exp_f32_e32 v72, v72
	v_exp_f32_e32 v73, v73
	v_exp_f32_e32 v74, v74
	v_exp_f32_e32 v75, v75
	ds_read_b128 v[164:167], v92 offset:2048
	ds_read_b128 v[160:163], v92 offset:2560
	v_mfma_f32_32x32x16_bf16 v[32:47], v[136:139], v[104:107], v[32:47]
	v_exp_f32_e32 v76, v76
	v_exp_f32_e32 v77, v77
	v_exp_f32_e32 v78, v78
	v_exp_f32_e32 v79, v79
	ds_read_b128 v[124:127], v92 offset:4096
	ds_read_b128 v[120:123], v92 offset:4608
	s_waitcnt lgkmcnt(10)
	v_mfma_f32_32x32x16_bf16 v[16:31], v[132:135], v[108:111], v[16:31]
	v_exp_f32_e32 v48, v48
	v_exp_f32_e32 v49, v49
	v_exp_f32_e32 v50, v50
	v_exp_f32_e32 v51, v51
	ds_read_b128 v[116:119], v92 offset:6144
	ds_read_b128 v[112:115], v92 offset:6656
	v_mfma_f32_32x32x16_bf16 v[32:47], v[132:135], v[194:197], v[32:47]
	v_exp_f32_e32 v52, v52
	v_exp_f32_e32 v53, v53
	v_exp_f32_e32 v54, v54
	v_exp_f32_e32 v55, v55
	s_waitcnt lgkmcnt(8)
	v_mfma_f32_32x32x16_bf16 v[16:31], v[128:131], v[198:201], v[16:31]
	v_exp_f32_e32 v56, v56
	v_exp_f32_e32 v57, v57
	v_exp_f32_e32 v58, v58
	v_exp_f32_e32 v59, v59
	v_mfma_f32_32x32x16_bf16 v[32:47], v[128:131], v[88:91], v[32:47]
	v_exp_f32_e32 v60, v60
	v_exp_f32_e32 v61, v61
	v_exp_f32_e32 v62, v62
	v_exp_f32_e32 v63, v63
	s_add_i32 s55, s53, 0x2000
	s_waitcnt vmcnt(2) lgkmcnt(0)
	s_barrier
	s_cmpk_lg_i32 s53, 0x4000
	s_mov_b32 s54, s35
	s_cselect_b32 s35, s55, 0
	s_add_i32 s34, s34, 2
	v_lshl_add_u64 v[174:175], v[174:175], 0, s[8:9]
	v_lshl_add_u64 v[176:177], v[176:177], 0, s[8:9]
	s_mov_b32 s52, s53
	s_cmpk_lt_u32 s34, 0x79
	s_cbranch_scc1 .LBB0_882
;   #define RESC() do{ if(!NOMAX&&resc){ asm volatile("s_waitcnt lgkmcnt(0)":::"memory"); \
;       _Pragma("unroll") for(int d_=0;d_<2*VM;++d_) _Pragma("unroll") for(int r=0;r<16;++r)o[d_][r]*=wsf[crow(r,hi)]; } }while(0)
;   #define ROT() do{sl_prev=sl_cur;sl_cur=sl_next;sl_next=(sl_next==(NSLOT-1)*SLOTB)?0:sl_next+SLOTB;}while(0)
;   #define ENDW(tt) do{ if((tt)+3<NT){ if constexpr(VM==2){WAIT_BAR(3);}else{WAIT_BAR(2);} } else if((tt)+2<NT){ if constexpr(VM==2){WAIT_BAR(2);}else{WAIT_BAR(1);} } else {WAIT_BAR(0);} }while(0)
; template<int THRL,int VM,bool NOMAX> __device__ __forceinline__ void attn_unit(const bf16*Qb,const bf16*__restrict__ Kh,const bf16*__restrict__ Vh,bf16*Ob,const int NT,const int sp,float*wscr,char*shm){
;     ...
;   for(;t+1<NT;t+=2){
;     STEP(pB0,pB1,pA0,pA1,t,(t+3<NT),(t+1<NT),(t+1<NT));       ENDW(t);   RESC(); ROT();
;     STEP(pA0,pA1,pB0,pB1,t+1,(t+4<NT),(t+2<NT),(t+2<NT));     ENDW(t+1); RESC(); ROT();
	s_and_b32 s29, s29, 0x3fffffc0
	s_lshl_b32 s29, s29, 2
	s_add_i32 s29, s29, 0
	s_cmp_lg_u32 0, -1
	s_cselect_b32 s34, 0, 0
	s_add_i32 s35, s34, 0x6000
	v_add3_u32 v174, v185, s35, v184
	ds_read_b64_tr_b16 v[188:189], v182 offset:40960
	ds_read_b64_tr_b16 v[190:191], v182 offset:41472
	v_add_f32_e32 v88, v64, v65
	v_add_f32_e32 v88, v66, v88
	v_add_f32_e32 v88, v67, v88
	v_add_f32_e32 v88, v68, v88
	v_add_f32_e32 v88, v69, v88
	v_cvt_pk_bf16_f32 v140, v64, v65
	v_cvt_pk_bf16_f32 v141, v66, v67
	s_waitcnt lgkmcnt(9)
	v_mfma_f32_32x32x16_bf16 v[96:111], v[84:87], v[156:159], 0
	ds_read_b64_tr_b16 v[64:65], v182 offset:45056
	ds_read_b64_tr_b16 v[66:67], v182 offset:45568
	v_add_f32_e32 v84, v70, v88
	v_add_f32_e32 v84, v71, v84
	v_add_f32_e32 v84, v72, v84
	v_add_f32_e32 v128, v73, v84
	v_cvt_pk_bf16_f32 v142, v68, v69
	v_cvt_pk_bf16_f32 v143, v70, v71
	s_waitcnt lgkmcnt(10)
	v_mfma_f32_32x32x16_bf16 v[80:95], v[80:83], v[156:159], 0
	ds_read_b64_tr_b16 v[68:69], v182 offset:41984
	ds_read_b64_tr_b16 v[70:71], v182 offset:42496
	v_add_f32_e32 v128, v74, v128
	v_add_f32_e32 v128, v75, v128
	v_add_f32_e32 v128, v76, v128
	v_add_f32_e32 v128, v77, v128
	v_cvt_pk_bf16_f32 v136, v72, v73
	v_cvt_pk_bf16_f32 v137, v74, v75
	s_waitcnt lgkmcnt(11)
	v_mfma_f32_32x32x16_bf16 v[96:111], v[164:167], v[152:155], v[96:111]
	ds_read_b64_tr_b16 v[72:73], v182 offset:46080
	ds_read_b64_tr_b16 v[74:75], v182 offset:46592
	v_add_f32_e32 v128, v78, v128
	v_add_f32_e32 v128, v79, v128
	v_add_f32_e32 v128, v48, v128
	v_add_f32_e32 v128, v49, v128
	v_cvt_pk_bf16_f32 v138, v76, v77
	v_cvt_pk_bf16_f32 v139, v78, v79
	s_waitcnt lgkmcnt(12)
	v_mfma_f32_32x32x16_bf16 v[80:95], v[160:163], v[152:155], v[80:95]
	ds_read_b64_tr_b16 v[76:77], v182 offset:43008
	ds_read_b64_tr_b16 v[78:79], v182 offset:43520
	v_add_f32_e32 v128, v50, v128
	v_add_f32_e32 v128, v51, v128
	v_add_f32_e32 v128, v52, v128
	v_add_f32_e32 v128, v53, v128
	v_cvt_pk_bf16_f32 v132, v48, v49
	v_cvt_pk_bf16_f32 v133, v50, v51
	s_waitcnt lgkmcnt(13)
	v_mfma_f32_32x32x16_bf16 v[96:111], v[124:127], v[148:151], v[96:111]
	ds_read_b64_tr_b16 v[48:49], v182 offset:47104
	ds_read_b64_tr_b16 v[50:51], v182 offset:47616
	v_add_f32_e32 v124, v54, v128
	v_add_f32_e32 v124, v55, v124
	v_add_f32_e32 v124, v56, v124
	v_add_f32_e32 v124, v57, v124
	v_cvt_pk_bf16_f32 v134, v52, v53
	v_cvt_pk_bf16_f32 v135, v54, v55
	s_waitcnt lgkmcnt(14)
	v_mfma_f32_32x32x16_bf16 v[80:95], v[120:123], v[148:151], v[80:95]
	ds_read_b64_tr_b16 v[52:53], v182 offset:44032
	ds_read_b64_tr_b16 v[54:55], v182 offset:44544
	v_add_f32_e32 v120, v58, v124
	v_add_f32_e32 v120, v59, v120
	v_add_f32_e32 v120, v60, v120
	v_add_f32_e32 v120, v61, v120
	v_cvt_pk_bf16_f32 v128, v56, v57
	v_cvt_pk_bf16_f32 v129, v58, v59
	s_waitcnt lgkmcnt(14)
	v_mfma_f32_32x32x16_bf16 v[96:111], v[116:119], v[144:147], v[96:111]
	ds_read_b64_tr_b16 v[56:57], v182 offset:48128
	ds_read_b64_tr_b16 v[58:59], v182 offset:48640
	v_add_f32_e32 v116, v62, v120
	v_add_f32_e32 v116, v63, v116
	v_add_f32_e32 v116, 0, v116
	v_cvt_pk_bf16_f32 v130, v60, v61
	v_cvt_pk_bf16_f32 v131, v62, v63
	v_mfma_f32_32x32x16_bf16 v[80:95], v[112:115], v[144:147], v[80:95]
	v_lshl_add_u64 v[60:61], v[172:173], 0, s[40:41]
	s_mov_b32 s35, m0
	s_mov_b32 m0, s33
	s_nop 0
	global_load_lds_dwordx4 v[60:61], off
	s_mov_b32 m0, s35
	s_add_i32 s33, s34, s17
	v_lshl_add_u64 v[60:61], v[170:171], 0, s[42:43]
	s_add_i32 s17, s33, 0x8000
	s_mov_b32 s34, m0
	s_mov_b32 m0, s17
	s_nop 0
	global_load_lds_dwordx4 v[60:61], off
	s_mov_b32 m0, s34
	v_add_f32_e32 v175, v186, v116
	s_waitcnt lgkmcnt(14)
	v_mfma_f32_32x32x16_bf16 v[16:31], v[140:143], v[188:191], v[16:31]
	v_exp_f32_e32 v96, v96
	v_exp_f32_e32 v97, v97
	v_exp_f32_e32 v98, v98
	v_exp_f32_e32 v99, v99
	s_waitcnt lgkmcnt(12)
	v_mfma_f32_32x32x16_bf16 v[32:47], v[140:143], v[64:67], v[32:47]
	v_exp_f32_e32 v100, v100
	v_exp_f32_e32 v101, v101
	v_exp_f32_e32 v102, v102
	v_exp_f32_e32 v103, v103
	ds_read_b128 v[60:63], v183 offset:8192
	ds_read_b128 v[64:67], v183 offset:8704
	s_waitcnt lgkmcnt(12)
	v_mfma_f32_32x32x16_bf16 v[16:31], v[136:139], v[68:71], v[16:31]
	v_exp_f32_e32 v104, v104
	v_exp_f32_e32 v105, v105
	v_exp_f32_e32 v106, v106
	v_exp_f32_e32 v107, v107
	ds_read_b128 v[68:71], v183 offset:10240
	ds_read_b128 v[160:163], v183 offset:10752
	s_waitcnt lgkmcnt(12)
	v_mfma_f32_32x32x16_bf16 v[32:47], v[136:139], v[72:75], v[32:47]
	v_exp_f32_e32 v108, v108
	v_exp_f32_e32 v109, v109
	v_exp_f32_e32 v110, v110
	v_exp_f32_e32 v111, v111
	ds_read_b128 v[72:75], v183 offset:12288
	ds_read_b128 v[164:167], v183 offset:12800
	s_waitcnt lgkmcnt(12)
	v_mfma_f32_32x32x16_bf16 v[16:31], v[132:135], v[76:79], v[16:31]
	v_exp_f32_e32 v80, v80
	v_exp_f32_e32 v81, v81
	v_exp_f32_e32 v82, v82
	v_exp_f32_e32 v83, v83
	ds_read_b128 v[76:79], v183 offset:14336
	ds_read_b128 v[184:187], v183 offset:14848
	s_waitcnt lgkmcnt(12)
	v_mfma_f32_32x32x16_bf16 v[32:47], v[132:135], v[48:51], v[32:47]
	v_exp_f32_e32 v84, v84
	v_exp_f32_e32 v85, v85
	v_exp_f32_e32 v86, v86
	v_exp_f32_e32 v87, v87
	s_waitcnt lgkmcnt(10)
	v_mfma_f32_32x32x16_bf16 v[16:31], v[128:131], v[52:55], v[16:31]
	v_exp_f32_e32 v88, v88
	v_exp_f32_e32 v89, v89
	v_exp_f32_e32 v90, v90
	v_exp_f32_e32 v91, v91
	s_waitcnt lgkmcnt(8)
	v_mfma_f32_32x32x16_bf16 v[32:47], v[128:131], v[56:59], v[32:47]
	v_exp_f32_e32 v92, v92
	v_exp_f32_e32 v93, v93
	v_exp_f32_e32 v94, v94
	v_exp_f32_e32 v95, v95
	s_waitcnt vmcnt(2) lgkmcnt(0)
	s_barrier
;   #define RESC() do{ if(!NOMAX&&resc){ asm volatile("s_waitcnt lgkmcnt(0)":::"memory"); \
;       _Pragma("unroll") for(int d_=0;d_<2*VM;++d_) _Pragma("unroll") for(int r=0;r<16;++r)o[d_][r]*=wsf[crow(r,hi)]; } }while(0)
;   #define ROT() do{sl_prev=sl_cur;sl_cur=sl_next;sl_next=(sl_next==(NSLOT-1)*SLOTB)?0:sl_next+SLOTB;}while(0)
;   #define ENDW(tt) do{ if((tt)+3<NT){ if constexpr(VM==2){WAIT_BAR(3);}else{WAIT_BAR(2);} } else if((tt)+2<NT){ if constexpr(VM==2){WAIT_BAR(2);}else{WAIT_BAR(1);} } else {WAIT_BAR(0);} }while(0)
; template<int THRL,int VM,bool NOMAX> __device__ __forceinline__ void attn_unit(const bf16*Qb,const bf16*__restrict__ Kh,const bf16*__restrict__ Vh,bf16*Ob,const int NT,const int sp,float*wscr,char*shm){
;     ...
;   for(;t+1<NT;t+=2){
;     STEP(pB0,pB1,pA0,pA1,t,(t+3<NT),(t+1<NT),(t+1<NT));       ENDW(t);   RESC(); ROT();
;     STEP(pA0,pA1,pB0,pB1,t+1,(t+4<NT),(t+2<NT),(t+2<NT));     ENDW(t+1); RESC(); ROT();
	ds_read_b64_tr_b16 v[188:189], v182 offset:24576
	ds_read_b64_tr_b16 v[190:191], v182 offset:25088
	v_add_f32_e32 v48, v96, v97
	v_add_f32_e32 v48, v98, v48
	v_add_f32_e32 v48, v99, v48
	v_add_f32_e32 v48, v100, v48
	v_add_f32_e32 v48, v101, v48
	v_cvt_pk_bf16_f32 v140, v96, v97
	v_cvt_pk_bf16_f32 v141, v98, v99
	s_waitcnt lgkmcnt(9)
	v_mfma_f32_32x32x16_bf16 v[112:127], v[60:63], v[156:159], 0
	ds_read_b64_tr_b16 v[96:97], v182 offset:28672
	ds_read_b64_tr_b16 v[98:99], v182 offset:29184
	v_add_f32_e32 v48, v102, v48
	v_add_f32_e32 v48, v103, v48
	v_add_f32_e32 v48, v104, v48
	v_add_f32_e32 v128, v105, v48
	s_waitcnt lgkmcnt(10)
	v_mfma_f32_32x32x16_bf16 v[48:63], v[64:67], v[156:159], 0
	v_cvt_pk_bf16_f32 v142, v100, v101
	v_cvt_pk_bf16_f32 v143, v102, v103
	ds_read_b64_tr_b16 v[64:65], v182 offset:25600
	ds_read_b64_tr_b16 v[66:67], v182 offset:26112
	v_add_f32_e32 v100, v106, v128
	v_add_f32_e32 v100, v107, v100
	v_add_f32_e32 v100, v108, v100
	v_add_f32_e32 v100, v109, v100
	v_cvt_pk_bf16_f32 v136, v104, v105
	v_cvt_pk_bf16_f32 v137, v106, v107
	s_waitcnt lgkmcnt(11)
	v_mfma_f32_32x32x16_bf16 v[112:127], v[68:71], v[152:155], v[112:127]
	ds_read_b64_tr_b16 v[68:69], v182 offset:29696
	ds_read_b64_tr_b16 v[70:71], v182 offset:30208
	s_waitcnt lgkmcnt(12)
	v_mfma_f32_32x32x16_bf16 v[48:63], v[160:163], v[152:155], v[48:63]
	v_add_f32_e32 v100, v110, v100
	v_add_f32_e32 v100, v111, v100
	v_add_f32_e32 v100, v80, v100
	v_add_f32_e32 v104, v81, v100
	v_cvt_pk_bf16_f32 v138, v108, v109
	v_cvt_pk_bf16_f32 v139, v110, v111
	ds_read_b64_tr_b16 v[100:101], v182 offset:26624
	ds_read_b64_tr_b16 v[102:103], v182 offset:27136
	v_add_f32_e32 v104, v82, v104
	v_add_f32_e32 v104, v83, v104
	v_add_f32_e32 v104, v84, v104
	v_add_f32_e32 v104, v85, v104
	v_cvt_pk_bf16_f32 v132, v80, v81
	v_cvt_pk_bf16_f32 v133, v82, v83
	s_waitcnt lgkmcnt(13)
	v_mfma_f32_32x32x16_bf16 v[112:127], v[72:75], v[148:151], v[112:127]
	ds_read_b64_tr_b16 v[72:73], v182 offset:30720
	ds_read_b64_tr_b16 v[74:75], v182 offset:31232
	s_waitcnt lgkmcnt(14)
	v_mfma_f32_32x32x16_bf16 v[48:63], v[164:167], v[148:151], v[48:63]
	v_add_f32_e32 v80, v86, v104
	v_add_f32_e32 v80, v87, v80
	v_add_f32_e32 v80, v88, v80
	v_add_f32_e32 v104, v89, v80
	v_cvt_pk_bf16_f32 v134, v84, v85
	v_cvt_pk_bf16_f32 v135, v86, v87
	ds_read_b64_tr_b16 v[80:81], v182 offset:27648
	ds_read_b64_tr_b16 v[82:83], v182 offset:28160
	v_add_f32_e32 v84, v90, v104
	v_add_f32_e32 v84, v91, v84
	v_add_f32_e32 v84, v92, v84
	v_add_f32_e32 v84, v93, v84
	v_cvt_pk_bf16_f32 v128, v88, v89
	v_cvt_pk_bf16_f32 v129, v90, v91
	s_waitcnt lgkmcnt(14)
	v_mfma_f32_32x32x16_bf16 v[112:127], v[76:79], v[144:147], v[112:127]
	ds_read_b64_tr_b16 v[76:77], v182 offset:31744
	ds_read_b64_tr_b16 v[78:79], v182 offset:32256
	v_mfma_f32_32x32x16_bf16 v[48:63], v[184:187], v[144:147], v[48:63]
	v_add_f32_e32 v84, v94, v84
	v_add_f32_e32 v84, v95, v84
	v_add_f32_e32 v84, 0, v84
	v_cvt_pk_bf16_f32 v130, v92, v93
	v_cvt_pk_bf16_f32 v131, v94, v95
	s_nop 0
	v_add_f32_e32 v175, v175, v84
	v_lshl_add_u64 v[84:85], v[172:173], 0, s[44:45]
	s_add_i32 s34, s33, 0x2000
	s_mov_b32 s35, m0
	s_mov_b32 m0, s34
	s_nop 0
	global_load_lds_dwordx4 v[84:85], off
	s_mov_b32 m0, s35
	v_lshl_add_u64 v[84:85], v[170:171], 0, s[48:49]
	s_add_i32 s33, s33, 0xa000
	s_mov_b32 s34, m0
	s_mov_b32 m0, s33
	s_nop 0
	global_load_lds_dwordx4 v[84:85], off
	s_mov_b32 m0, s34
	s_waitcnt lgkmcnt(14)
	v_mfma_f32_32x32x16_bf16 v[16:31], v[140:143], v[188:191], v[16:31]
	v_exp_f32_e32 v112, v112
	v_exp_f32_e32 v113, v113
	v_exp_f32_e32 v114, v114
	v_exp_f32_e32 v115, v115
	s_waitcnt lgkmcnt(12)
	v_mfma_f32_32x32x16_bf16 v[32:47], v[140:143], v[96:99], v[32:47]
	v_exp_f32_e32 v116, v116
	v_exp_f32_e32 v117, v117
	v_exp_f32_e32 v118, v118
	v_exp_f32_e32 v119, v119
	ds_read_b128 v[84:87], v183 offset:16384
	ds_read_b128 v[96:99], v183 offset:16896
	s_waitcnt lgkmcnt(12)
	v_mfma_f32_32x32x16_bf16 v[16:31], v[136:139], v[64:67], v[16:31]
	v_exp_f32_e32 v120, v120
	v_exp_f32_e32 v121, v121
	v_exp_f32_e32 v122, v122
	v_exp_f32_e32 v123, v123
	ds_read_b128 v[104:107], v183 offset:18432
	ds_read_b128 v[108:111], v183 offset:18944
	s_waitcnt lgkmcnt(12)
	v_mfma_f32_32x32x16_bf16 v[32:47], v[136:139], v[68:71], v[32:47]
	v_exp_f32_e32 v124, v124
	v_exp_f32_e32 v125, v125
	v_exp_f32_e32 v126, v126
	v_exp_f32_e32 v127, v127
	ds_read_b128 v[160:163], v183 offset:20480
	ds_read_b128 v[164:167], v183 offset:20992
	s_waitcnt lgkmcnt(12)
	v_mfma_f32_32x32x16_bf16 v[16:31], v[132:135], v[100:103], v[16:31]
	v_exp_f32_e32 v48, v48
	v_exp_f32_e32 v49, v49
	v_exp_f32_e32 v50, v50
	v_exp_f32_e32 v51, v51
	ds_read_b128 v[100:103], v183 offset:22528
	ds_read_b128 v[184:187], v183 offset:23040
	s_waitcnt lgkmcnt(12)
	v_mfma_f32_32x32x16_bf16 v[32:47], v[132:135], v[72:75], v[32:47]
	v_exp_f32_e32 v52, v52
	v_exp_f32_e32 v53, v53
	v_exp_f32_e32 v54, v54
	v_exp_f32_e32 v55, v55
	s_waitcnt lgkmcnt(10)
	v_mfma_f32_32x32x16_bf16 v[16:31], v[128:131], v[80:83], v[16:31]
	v_exp_f32_e32 v56, v56
	v_exp_f32_e32 v57, v57
	v_exp_f32_e32 v58, v58
	v_exp_f32_e32 v59, v59
	s_waitcnt lgkmcnt(8)
	v_mfma_f32_32x32x16_bf16 v[32:47], v[128:131], v[76:79], v[32:47]
	v_exp_f32_e32 v60, v60
	v_exp_f32_e32 v61, v61
	v_exp_f32_e32 v62, v62
	v_exp_f32_e32 v63, v63
	s_waitcnt vmcnt(2) lgkmcnt(0)
	s_barrier
;   #define RESC() do{ if(!NOMAX&&resc){ asm volatile("s_waitcnt lgkmcnt(0)":::"memory"); \
;       _Pragma("unroll") for(int d_=0;d_<2*VM;++d_) _Pragma("unroll") for(int r=0;r<16;++r)o[d_][r]*=wsf[crow(r,hi)]; } }while(0)
;   #define ROT() do{sl_prev=sl_cur;sl_cur=sl_next;sl_next=(sl_next==(NSLOT-1)*SLOTB)?0:sl_next+SLOTB;}while(0)
;   #define ENDW(tt) do{ if((tt)+3<NT){ if constexpr(VM==2){WAIT_BAR(3);}else{WAIT_BAR(2);} } else if((tt)+2<NT){ if constexpr(VM==2){WAIT_BAR(2);}else{WAIT_BAR(1);} } else {WAIT_BAR(0);} }while(0)
; template<int THRL,int VM,bool NOMAX> __device__ __forceinline__ void attn_unit(const bf16*Qb,const bf16*__restrict__ Kh,const bf16*__restrict__ Vh,bf16*Ob,const int NT,const int sp,float*wscr,char*shm){
;     ...
;   for(;t+1<NT;t+=2){
;     STEP(pB0,pB1,pA0,pA1,t,(t+3<NT),(t+1<NT),(t+1<NT));       ENDW(t);   RESC(); ROT();
;     STEP(pA0,pA1,pB0,pB1,t+1,(t+4<NT),(t+2<NT),(t+2<NT));     ENDW(t+1); RESC(); ROT();
	ds_read_b64_tr_b16 v[188:189], v182 offset:32768
	ds_read_b64_tr_b16 v[190:191], v182 offset:33280
	v_add_f32_e32 v64, v112, v113
	v_add_f32_e32 v64, v114, v64
	v_add_f32_e32 v64, v115, v64
	v_add_f32_e32 v64, v116, v64
	v_add_f32_e32 v64, v117, v64
	v_cvt_pk_bf16_f32 v140, v112, v113
	v_cvt_pk_bf16_f32 v141, v114, v115
	s_waitcnt lgkmcnt(9)
	v_mfma_f32_32x32x16_bf16 v[80:95], v[84:87], v[156:159], 0
	ds_read_b64_tr_b16 v[112:113], v182 offset:36864
	ds_read_b64_tr_b16 v[114:115], v182 offset:37376
	v_add_f32_e32 v64, v118, v64
	v_add_f32_e32 v64, v119, v64
	v_add_f32_e32 v64, v120, v64
	v_add_f32_e32 v128, v121, v64
	v_cvt_pk_bf16_f32 v142, v116, v117
	v_cvt_pk_bf16_f32 v143, v118, v119
	s_waitcnt lgkmcnt(10)
	v_mfma_f32_32x32x16_bf16 v[64:79], v[96:99], v[156:159], 0
	ds_read_b64_tr_b16 v[96:97], v182 offset:33792
	ds_read_b64_tr_b16 v[98:99], v182 offset:34304
	v_add_f32_e32 v116, v122, v128
	v_add_f32_e32 v116, v123, v116
	v_add_f32_e32 v116, v124, v116
	v_add_f32_e32 v116, v125, v116
	v_cvt_pk_bf16_f32 v136, v120, v121
	v_cvt_pk_bf16_f32 v137, v122, v123
	s_waitcnt lgkmcnt(11)
	v_mfma_f32_32x32x16_bf16 v[80:95], v[104:107], v[152:155], v[80:95]
	ds_read_b64_tr_b16 v[104:105], v182 offset:37888
	ds_read_b64_tr_b16 v[106:107], v182 offset:38400
	v_add_f32_e32 v116, v126, v116
	v_add_f32_e32 v116, v127, v116
	v_add_f32_e32 v116, v48, v116
	v_add_f32_e32 v116, v49, v116
	v_cvt_pk_bf16_f32 v138, v124, v125
	v_cvt_pk_bf16_f32 v139, v126, v127
	s_waitcnt lgkmcnt(12)
	v_mfma_f32_32x32x16_bf16 v[64:79], v[108:111], v[152:155], v[64:79]
	ds_read_b64_tr_b16 v[108:109], v182 offset:34816
	ds_read_b64_tr_b16 v[110:111], v182 offset:35328
	v_add_f32_e32 v116, v50, v116
	v_add_f32_e32 v116, v51, v116
	v_add_f32_e32 v116, v52, v116
	v_add_f32_e32 v116, v53, v116
	v_cvt_pk_bf16_f32 v132, v48, v49
	v_cvt_pk_bf16_f32 v133, v50, v51
	s_waitcnt lgkmcnt(13)
	v_mfma_f32_32x32x16_bf16 v[80:95], v[160:163], v[148:151], v[80:95]
	ds_read_b64_tr_b16 v[48:49], v182 offset:38912
	ds_read_b64_tr_b16 v[50:51], v182 offset:39424
	v_add_f32_e32 v116, v54, v116
	v_add_f32_e32 v116, v55, v116
	v_add_f32_e32 v116, v56, v116
	v_add_f32_e32 v116, v57, v116
	v_cvt_pk_bf16_f32 v134, v52, v53
	v_cvt_pk_bf16_f32 v135, v54, v55
	s_waitcnt lgkmcnt(14)
	v_mfma_f32_32x32x16_bf16 v[64:79], v[164:167], v[148:151], v[64:79]
	ds_read_b64_tr_b16 v[52:53], v182 offset:35840
	ds_read_b64_tr_b16 v[54:55], v182 offset:36352
	v_add_f32_e32 v116, v58, v116
	v_add_f32_e32 v116, v59, v116
	v_add_f32_e32 v116, v60, v116
	v_add_f32_e32 v116, v61, v116
	v_cvt_pk_bf16_f32 v128, v56, v57
	v_cvt_pk_bf16_f32 v129, v58, v59
	s_waitcnt lgkmcnt(14)
	v_mfma_f32_32x32x16_bf16 v[80:95], v[100:103], v[144:147], v[80:95]
	ds_read_b64_tr_b16 v[56:57], v182 offset:39936
	ds_read_b64_tr_b16 v[58:59], v182 offset:40448
	v_add_f32_e32 v100, v62, v116
	v_add_f32_e32 v100, v63, v100
	v_add_f32_e32 v100, 0, v100
	v_cvt_pk_bf16_f32 v130, v60, v61
	v_cvt_pk_bf16_f32 v131, v62, v63
	v_mfma_f32_32x32x16_bf16 v[64:79], v[184:187], v[144:147], v[64:79]
	v_lshl_add_u64 v[60:61], v[170:171], 0, s[40:41]
	s_mov_b32 s33, m0
	s_mov_b32 m0, s16
	s_nop 0
	global_load_lds_dwordx4 v[60:61], off
	s_mov_b32 m0, s33
	v_add_f32_e32 v172, v175, v100
	s_waitcnt lgkmcnt(14)
	v_mfma_f32_32x32x16_bf16 v[16:31], v[140:143], v[188:191], v[16:31]
	v_exp_f32_e32 v80, v80
	v_exp_f32_e32 v81, v81
	v_exp_f32_e32 v82, v82
	v_exp_f32_e32 v83, v83
	s_waitcnt lgkmcnt(12)
	v_mfma_f32_32x32x16_bf16 v[32:47], v[140:143], v[112:115], v[32:47]
	v_exp_f32_e32 v84, v84
	v_exp_f32_e32 v85, v85
	v_exp_f32_e32 v86, v86
	v_exp_f32_e32 v87, v87
	ds_read_b128 v[60:63], v183
	ds_read_b128 v[112:115], v183 offset:512
	s_waitcnt lgkmcnt(12)
	v_mfma_f32_32x32x16_bf16 v[16:31], v[136:139], v[96:99], v[16:31]
	v_exp_f32_e32 v88, v88
	v_exp_f32_e32 v89, v89
	v_exp_f32_e32 v90, v90
	v_exp_f32_e32 v91, v91
	ds_read_b128 v[116:119], v183 offset:2048
	ds_read_b128 v[120:123], v183 offset:2560
	s_waitcnt lgkmcnt(12)
	v_mfma_f32_32x32x16_bf16 v[32:47], v[136:139], v[104:107], v[32:47]
	v_exp_f32_e32 v92, v92
	v_exp_f32_e32 v93, v93
	v_exp_f32_e32 v94, v94
	v_exp_f32_e32 v95, v95
	ds_read_b128 v[124:127], v183 offset:4096
	ds_read_b128 v[160:163], v183 offset:4608
	s_waitcnt lgkmcnt(12)
	v_mfma_f32_32x32x16_bf16 v[16:31], v[132:135], v[108:111], v[16:31]
	v_exp_f32_e32 v64, v64
	v_exp_f32_e32 v65, v65
	v_exp_f32_e32 v66, v66
	v_exp_f32_e32 v67, v67
	ds_read_b128 v[164:167], v183 offset:6144
	ds_read_b128 v[184:187], v183 offset:6656
	s_waitcnt lgkmcnt(12)
	v_mfma_f32_32x32x16_bf16 v[32:47], v[132:135], v[48:51], v[32:47]
	v_exp_f32_e32 v68, v68
	v_exp_f32_e32 v69, v69
	v_exp_f32_e32 v70, v70
	v_exp_f32_e32 v71, v71
	s_waitcnt lgkmcnt(10)
	v_mfma_f32_32x32x16_bf16 v[16:31], v[128:131], v[52:55], v[16:31]
	v_exp_f32_e32 v72, v72
	v_exp_f32_e32 v73, v73
	v_exp_f32_e32 v74, v74
	v_exp_f32_e32 v75, v75
	s_waitcnt lgkmcnt(8)
	v_mfma_f32_32x32x16_bf16 v[32:47], v[128:131], v[56:59], v[32:47]
	v_exp_f32_e32 v76, v76
	v_exp_f32_e32 v77, v77
	v_exp_f32_e32 v78, v78
	v_exp_f32_e32 v79, v79
	s_waitcnt vmcnt(1) lgkmcnt(0)
	s_barrier
;   #define RESC() do{ if(!NOMAX&&resc){ asm volatile("s_waitcnt lgkmcnt(0)":::"memory"); \
;       _Pragma("unroll") for(int d_=0;d_<2*VM;++d_) _Pragma("unroll") for(int r=0;r<16;++r)o[d_][r]*=wsf[crow(r,hi)]; } }while(0)
;   #define ROT() do{sl_prev=sl_cur;sl_cur=sl_next;sl_next=(sl_next==(NSLOT-1)*SLOTB)?0:sl_next+SLOTB;}while(0)
;   #define ENDW(tt) do{ if((tt)+3<NT){ if constexpr(VM==2){WAIT_BAR(3);}else{WAIT_BAR(2);} } else if((tt)+2<NT){ if constexpr(VM==2){WAIT_BAR(2);}else{WAIT_BAR(1);} } else {WAIT_BAR(0);} }while(0)
; template<int THRL,int VM,bool NOMAX> __device__ __forceinline__ void attn_unit(const bf16*Qb,const bf16*__restrict__ Kh,const bf16*__restrict__ Vh,bf16*Ob,const int NT,const int sp,float*wscr,char*shm){
;     ...
;   for(;t+1<NT;t+=2){
;     STEP(pB0,pB1,pA0,pA1,t,(t+3<NT),(t+1<NT),(t+1<NT));       ENDW(t);   RESC(); ROT();
;     STEP(pA0,pA1,pB0,pB1,t+1,(t+4<NT),(t+2<NT),(t+2<NT));     ENDW(t+1); RESC(); ROT();
	ds_read_b64_tr_b16 v[188:189], v182 offset:40960
	ds_read_b64_tr_b16 v[190:191], v182 offset:41472
	v_add_f32_e32 v48, v80, v81
	v_add_f32_e32 v48, v82, v48
	v_add_f32_e32 v48, v83, v48
	v_add_f32_e32 v48, v84, v48
	v_add_f32_e32 v48, v85, v48
	v_cvt_pk_bf16_f32 v140, v80, v81
	v_cvt_pk_bf16_f32 v141, v82, v83
	s_waitcnt lgkmcnt(9)
	v_mfma_f32_32x32x16_bf16 v[96:111], v[60:63], v[156:159], 0
	ds_read_b64_tr_b16 v[80:81], v182 offset:45056
	ds_read_b64_tr_b16 v[82:83], v182 offset:45568
	v_add_f32_e32 v48, v86, v48
	v_add_f32_e32 v48, v87, v48
	v_add_f32_e32 v48, v88, v48
	v_add_f32_e32 v128, v89, v48
	s_waitcnt lgkmcnt(10)
	v_mfma_f32_32x32x16_bf16 v[48:63], v[112:115], v[156:159], 0
	v_cvt_pk_bf16_f32 v142, v84, v85
	v_cvt_pk_bf16_f32 v143, v86, v87
	ds_read_b64_tr_b16 v[84:85], v182 offset:41984
	ds_read_b64_tr_b16 v[86:87], v182 offset:42496
	v_add_f32_e32 v112, v90, v128
	v_add_f32_e32 v112, v91, v112
	v_add_f32_e32 v112, v92, v112
	v_add_f32_e32 v112, v93, v112
	v_cvt_pk_bf16_f32 v136, v88, v89
	v_cvt_pk_bf16_f32 v137, v90, v91
	s_waitcnt lgkmcnt(11)
	v_mfma_f32_32x32x16_bf16 v[96:111], v[116:119], v[152:155], v[96:111]
	ds_read_b64_tr_b16 v[88:89], v182 offset:46080
	ds_read_b64_tr_b16 v[90:91], v182 offset:46592
	s_waitcnt lgkmcnt(12)
	v_mfma_f32_32x32x16_bf16 v[48:63], v[120:123], v[152:155], v[48:63]
	v_add_f32_e32 v112, v94, v112
	v_add_f32_e32 v112, v95, v112
	v_add_f32_e32 v112, v64, v112
	v_add_f32_e32 v112, v65, v112
	v_cvt_pk_bf16_f32 v138, v92, v93
	v_cvt_pk_bf16_f32 v139, v94, v95
	ds_read_b64_tr_b16 v[92:93], v182 offset:43008
	ds_read_b64_tr_b16 v[94:95], v182 offset:43520
	v_add_f32_e32 v112, v66, v112
	v_add_f32_e32 v112, v67, v112
	v_add_f32_e32 v112, v68, v112
	v_add_f32_e32 v112, v69, v112
	v_cvt_pk_bf16_f32 v132, v64, v65
	v_cvt_pk_bf16_f32 v133, v66, v67
	s_waitcnt lgkmcnt(13)
	v_mfma_f32_32x32x16_bf16 v[96:111], v[124:127], v[148:151], v[96:111]
	ds_read_b64_tr_b16 v[64:65], v182 offset:47104
	ds_read_b64_tr_b16 v[66:67], v182 offset:47616
	s_waitcnt lgkmcnt(14)
	v_mfma_f32_32x32x16_bf16 v[48:63], v[160:163], v[148:151], v[48:63]
	v_add_f32_e32 v112, v70, v112
	v_add_f32_e32 v112, v71, v112
	v_add_f32_e32 v112, v72, v112
	v_add_f32_e32 v112, v73, v112
	v_cvt_pk_bf16_f32 v134, v68, v69
	v_cvt_pk_bf16_f32 v135, v70, v71
	ds_read_b64_tr_b16 v[68:69], v182 offset:44032
	ds_read_b64_tr_b16 v[70:71], v182 offset:44544
	v_add_f32_e32 v112, v74, v112
	v_add_f32_e32 v112, v75, v112
	v_add_f32_e32 v112, v76, v112
	v_add_f32_e32 v112, v77, v112
	v_cvt_pk_bf16_f32 v128, v72, v73
	v_cvt_pk_bf16_f32 v129, v74, v75
	s_waitcnt lgkmcnt(14)
	v_mfma_f32_32x32x16_bf16 v[96:111], v[164:167], v[144:147], v[96:111]
	ds_read_b64_tr_b16 v[72:73], v182 offset:48128
	ds_read_b64_tr_b16 v[74:75], v182 offset:48640
	v_mfma_f32_32x32x16_bf16 v[48:63], v[184:187], v[144:147], v[48:63]
	v_add_f32_e32 v112, v78, v112
	v_add_f32_e32 v112, v79, v112
	v_add_f32_e32 v112, 0, v112
	v_cvt_pk_bf16_f32 v130, v76, v77
	v_cvt_pk_bf16_f32 v131, v78, v79
	v_lshl_add_u64 v[76:77], v[170:171], 0, s[44:45]
	s_mov_b32 s16, m0
	s_mov_b32 m0, s17
	s_nop 0
	global_load_lds_dwordx4 v[76:77], off
	s_mov_b32 m0, s16
	v_add_f32_e32 v120, v172, v112
	s_waitcnt lgkmcnt(14)
	v_mfma_f32_32x32x16_bf16 v[16:31], v[140:143], v[188:191], v[16:31]
	v_exp_f32_e32 v96, v96
	v_exp_f32_e32 v97, v97
	v_exp_f32_e32 v98, v98
	v_exp_f32_e32 v99, v99
	s_waitcnt lgkmcnt(12)
	v_mfma_f32_32x32x16_bf16 v[32:47], v[140:143], v[80:83], v[32:47]
	v_exp_f32_e32 v100, v100
	v_exp_f32_e32 v101, v101
	v_exp_f32_e32 v102, v102
	v_exp_f32_e32 v103, v103
	ds_read_b128 v[76:79], v183 offset:8192
	ds_read_b128 v[80:83], v183 offset:8704
	s_waitcnt lgkmcnt(12)
	v_mfma_f32_32x32x16_bf16 v[16:31], v[136:139], v[84:87], v[16:31]
	v_exp_f32_e32 v104, v104
	v_exp_f32_e32 v105, v105
	v_exp_f32_e32 v106, v106
	v_exp_f32_e32 v107, v107
	ds_read_b128 v[122:125], v183 offset:10240
	ds_read_b128 v[160:163], v183 offset:10752
	s_waitcnt lgkmcnt(12)
	v_mfma_f32_32x32x16_bf16 v[32:47], v[136:139], v[88:91], v[32:47]
	v_exp_f32_e32 v108, v108
	v_exp_f32_e32 v109, v109
	v_exp_f32_e32 v110, v110
	v_exp_f32_e32 v111, v111
	ds_read_b128 v[164:167], v183 offset:12288
	ds_read_b128 v[170:173], v183 offset:12800
	s_waitcnt lgkmcnt(12)
	v_mfma_f32_32x32x16_bf16 v[16:31], v[132:135], v[92:95], v[16:31]
	v_exp_f32_e32 v48, v48
	v_exp_f32_e32 v49, v49
	v_exp_f32_e32 v50, v50
	v_exp_f32_e32 v51, v51
	ds_read_b128 v[184:187], v183 offset:14336
	ds_read_b128 v[188:191], v183 offset:14848
	s_waitcnt lgkmcnt(12)
	v_mfma_f32_32x32x16_bf16 v[32:47], v[132:135], v[64:67], v[32:47]
	v_exp_f32_e32 v52, v52
	v_exp_f32_e32 v53, v53
	v_exp_f32_e32 v54, v54
	v_exp_f32_e32 v55, v55
	s_waitcnt lgkmcnt(10)
	v_mfma_f32_32x32x16_bf16 v[16:31], v[128:131], v[68:71], v[16:31]
	v_exp_f32_e32 v56, v56
	v_exp_f32_e32 v57, v57
	v_exp_f32_e32 v58, v58
	v_exp_f32_e32 v59, v59
	s_waitcnt lgkmcnt(8)
	v_mfma_f32_32x32x16_bf16 v[32:47], v[128:131], v[72:75], v[32:47]
	v_exp_f32_e32 v60, v60
	v_exp_f32_e32 v61, v61
	v_exp_f32_e32 v62, v62
	v_exp_f32_e32 v63, v63
	s_waitcnt vmcnt(0) lgkmcnt(0)
	s_barrier
	ds_read_b64_tr_b16 v[112:113], v182 offset:24576
	ds_read_b64_tr_b16 v[114:115], v182 offset:25088
	v_add_f32_e32 v64, v96, v97
	v_add_f32_e32 v64, v98, v64
	v_add_f32_e32 v64, v99, v64
	v_add_f32_e32 v64, v100, v64
	v_add_f32_e32 v84, v101, v64
	v_cvt_pk_bf16_f32 v140, v96, v97
	v_cvt_pk_bf16_f32 v141, v98, v99
	s_waitcnt lgkmcnt(9)
	v_mfma_f32_32x32x16_bf16 v[64:79], v[76:79], v[156:159], 0
	ds_read_b64_tr_b16 v[96:97], v182 offset:28672
	ds_read_b64_tr_b16 v[98:99], v182 offset:29184
	v_add_f32_e32 v84, v102, v84
	v_add_f32_e32 v84, v103, v84
	v_add_f32_e32 v84, v104, v84
	v_add_f32_e32 v121, v105, v84
	v_cvt_pk_bf16_f32 v142, v100, v101
	v_cvt_pk_bf16_f32 v143, v102, v103
	s_waitcnt lgkmcnt(10)
	v_mfma_f32_32x32x16_bf16 v[80:95], v[80:83], v[156:159], 0
	ds_read_b64_tr_b16 v[116:117], v182 offset:25600
	ds_read_b64_tr_b16 v[118:119], v182 offset:26112
	v_add_f32_e32 v100, v106, v121
	v_add_f32_e32 v100, v107, v100
	v_add_f32_e32 v100, v108, v100
	v_add_f32_e32 v121, v109, v100
	v_cvt_pk_bf16_f32 v136, v104, v105
	v_cvt_pk_bf16_f32 v137, v106, v107
	s_waitcnt lgkmcnt(11)
	v_mfma_f32_32x32x16_bf16 v[64:79], v[122:125], v[152:155], v[64:79]
	ds_read_b64_tr_b16 v[100:101], v182 offset:29696
	ds_read_b64_tr_b16 v[102:103], v182 offset:30208
	v_add_f32_e32 v104, v110, v121
	v_add_f32_e32 v104, v111, v104
	v_add_f32_e32 v104, v48, v104
	v_add_f32_e32 v121, v49, v104
	v_cvt_pk_bf16_f32 v138, v108, v109
	v_cvt_pk_bf16_f32 v139, v110, v111
	s_waitcnt lgkmcnt(12)
	v_mfma_f32_32x32x16_bf16 v[80:95], v[160:163], v[152:155], v[80:95]
	ds_read_b64_tr_b16 v[104:105], v182 offset:26624
	ds_read_b64_tr_b16 v[106:107], v182 offset:27136
	v_add_f32_e32 v108, v50, v121
	v_add_f32_e32 v108, v51, v108
	v_add_f32_e32 v108, v52, v108
	v_add_f32_e32 v108, v53, v108
	v_cvt_pk_bf16_f32 v132, v48, v49
	v_cvt_pk_bf16_f32 v133, v50, v51
	s_waitcnt lgkmcnt(13)
	v_mfma_f32_32x32x16_bf16 v[64:79], v[164:167], v[148:151], v[64:79]
	ds_read_b64_tr_b16 v[48:49], v182 offset:30720
	ds_read_b64_tr_b16 v[50:51], v182 offset:31232
	v_add_f32_e32 v108, v54, v108
	v_add_f32_e32 v108, v55, v108
	v_add_f32_e32 v108, v56, v108
	v_add_f32_e32 v121, v57, v108
	v_cvt_pk_bf16_f32 v134, v52, v53
	v_cvt_pk_bf16_f32 v135, v54, v55
	s_waitcnt lgkmcnt(14)
	v_mfma_f32_32x32x16_bf16 v[80:95], v[170:173], v[148:151], v[80:95]
	ds_read_b64_tr_b16 v[108:109], v182 offset:27648
	ds_read_b64_tr_b16 v[110:111], v182 offset:28160
	v_add_f32_e32 v52, v58, v121
	v_add_f32_e32 v52, v59, v52
	v_add_f32_e32 v52, v60, v52
	v_add_f32_e32 v121, v61, v52
	v_cvt_pk_bf16_f32 v128, v56, v57
	v_cvt_pk_bf16_f32 v129, v58, v59
	s_waitcnt lgkmcnt(14)
	v_mfma_f32_32x32x16_bf16 v[64:79], v[184:187], v[144:147], v[64:79]
	ds_read_b64_tr_b16 v[52:53], v182 offset:31744
	ds_read_b64_tr_b16 v[54:55], v182 offset:32256
	v_add_f32_e32 v56, v62, v121
	v_add_f32_e32 v56, v63, v56
	v_add_f32_e32 v56, 0, v56
	v_cvt_pk_bf16_f32 v130, v60, v61
	v_cvt_pk_bf16_f32 v131, v62, v63
	v_mfma_f32_32x32x16_bf16 v[80:95], v[188:191], v[144:147], v[80:95]
	s_nop 3
	v_exp_f32_e32 v64, v64
	v_exp_f32_e32 v65, v65
	v_exp_f32_e32 v66, v66
	v_exp_f32_e32 v67, v67
	s_nop 0
	v_exp_f32_e32 v68, v68
	v_exp_f32_e32 v69, v69
	v_exp_f32_e32 v70, v70
	v_exp_f32_e32 v71, v71
	s_nop 0
	v_exp_f32_e32 v72, v72
	v_exp_f32_e32 v73, v73
	v_exp_f32_e32 v74, v74
	v_exp_f32_e32 v75, v75
	s_nop 0
	v_exp_f32_e32 v76, v76
	v_exp_f32_e32 v77, v77
	v_exp_f32_e32 v78, v78
	v_exp_f32_e32 v79, v79
	v_exp_f32_e32 v80, v80
	v_exp_f32_e32 v81, v81
	v_exp_f32_e32 v82, v82
	v_exp_f32_e32 v83, v83
	s_nop 0
	v_exp_f32_e32 v84, v84
	v_exp_f32_e32 v85, v85
	v_exp_f32_e32 v86, v86
	v_exp_f32_e32 v87, v87
	s_nop 0
	v_exp_f32_e32 v88, v88
	v_exp_f32_e32 v89, v89
	v_exp_f32_e32 v90, v90
	v_exp_f32_e32 v91, v91
	s_nop 0
	v_exp_f32_e32 v92, v92
	v_exp_f32_e32 v93, v93
	v_exp_f32_e32 v94, v94
	v_exp_f32_e32 v95, v95
	s_waitcnt lgkmcnt(14)
; #define SBAR() __builtin_amdgcn_sched_barrier(0)
;   #define RESC() do{ if(!NOMAX&&resc){ asm volatile("s_waitcnt lgkmcnt(0)":::"memory"); \
;       _Pragma("unroll") for(int d_=0;d_<2*VM;++d_) _Pragma("unroll") for(int r=0;r<16;++r)o[d_][r]*=wsf[crow(r,hi)]; } }while(0)
;   #define PKW(P,B) cvtpk_s(P[B],P[B+1])
; __device__ __forceinline__ void pv(f32x16*o,int vb,bf16x8 pa0,bf16x8 pa1,bf16x8 pa2,bf16x8 pa3){
;   #pragma unroll
;   for(int d0=0;d0<2;++d0){s16x4 lo[4],hi[4];
;     #pragma unroll
;     for(int ks=0;ks<4;++ks){
;       asm volatile("ds_read_b64_tr_b16 %0,%1 offset:%c2":"=&v"(lo[ks]):"v"(vb),"i"(d0*4096+ks*1024):"memory");
;       asm volatile("ds_read_b64_tr_b16 %0,%1 offset:%c2":"=&v"(hi[ks]):"v"(vb),"i"(d0*4096+ks*1024+512):"memory");}
;     asm volatile("s_waitcnt lgkmcnt(0)":::"memory");SBAR();
;     ...
;     o[d0]=__builtin_amdgcn_mfma_f32_32x32x16_bf16(pa0,PK(0),o[d0],0,0,0);
;     o[d0]=__builtin_amdgcn_mfma_f32_32x32x16_bf16(pa1,PK(1),o[d0],0,0,0);
;     o[d0]=__builtin_amdgcn_mfma_f32_32x32x16_bf16(pa2,PK(2),o[d0],0,0,0);
;     o[d0]=__builtin_amdgcn_mfma_f32_32x32x16_bf16(pa3,PK(3),o[d0],0,0,0);
;     ...
;   }
; }
; template<int THRL,int VM,bool NOMAX> __device__ __forceinline__ void attn_unit(const bf16*Qb,const bf16*__restrict__ Kh,const bf16*__restrict__ Vh,bf16*Ob,const int NT,const int sp,float*wscr,char*shm){
;     ...
;   STEP(pB0,pB1,pA0,pA1,NT-1,false,false,false); RESC();
;   { float sacc=pB0[0]+pB0[1]; _Pragma("unroll") for(int r=2;r<16;++r)sacc+=pB0[r]; _Pragma("unroll") for(int r=0;r<16;++r)sacc+=pB1[r]; l_reg+=sacc;
;     pw0=(u32x4){PKW(pB0,0),PKW(pB0,2),PKW(pB0,4),PKW(pB0,6)};pw1=(u32x4){PKW(pB0,8),PKW(pB0,10),PKW(pB0,12),PKW(pB0,14)};pw2=(u32x4){PKW(pB1,0),PKW(pB1,2),PKW(pB1,4),PKW(pB1,6)};pw3=(u32x4){PKW(pB1,8),PKW(pB1,10),PKW(pB1,12),PKW(pB1,14)};
;     SBAR(); pv(o,vb0+VM*sl_cur,PAF(0),PAF(1),PAF(2),PAF(3)); if constexpr(VM==2) pv(o+2,vb0+VM*sl_cur+8192,PAF(0),PAF(1),PAF(2),PAF(3)); }
;     ...
;   {auto rr=__builtin_amdgcn_permlane32_swap(__float_as_uint(l_reg),__float_as_uint(l_reg),false,false);l_reg=__uint_as_float(rr[0])+__uint_as_float(rr[1]);}
;   if(hi==0)wsf[32+r32]=l_reg;asm volatile("s_waitcnt lgkmcnt(0)":::"memory");
	v_mfma_f32_32x32x16_bf16 v[16:31], v[140:143], v[112:115], v[16:31]
	v_add_f32_e32 v57, v64, v65
	v_add_f32_e32 v57, v66, v57
	v_add_f32_e32 v57, v67, v57
	v_add_f32_e32 v57, v68, v57
	v_add_f32_e32 v57, v69, v57
	v_add_f32_e32 v57, v70, v57
	v_add_f32_e32 v57, v71, v57
	s_waitcnt lgkmcnt(12)
	v_mfma_f32_32x32x16_bf16 v[32:47], v[140:143], v[96:99], v[32:47]
	v_add_f32_e32 v57, v72, v57
	v_add_f32_e32 v57, v73, v57
	v_add_f32_e32 v57, v74, v57
	v_add_f32_e32 v57, v75, v57
	v_add_f32_e32 v57, v76, v57
	v_add_f32_e32 v57, v77, v57
	v_add_f32_e32 v57, v78, v57
	s_waitcnt lgkmcnt(10)
	v_mfma_f32_32x32x16_bf16 v[16:31], v[136:139], v[116:119], v[16:31]
	v_add_f32_e32 v57, v79, v57
	v_add_f32_e32 v57, v80, v57
	v_add_f32_e32 v57, v81, v57
	v_add_f32_e32 v57, v82, v57
	v_add_f32_e32 v57, v83, v57
	v_add_f32_e32 v57, v84, v57
	v_add_f32_e32 v57, v85, v57
	s_waitcnt lgkmcnt(8)
	v_mfma_f32_32x32x16_bf16 v[32:47], v[136:139], v[100:103], v[32:47]
	v_add_f32_e32 v57, v86, v57
	v_add_f32_e32 v57, v87, v57
	v_add_f32_e32 v57, v88, v57
	v_add_f32_e32 v57, v89, v57
	v_add_f32_e32 v57, v90, v57
	v_add_f32_e32 v57, v91, v57
	v_add_f32_e32 v57, v92, v57
	s_waitcnt lgkmcnt(6)
	v_mfma_f32_32x32x16_bf16 v[16:31], v[132:135], v[104:107], v[16:31]
	v_add_f32_e32 v57, v93, v57
	v_add_f32_e32 v57, v94, v57
	v_add_f32_e32 v57, v95, v57
	v_add_f32_e32 v56, v120, v56
	v_add_f32_e32 v56, v56, v57
	v_cvt_pk_bf16_f32 v58, v64, v65
	v_cvt_pk_bf16_f32 v59, v66, v67
	s_waitcnt lgkmcnt(4)
	v_mfma_f32_32x32x16_bf16 v[32:47], v[132:135], v[48:51], v[32:47]
	v_cvt_pk_bf16_f32 v48, v80, v81
	v_cvt_pk_bf16_f32 v60, v68, v69
	v_cvt_pk_bf16_f32 v61, v70, v71
	v_cvt_pk_bf16_f32 v62, v72, v73
	v_cvt_pk_bf16_f32 v63, v74, v75
	v_cvt_pk_bf16_f32 v64, v76, v77
	v_cvt_pk_bf16_f32 v65, v78, v79
	s_waitcnt lgkmcnt(2)
	v_mfma_f32_32x32x16_bf16 v[16:31], v[128:131], v[108:111], v[16:31]
	v_cvt_pk_bf16_f32 v49, v82, v83
	v_cvt_pk_bf16_f32 v50, v84, v85
	v_cvt_pk_bf16_f32 v51, v86, v87
	v_cvt_pk_bf16_f32 v66, v88, v89
	v_cvt_pk_bf16_f32 v67, v90, v91
	v_cvt_pk_bf16_f32 v68, v92, v93
	v_cvt_pk_bf16_f32 v69, v94, v95
	s_waitcnt lgkmcnt(0)
	v_mfma_f32_32x32x16_bf16 v[32:47], v[128:131], v[52:55], v[32:47]
	v_add3_u32 v57, v174, v168, s18
	ds_read_b64_tr_b16 v[52:53],v57 offset:0
	ds_read_b64_tr_b16 v[54:55],v57 offset:512
	ds_read_b64_tr_b16 v[70:71],v57 offset:1024
	ds_read_b64_tr_b16 v[72:73],v57 offset:1536
	ds_read_b64_tr_b16 v[74:75],v57 offset:2048
	ds_read_b64_tr_b16 v[76:77],v57 offset:2560
	ds_read_b64_tr_b16 v[78:79],v57 offset:3072
	ds_read_b64_tr_b16 v[80:81],v57 offset:3584
	s_waitcnt lgkmcnt(0)
	s_nop 0
	v_mfma_f32_32x32x16_bf16 v[16:31], v[58:61], v[52:55], v[16:31]
	ds_read_b64_tr_b16 v[52:53],v57 offset:4096
	ds_read_b64_tr_b16 v[54:55],v57 offset:4608
	v_mfma_f32_32x32x16_bf16 v[16:31], v[62:65], v[70:73], v[16:31]
	ds_read_b64_tr_b16 v[70:71],v57 offset:5120
	ds_read_b64_tr_b16 v[72:73],v57 offset:5632
	v_mfma_f32_32x32x16_bf16 v[16:31], v[48:51], v[74:77], v[16:31]
	ds_read_b64_tr_b16 v[74:75],v57 offset:6144
	ds_read_b64_tr_b16 v[76:77],v57 offset:6656
	ds_read_b64_tr_b16 v[82:83],v57 offset:7168
	ds_read_b64_tr_b16 v[84:85],v57 offset:7680
	s_waitcnt lgkmcnt(0)
	v_mfma_f32_32x32x16_bf16 v[16:31], v[66:69], v[78:81], v[16:31]
	v_mfma_f32_32x32x16_bf16 v[32:47], v[58:61], v[52:55], v[32:47]
	v_cmp_gt_u32_e32 vcc, 32, v178
	v_mfma_f32_32x32x16_bf16 v[32:47], v[62:65], v[70:73], v[32:47]
	v_mfma_f32_32x32x16_bf16 v[32:47], v[48:51], v[74:77], v[32:47]
	v_mov_b32_e32 v48, v56
	s_nop 1
	v_permlane32_swap_b32_e32 v56, v48
	v_mfma_f32_32x32x16_bf16 v[32:47], v[66:69], v[82:85], v[32:47]
	s_and_saveexec_b64 s[16:17], vcc
	s_cbranch_execz .LBB0_878
	v_add_f32_e32 v48, v56, v48
	v_lshl_add_u32 v49, v180, 2, s29
	ds_write_b32 v49, v48 offset:49280
	s_branch .LBB0_878

; __device__ __forceinline__ void glds16(const void*gsrc,unsigned lds_dst){unsigned keep;
;   asm volatile("s_mov_b32 %0, m0\n\ts_mov_b32 m0, %2\n\ts_nop 0\n\tglobal_load_lds_dwordx4 %1, off\n\ts_mov_b32 m0, %0":"=&s"(keep):"v"(gsrc),"s"(lds_dst):"memory");}
.LBB0_891:
	v_add_u32_e32 v187, s52, v168
	ds_read_b64_tr_b16 v[188:189], v187 offset:24576
	ds_read_b64_tr_b16 v[190:191], v187 offset:25088
	v_add_f32_e32 v88, v64, v65
	v_add_f32_e32 v88, v66, v88
	v_add_f32_e32 v88, v67, v88
	v_add_f32_e32 v88, v68, v88
	v_add_f32_e32 v88, v69, v88
	v_cvt_pk_bf16_f32 v140, v64, v65
	v_cvt_pk_bf16_f32 v141, v66, v67
	v_mfma_f32_32x32x16_bf16 v[96:111], v[84:87], v[156:159], 0
	ds_read_b64_tr_b16 v[64:65], v187 offset:28672
	ds_read_b64_tr_b16 v[66:67], v187 offset:29184
	v_add_f32_e32 v84, v70, v88
	v_add_f32_e32 v84, v71, v84
	v_add_f32_e32 v84, v72, v84
	v_add_f32_e32 v128, v73, v84
	v_mfma_f32_32x32x16_bf16 v[80:95], v[80:83], v[156:159], 0
	v_cvt_pk_bf16_f32 v142, v68, v69
	v_cvt_pk_bf16_f32 v143, v70, v71
	ds_read_b64_tr_b16 v[68:69], v187 offset:25600
	ds_read_b64_tr_b16 v[70:71], v187 offset:26112
	v_add_f32_e32 v128, v74, v128
	v_add_f32_e32 v128, v75, v128
	v_add_f32_e32 v128, v76, v128
	v_add_f32_e32 v128, v77, v128
	v_cvt_pk_bf16_f32 v136, v72, v73
	v_cvt_pk_bf16_f32 v137, v74, v75
	v_mfma_f32_32x32x16_bf16 v[96:111], v[164:167], v[152:155], v[96:111]
	ds_read_b64_tr_b16 v[72:73], v187 offset:29696
	ds_read_b64_tr_b16 v[74:75], v187 offset:30208
	v_mfma_f32_32x32x16_bf16 v[80:95], v[160:163], v[152:155], v[80:95]
	v_add_f32_e32 v128, v78, v128
	v_add_f32_e32 v128, v79, v128
	v_add_f32_e32 v128, v48, v128
	v_add_f32_e32 v128, v49, v128
	v_cvt_pk_bf16_f32 v138, v76, v77
	v_cvt_pk_bf16_f32 v139, v78, v79
	ds_read_b64_tr_b16 v[76:77], v187 offset:26624
	ds_read_b64_tr_b16 v[78:79], v187 offset:27136
	v_add_f32_e32 v128, v50, v128
	v_add_f32_e32 v128, v51, v128
	v_add_f32_e32 v128, v52, v128
	v_add_f32_e32 v128, v53, v128
	v_cvt_pk_bf16_f32 v132, v48, v49
	v_cvt_pk_bf16_f32 v133, v50, v51
	v_mfma_f32_32x32x16_bf16 v[96:111], v[124:127], v[148:151], v[96:111]
	ds_read_b64_tr_b16 v[48:49], v187 offset:30720
	ds_read_b64_tr_b16 v[50:51], v187 offset:31232
	v_mfma_f32_32x32x16_bf16 v[80:95], v[120:123], v[148:151], v[80:95]
	v_add_f32_e32 v124, v54, v128
	v_add_f32_e32 v124, v55, v124
	v_add_f32_e32 v124, v56, v124
	v_add_f32_e32 v124, v57, v124
	v_cvt_pk_bf16_f32 v134, v52, v53
	v_cvt_pk_bf16_f32 v135, v54, v55
	ds_read_b64_tr_b16 v[52:53], v187 offset:27648
	ds_read_b64_tr_b16 v[54:55], v187 offset:28160
	v_add_f32_e32 v120, v58, v124
	v_add_f32_e32 v120, v59, v120
	v_add_f32_e32 v120, v60, v120
	v_add_f32_e32 v120, v61, v120
	v_cvt_pk_bf16_f32 v128, v56, v57
	v_cvt_pk_bf16_f32 v129, v58, v59
	v_mfma_f32_32x32x16_bf16 v[96:111], v[116:119], v[144:147], v[96:111]
	ds_read_b64_tr_b16 v[56:57], v187 offset:31744
	ds_read_b64_tr_b16 v[58:59], v187 offset:32256
	v_mfma_f32_32x32x16_bf16 v[80:95], v[112:115], v[144:147], v[80:95]
	v_add_f32_e32 v116, v62, v120
	v_add_f32_e32 v116, v63, v116
	v_cvt_pk_bf16_f32 v130, v60, v61
	v_cvt_pk_bf16_f32 v131, v62, v63
	s_add_i32 m0, s34, s17
	v_lshl_add_u64 v[60:61], v[176:177], 0, s[38:39]
	global_load_lds_dwordx4 v[60:61], off
	s_add_i32 m0, s33, s16
	v_lshl_add_u64 v[60:61], v[174:175], 0, s[38:39]
	global_load_lds_dwordx4 v[60:61], off
	v_add_f32_e32 v202, v186, v116
	s_waitcnt lgkmcnt(12)
	v_mfma_f32_32x32x16_bf16 v[16:31], v[140:143], v[188:191], v[16:31]
	v_exp_f32_e32 v96, v96
	v_exp_f32_e32 v97, v97
	v_exp_f32_e32 v98, v98
	v_exp_f32_e32 v99, v99
	v_mfma_f32_32x32x16_bf16 v[32:47], v[140:143], v[64:67], v[32:47]
	v_exp_f32_e32 v100, v100
	v_exp_f32_e32 v101, v101
	v_exp_f32_e32 v102, v102
	v_exp_f32_e32 v103, v103
	v_add_u32_e32 v64, s33, v182
	ds_read_b128 v[60:63], v64
	ds_read_b128 v[112:115], v64 offset:512
	s_waitcnt lgkmcnt(10)
	v_mfma_f32_32x32x16_bf16 v[16:31], v[136:139], v[68:71], v[16:31]
	v_exp_f32_e32 v104, v104
	v_exp_f32_e32 v105, v105
	v_exp_f32_e32 v106, v106
	v_exp_f32_e32 v107, v107
	ds_read_b128 v[116:119], v64 offset:2048
	ds_read_b128 v[120:123], v64 offset:2560
	v_mfma_f32_32x32x16_bf16 v[32:47], v[136:139], v[72:75], v[32:47]
	v_exp_f32_e32 v108, v108
	v_exp_f32_e32 v109, v109
	v_exp_f32_e32 v110, v110
	v_exp_f32_e32 v111, v111
	ds_read_b128 v[124:127], v64 offset:4096
	ds_read_b128 v[160:163], v64 offset:4608
	s_waitcnt lgkmcnt(10)
	v_mfma_f32_32x32x16_bf16 v[16:31], v[132:135], v[76:79], v[16:31]
	v_exp_f32_e32 v80, v80
	v_exp_f32_e32 v81, v81
	v_exp_f32_e32 v82, v82
	v_exp_f32_e32 v83, v83
	ds_read_b128 v[164:167], v64 offset:6144
	ds_read_b128 v[186:189], v64 offset:6656
	v_mfma_f32_32x32x16_bf16 v[32:47], v[132:135], v[48:51], v[32:47]
	v_exp_f32_e32 v84, v84
	v_exp_f32_e32 v85, v85
	v_exp_f32_e32 v86, v86
	v_exp_f32_e32 v87, v87
	s_waitcnt lgkmcnt(8)
	v_mfma_f32_32x32x16_bf16 v[16:31], v[128:131], v[52:55], v[16:31]
	v_exp_f32_e32 v88, v88
	v_exp_f32_e32 v89, v89
	v_exp_f32_e32 v90, v90
	v_exp_f32_e32 v91, v91
	v_mfma_f32_32x32x16_bf16 v[32:47], v[128:131], v[56:59], v[32:47]
	v_exp_f32_e32 v92, v92
	v_exp_f32_e32 v93, v93
	v_exp_f32_e32 v94, v94
	v_exp_f32_e32 v95, v95
	s_waitcnt vmcnt(2) lgkmcnt(0)
	s_barrier
; #define WAIT_BAR(N) asm volatile("s_waitcnt vmcnt(" #N ") lgkmcnt(0)\n\ts_barrier":::"memory")
;   #define RESC() do{ if(!NOMAX&&resc){ asm volatile("s_waitcnt lgkmcnt(0)":::"memory"); \
;       _Pragma("unroll") for(int d_=0;d_<2*VM;++d_) _Pragma("unroll") for(int r=0;r<16;++r)o[d_][r]*=wsf[crow(r,hi)]; } }while(0)
;   #define ROT() do{sl_prev=sl_cur;sl_cur=sl_next;sl_next=(sl_next==(NSLOT-1)*SLOTB)?0:sl_next+SLOTB;}while(0)
; __device__ __forceinline__ void glds16(const void*gsrc,unsigned lds_dst){unsigned keep;
;   asm volatile("s_mov_b32 %0, m0\n\ts_mov_b32 m0, %2\n\ts_nop 0\n\tglobal_load_lds_dwordx4 %1, off\n\ts_mov_b32 m0, %0":"=&s"(keep):"v"(gsrc),"s"(lds_dst):"memory");}
; template<int THRL,int VM,bool NOMAX> __device__ __forceinline__ void attn_unit(const bf16*Qb,const bf16*__restrict__ Kh,const bf16*__restrict__ Vh,bf16*Ob,const int NT,const int sp,float*wscr,char*shm){
;     ...
;   int t=1;
;   for(;t+5<NT;t+=2){
;     STEP(pB0,pB1,pA0,pA1,t,true,true,true);     if constexpr(VM==2){WAIT_BAR(3);}else{WAIT_BAR(2);} RESC(); ROT();
;     STEP(pA0,pA1,pB0,pB1,t+1,true,true,true);   if constexpr(VM==2){WAIT_BAR(3);}else{WAIT_BAR(2);} RESC(); ROT();
	s_add_i32 s35, s33, 0x2000
	s_cmpk_lg_i32 s33, 0x4000
	s_cselect_b32 s35, s35, 0
	v_add_u32_e32 v203, s34, v168
	ds_read_b64_tr_b16 v[190:191], v203 offset:24576
	ds_read_b64_tr_b16 v[192:193], v203 offset:25088
	v_mfma_f32_32x32x16_bf16 v[64:79], v[60:63], v[156:159], 0
	v_add_f32_e32 v48, v96, v97
	v_add_f32_e32 v48, v98, v48
	v_add_f32_e32 v48, v99, v48
	v_add_f32_e32 v48, v100, v48
	v_add_f32_e32 v48, v101, v48
	v_cvt_pk_bf16_f32 v140, v96, v97
	v_cvt_pk_bf16_f32 v141, v98, v99
	ds_read_b64_tr_b16 v[96:97], v203 offset:28672
	ds_read_b64_tr_b16 v[98:99], v203 offset:29184
	v_add_f32_e32 v48, v102, v48
	v_add_f32_e32 v48, v103, v48
	v_add_f32_e32 v48, v104, v48
	v_add_f32_e32 v128, v105, v48
	v_mfma_f32_32x32x16_bf16 v[48:63], v[112:115], v[156:159], 0
	v_cvt_pk_bf16_f32 v142, v100, v101
	v_cvt_pk_bf16_f32 v143, v102, v103
	ds_read_b64_tr_b16 v[100:101], v203 offset:25600
	ds_read_b64_tr_b16 v[102:103], v203 offset:26112
	v_mfma_f32_32x32x16_bf16 v[64:79], v[116:119], v[152:155], v[64:79]
	v_add_f32_e32 v112, v106, v128
	v_add_f32_e32 v112, v107, v112
	v_add_f32_e32 v112, v108, v112
	v_add_f32_e32 v112, v109, v112
	v_cvt_pk_bf16_f32 v136, v104, v105
	v_cvt_pk_bf16_f32 v137, v106, v107
	ds_read_b64_tr_b16 v[104:105], v203 offset:29696
	ds_read_b64_tr_b16 v[106:107], v203 offset:30208
	v_mfma_f32_32x32x16_bf16 v[48:63], v[120:123], v[152:155], v[48:63]
	v_add_f32_e32 v112, v110, v112
	v_add_f32_e32 v112, v111, v112
	v_add_f32_e32 v112, v80, v112
	v_add_f32_e32 v112, v81, v112
	v_cvt_pk_bf16_f32 v138, v108, v109
	v_cvt_pk_bf16_f32 v139, v110, v111
	ds_read_b64_tr_b16 v[108:109], v203 offset:26624
	ds_read_b64_tr_b16 v[110:111], v203 offset:27136
	v_mfma_f32_32x32x16_bf16 v[64:79], v[124:127], v[148:151], v[64:79]
	v_add_f32_e32 v112, v82, v112
	v_add_f32_e32 v112, v83, v112
	v_add_f32_e32 v112, v84, v112
	v_add_f32_e32 v112, v85, v112
	v_cvt_pk_bf16_f32 v132, v80, v81
	v_cvt_pk_bf16_f32 v133, v82, v83
	ds_read_b64_tr_b16 v[194:195], v203 offset:30720
	ds_read_b64_tr_b16 v[196:197], v203 offset:31232
	v_mfma_f32_32x32x16_bf16 v[48:63], v[160:163], v[148:151], v[48:63]
	v_add_f32_e32 v80, v86, v112
	v_add_f32_e32 v80, v87, v80
	v_add_f32_e32 v80, v88, v80
	v_add_f32_e32 v80, v89, v80
	v_cvt_pk_bf16_f32 v134, v84, v85
	v_cvt_pk_bf16_f32 v135, v86, v87
	ds_read_b64_tr_b16 v[198:199], v203 offset:27648
	ds_read_b64_tr_b16 v[200:201], v203 offset:28160
	v_mfma_f32_32x32x16_bf16 v[64:79], v[164:167], v[144:147], v[64:79]
	v_add_f32_e32 v80, v90, v80
	v_add_f32_e32 v80, v91, v80
	v_add_f32_e32 v80, v92, v80
	v_add_f32_e32 v80, v93, v80
	v_cvt_pk_bf16_f32 v128, v88, v89
	v_cvt_pk_bf16_f32 v129, v90, v91
	ds_read_b64_tr_b16 v[88:89], v203 offset:31744
	ds_read_b64_tr_b16 v[90:91], v203 offset:32256
	v_mfma_f32_32x32x16_bf16 v[48:63], v[186:189], v[144:147], v[48:63]
	v_add_f32_e32 v80, v94, v80
	v_add_f32_e32 v80, v95, v80
	v_cvt_pk_bf16_f32 v130, v92, v93
	v_cvt_pk_bf16_f32 v131, v94, v95
	s_add_i32 m0, s33, s17
	s_nop 0
	global_load_lds_dwordx4 v[176:177], off
	s_add_i32 m0, s35, s16
	s_nop 0
	global_load_lds_dwordx4 v[174:175], off
	v_add_f32_e32 v186, v202, v80
	s_waitcnt lgkmcnt(12)
	v_mfma_f32_32x32x16_bf16 v[16:31], v[140:143], v[190:193], v[16:31]
	v_exp_f32_e32 v64, v64
	v_exp_f32_e32 v65, v65
	v_exp_f32_e32 v66, v66
	v_exp_f32_e32 v67, v67
	v_mfma_f32_32x32x16_bf16 v[32:47], v[140:143], v[96:99], v[32:47]
	v_exp_f32_e32 v68, v68
	v_exp_f32_e32 v69, v69
	v_exp_f32_e32 v70, v70
	v_exp_f32_e32 v71, v71
	v_add_u32_e32 v92, s35, v182
	ds_read_b128 v[84:87], v92
	ds_read_b128 v[80:83], v92 offset:512
	s_waitcnt lgkmcnt(10)
	v_mfma_f32_32x32x16_bf16 v[16:31], v[136:139], v[100:103], v[16:31]
	v_exp_f32_e32 v72, v72
	v_exp_f32_e32 v73, v73
	v_exp_f32_e32 v74, v74
	v_exp_f32_e32 v75, v75
	ds_read_b128 v[164:167], v92 offset:2048
	ds_read_b128 v[160:163], v92 offset:2560
	v_mfma_f32_32x32x16_bf16 v[32:47], v[136:139], v[104:107], v[32:47]
	v_exp_f32_e32 v76, v76
	v_exp_f32_e32 v77, v77
	v_exp_f32_e32 v78, v78
	v_exp_f32_e32 v79, v79
	ds_read_b128 v[124:127], v92 offset:4096
	ds_read_b128 v[120:123], v92 offset:4608
	s_waitcnt lgkmcnt(10)
	v_mfma_f32_32x32x16_bf16 v[16:31], v[132:135], v[108:111], v[16:31]
	v_exp_f32_e32 v48, v48
	v_exp_f32_e32 v49, v49
	v_exp_f32_e32 v50, v50
	v_exp_f32_e32 v51, v51
	ds_read_b128 v[116:119], v92 offset:6144
	ds_read_b128 v[112:115], v92 offset:6656
	v_mfma_f32_32x32x16_bf16 v[32:47], v[132:135], v[194:197], v[32:47]
	v_exp_f32_e32 v52, v52
	v_exp_f32_e32 v53, v53
	v_exp_f32_e32 v54, v54
	v_exp_f32_e32 v55, v55
	s_waitcnt lgkmcnt(8)
	v_mfma_f32_32x32x16_bf16 v[16:31], v[128:131], v[198:201], v[16:31]
	v_exp_f32_e32 v56, v56
	v_exp_f32_e32 v57, v57
	v_exp_f32_e32 v58, v58
	v_exp_f32_e32 v59, v59
	v_mfma_f32_32x32x16_bf16 v[32:47], v[128:131], v[88:91], v[32:47]
	v_exp_f32_e32 v60, v60
	v_exp_f32_e32 v61, v61
	v_exp_f32_e32 v62, v62
	v_exp_f32_e32 v63, v63
	s_add_i32 s53, s35, 0x2000
	s_waitcnt vmcnt(2) lgkmcnt(0)
	s_barrier
	s_cmpk_lg_i32 s35, 0x4000
	s_mov_b32 s52, s33
	s_cselect_b32 s33, s53, 0
	s_add_i32 s29, s29, 2
	v_lshl_add_u64 v[174:175], v[174:175], 0, s[8:9]
	v_lshl_add_u64 v[176:177], v[176:177], 0, s[8:9]
	s_mov_b32 s34, s35
	s_cmp_lt_u32 s29, 57
	s_cbranch_scc1 .LBB0_891
;   #define RESC() do{ if(!NOMAX&&resc){ asm volatile("s_waitcnt lgkmcnt(0)":::"memory"); \
;       _Pragma("unroll") for(int d_=0;d_<2*VM;++d_) _Pragma("unroll") for(int r=0;r<16;++r)o[d_][r]*=wsf[crow(r,hi)]; } }while(0)
;   #define ROT() do{sl_prev=sl_cur;sl_cur=sl_next;sl_next=(sl_next==(NSLOT-1)*SLOTB)?0:sl_next+SLOTB;}while(0)
;   #define ENDW(tt) do{ if((tt)+3<NT){ if constexpr(VM==2){WAIT_BAR(3);}else{WAIT_BAR(2);} } else if((tt)+2<NT){ if constexpr(VM==2){WAIT_BAR(2);}else{WAIT_BAR(1);} } else {WAIT_BAR(0);} }while(0)
; template<int THRL,int VM,bool NOMAX> __device__ __forceinline__ void attn_unit(const bf16*Qb,const bf16*__restrict__ Kh,const bf16*__restrict__ Vh,bf16*Ob,const int NT,const int sp,float*wscr,char*shm){
;     ...
;   for(;t+1<NT;t+=2){
;     STEP(pB0,pB1,pA0,pA1,t,(t+3<NT),(t+1<NT),(t+1<NT));       ENDW(t);   RESC(); ROT();
;     STEP(pA0,pA1,pB0,pB1,t+1,(t+4<NT),(t+2<NT),(t+2<NT));     ENDW(t+1); RESC(); ROT();
	s_and_b32 s19, s19, 0x3fffffc0
	s_lshl_b32 s19, s19, 2
	s_add_i32 s19, s19, 0
	s_cmp_lg_u32 0, -1
	s_cselect_b32 s29, 0, 0
	s_add_i32 s33, s29, 0x6000
	v_add_u32_e32 v88, s33, v184
	v_add3_u32 v174, v88, v183, v185
	ds_read_b64_tr_b16 v[188:189], v168 offset:32768
	ds_read_b64_tr_b16 v[190:191], v168 offset:33280
	v_add_f32_e32 v88, v64, v65
	v_add_f32_e32 v88, v66, v88
	v_add_f32_e32 v88, v67, v88
	v_add_f32_e32 v88, v68, v88
	v_add_f32_e32 v88, v69, v88
	v_cvt_pk_bf16_f32 v140, v64, v65
	v_cvt_pk_bf16_f32 v141, v66, v67
	s_waitcnt lgkmcnt(9)
	v_mfma_f32_32x32x16_bf16 v[96:111], v[84:87], v[156:159], 0
	ds_read_b64_tr_b16 v[64:65], v168 offset:36864
	ds_read_b64_tr_b16 v[66:67], v168 offset:37376
	v_add_f32_e32 v84, v70, v88
	v_add_f32_e32 v84, v71, v84
	v_add_f32_e32 v84, v72, v84
	v_add_f32_e32 v128, v73, v84
	v_cvt_pk_bf16_f32 v142, v68, v69
	v_cvt_pk_bf16_f32 v143, v70, v71
	s_waitcnt lgkmcnt(10)
	v_mfma_f32_32x32x16_bf16 v[80:95], v[80:83], v[156:159], 0
	ds_read_b64_tr_b16 v[68:69], v168 offset:33792
	ds_read_b64_tr_b16 v[70:71], v168 offset:34304
	v_add_f32_e32 v128, v74, v128
	v_add_f32_e32 v128, v75, v128
	v_add_f32_e32 v128, v76, v128
	v_add_f32_e32 v128, v77, v128
	v_cvt_pk_bf16_f32 v136, v72, v73
	v_cvt_pk_bf16_f32 v137, v74, v75
	s_waitcnt lgkmcnt(11)
	v_mfma_f32_32x32x16_bf16 v[96:111], v[164:167], v[152:155], v[96:111]
	ds_read_b64_tr_b16 v[72:73], v168 offset:37888
	ds_read_b64_tr_b16 v[74:75], v168 offset:38400
	v_add_f32_e32 v128, v78, v128
	v_add_f32_e32 v128, v79, v128
	v_add_f32_e32 v128, v48, v128
	v_add_f32_e32 v128, v49, v128
	v_cvt_pk_bf16_f32 v138, v76, v77
	v_cvt_pk_bf16_f32 v139, v78, v79
	s_waitcnt lgkmcnt(12)
	v_mfma_f32_32x32x16_bf16 v[80:95], v[160:163], v[152:155], v[80:95]
	ds_read_b64_tr_b16 v[76:77], v168 offset:34816
	ds_read_b64_tr_b16 v[78:79], v168 offset:35328
	v_add_f32_e32 v128, v50, v128
	v_add_f32_e32 v128, v51, v128
	v_add_f32_e32 v128, v52, v128
	v_add_f32_e32 v128, v53, v128
	v_cvt_pk_bf16_f32 v132, v48, v49
	v_cvt_pk_bf16_f32 v133, v50, v51
	s_waitcnt lgkmcnt(13)
	v_mfma_f32_32x32x16_bf16 v[96:111], v[124:127], v[148:151], v[96:111]
	ds_read_b64_tr_b16 v[48:49], v168 offset:38912
	ds_read_b64_tr_b16 v[50:51], v168 offset:39424
	v_add_f32_e32 v124, v54, v128
	v_add_f32_e32 v124, v55, v124
	v_add_f32_e32 v124, v56, v124
	v_add_f32_e32 v124, v57, v124
	v_cvt_pk_bf16_f32 v134, v52, v53
	v_cvt_pk_bf16_f32 v135, v54, v55
	s_waitcnt lgkmcnt(14)
	v_mfma_f32_32x32x16_bf16 v[80:95], v[120:123], v[148:151], v[80:95]
	ds_read_b64_tr_b16 v[52:53], v168 offset:35840
	ds_read_b64_tr_b16 v[54:55], v168 offset:36352
	v_add_f32_e32 v120, v58, v124
	v_add_f32_e32 v120, v59, v120
	v_add_f32_e32 v120, v60, v120
	v_add_f32_e32 v120, v61, v120
	v_cvt_pk_bf16_f32 v128, v56, v57
	v_cvt_pk_bf16_f32 v129, v58, v59
	s_waitcnt lgkmcnt(14)
	v_mfma_f32_32x32x16_bf16 v[96:111], v[116:119], v[144:147], v[96:111]
	ds_read_b64_tr_b16 v[56:57], v168 offset:39936
	ds_read_b64_tr_b16 v[58:59], v168 offset:40448
	v_add_f32_e32 v116, v62, v120
	v_add_f32_e32 v116, v63, v116
	v_add_f32_e32 v116, 0, v116
	v_cvt_pk_bf16_f32 v130, v60, v61
	v_cvt_pk_bf16_f32 v131, v62, v63
	v_mfma_f32_32x32x16_bf16 v[80:95], v[112:115], v[144:147], v[80:95]
	s_add_i32 s28, s29, s28
	v_lshl_add_u64 v[60:61], v[172:173], 0, s[40:41]
	s_add_i32 s29, s28, 0x4000
	s_mov_b32 s33, m0
	s_mov_b32 m0, s29
	s_nop 0
	global_load_lds_dwordx4 v[60:61], off
	s_mov_b32 m0, s33
	v_lshl_add_u64 v[60:61], v[170:171], 0, s[42:43]
	s_mov_b32 s29, m0
	s_mov_b32 m0, s16
	s_nop 0
	global_load_lds_dwordx4 v[60:61], off
	s_mov_b32 m0, s29
	v_add_f32_e32 v175, v186, v116
	s_waitcnt lgkmcnt(14)
	v_mfma_f32_32x32x16_bf16 v[16:31], v[140:143], v[188:191], v[16:31]
	v_exp_f32_e32 v96, v96
	v_exp_f32_e32 v97, v97
	v_exp_f32_e32 v98, v98
	v_exp_f32_e32 v99, v99
	s_waitcnt lgkmcnt(12)
	v_mfma_f32_32x32x16_bf16 v[32:47], v[140:143], v[64:67], v[32:47]
	v_exp_f32_e32 v100, v100
	v_exp_f32_e32 v101, v101
	v_exp_f32_e32 v102, v102
	v_exp_f32_e32 v103, v103
	ds_read_b128 v[60:63], v182
	ds_read_b128 v[64:67], v182 offset:512
	s_waitcnt lgkmcnt(12)
	v_mfma_f32_32x32x16_bf16 v[16:31], v[136:139], v[68:71], v[16:31]
	v_exp_f32_e32 v104, v104
	v_exp_f32_e32 v105, v105
	v_exp_f32_e32 v106, v106
	v_exp_f32_e32 v107, v107
	ds_read_b128 v[68:71], v182 offset:2048
	ds_read_b128 v[160:163], v182 offset:2560
	s_waitcnt lgkmcnt(12)
	v_mfma_f32_32x32x16_bf16 v[32:47], v[136:139], v[72:75], v[32:47]
	v_exp_f32_e32 v108, v108
	v_exp_f32_e32 v109, v109
	v_exp_f32_e32 v110, v110
	v_exp_f32_e32 v111, v111
	ds_read_b128 v[72:75], v182 offset:4096
	ds_read_b128 v[164:167], v182 offset:4608
	s_waitcnt lgkmcnt(12)
	v_mfma_f32_32x32x16_bf16 v[16:31], v[132:135], v[76:79], v[16:31]
	v_exp_f32_e32 v80, v80
	v_exp_f32_e32 v81, v81
	v_exp_f32_e32 v82, v82
	v_exp_f32_e32 v83, v83
	ds_read_b128 v[76:79], v182 offset:6144
	ds_read_b128 v[184:187], v182 offset:6656
	s_waitcnt lgkmcnt(12)
	v_mfma_f32_32x32x16_bf16 v[32:47], v[132:135], v[48:51], v[32:47]
	v_exp_f32_e32 v84, v84
	v_exp_f32_e32 v85, v85
	v_exp_f32_e32 v86, v86
	v_exp_f32_e32 v87, v87
	s_waitcnt lgkmcnt(10)
	v_mfma_f32_32x32x16_bf16 v[16:31], v[128:131], v[52:55], v[16:31]
	v_exp_f32_e32 v88, v88
	v_exp_f32_e32 v89, v89
	v_exp_f32_e32 v90, v90
	v_exp_f32_e32 v91, v91
	s_waitcnt lgkmcnt(8)
	v_mfma_f32_32x32x16_bf16 v[32:47], v[128:131], v[56:59], v[32:47]
	v_exp_f32_e32 v92, v92
	v_exp_f32_e32 v93, v93
	v_exp_f32_e32 v94, v94
	v_exp_f32_e32 v95, v95
	s_waitcnt vmcnt(2) lgkmcnt(0)
	s_barrier
	ds_read_b64_tr_b16 v[188:189], v168 offset:40960
	ds_read_b64_tr_b16 v[190:191], v168 offset:41472
	v_add_f32_e32 v48, v96, v97
	v_add_f32_e32 v48, v98, v48
	v_add_f32_e32 v48, v99, v48
	v_add_f32_e32 v48, v100, v48
	v_add_f32_e32 v48, v101, v48
	v_cvt_pk_bf16_f32 v140, v96, v97
	v_cvt_pk_bf16_f32 v141, v98, v99
	s_waitcnt lgkmcnt(9)
	v_mfma_f32_32x32x16_bf16 v[112:127], v[60:63], v[156:159], 0
	ds_read_b64_tr_b16 v[96:97], v168 offset:45056
	ds_read_b64_tr_b16 v[98:99], v168 offset:45568
	v_add_f32_e32 v48, v102, v48
	v_add_f32_e32 v48, v103, v48
	v_add_f32_e32 v48, v104, v48
	v_add_f32_e32 v128, v105, v48
	s_waitcnt lgkmcnt(10)
	v_mfma_f32_32x32x16_bf16 v[48:63], v[64:67], v[156:159], 0
	v_cvt_pk_bf16_f32 v142, v100, v101
	v_cvt_pk_bf16_f32 v143, v102, v103
	ds_read_b64_tr_b16 v[64:65], v168 offset:41984
	ds_read_b64_tr_b16 v[66:67], v168 offset:42496
	v_add_f32_e32 v100, v106, v128
	v_add_f32_e32 v100, v107, v100
	v_add_f32_e32 v100, v108, v100
	v_add_f32_e32 v100, v109, v100
	v_cvt_pk_bf16_f32 v136, v104, v105
	v_cvt_pk_bf16_f32 v137, v106, v107
	s_waitcnt lgkmcnt(11)
	v_mfma_f32_32x32x16_bf16 v[112:127], v[68:71], v[152:155], v[112:127]
	ds_read_b64_tr_b16 v[68:69], v168 offset:46080
	ds_read_b64_tr_b16 v[70:71], v168 offset:46592
	s_waitcnt lgkmcnt(12)
	v_mfma_f32_32x32x16_bf16 v[48:63], v[160:163], v[152:155], v[48:63]
	v_add_f32_e32 v100, v110, v100
	v_add_f32_e32 v100, v111, v100
	v_add_f32_e32 v100, v80, v100
	v_add_f32_e32 v104, v81, v100
	v_cvt_pk_bf16_f32 v138, v108, v109
	v_cvt_pk_bf16_f32 v139, v110, v111
	ds_read_b64_tr_b16 v[100:101], v168 offset:43008
	ds_read_b64_tr_b16 v[102:103], v168 offset:43520
	v_add_f32_e32 v104, v82, v104
	v_add_f32_e32 v104, v83, v104
	v_add_f32_e32 v104, v84, v104
	v_add_f32_e32 v104, v85, v104
	v_cvt_pk_bf16_f32 v132, v80, v81
	v_cvt_pk_bf16_f32 v133, v82, v83
	s_waitcnt lgkmcnt(13)
	v_mfma_f32_32x32x16_bf16 v[112:127], v[72:75], v[148:151], v[112:127]
	ds_read_b64_tr_b16 v[72:73], v168 offset:47104
	ds_read_b64_tr_b16 v[74:75], v168 offset:47616
	s_waitcnt lgkmcnt(14)
	v_mfma_f32_32x32x16_bf16 v[48:63], v[164:167], v[148:151], v[48:63]
	v_add_f32_e32 v80, v86, v104
	v_add_f32_e32 v80, v87, v80
	v_add_f32_e32 v80, v88, v80
	v_add_f32_e32 v104, v89, v80
	v_cvt_pk_bf16_f32 v134, v84, v85
	v_cvt_pk_bf16_f32 v135, v86, v87
	ds_read_b64_tr_b16 v[80:81], v168 offset:44032
	ds_read_b64_tr_b16 v[82:83], v168 offset:44544
	v_add_f32_e32 v84, v90, v104
	v_add_f32_e32 v84, v91, v84
	v_add_f32_e32 v84, v92, v84
	v_add_f32_e32 v84, v93, v84
	v_cvt_pk_bf16_f32 v128, v88, v89
	v_cvt_pk_bf16_f32 v129, v90, v91
	s_waitcnt lgkmcnt(14)
	v_mfma_f32_32x32x16_bf16 v[112:127], v[76:79], v[144:147], v[112:127]
	ds_read_b64_tr_b16 v[76:77], v168 offset:48128
	ds_read_b64_tr_b16 v[78:79], v168 offset:48640
	v_mfma_f32_32x32x16_bf16 v[48:63], v[184:187], v[144:147], v[48:63]
	v_add_f32_e32 v84, v94, v84
	v_add_f32_e32 v84, v95, v84
	v_add_f32_e32 v84, 0, v84
	v_cvt_pk_bf16_f32 v130, v92, v93
	v_cvt_pk_bf16_f32 v131, v94, v95
	s_nop 0
	v_add_f32_e32 v175, v175, v84
	v_lshl_add_u64 v[84:85], v[172:173], 0, s[44:45]
	s_mov_b32 s29, m0
	s_mov_b32 m0, s17
	s_nop 0
	global_load_lds_dwordx4 v[84:85], off
	s_mov_b32 m0, s29
	v_lshl_add_u64 v[84:85], v[170:171], 0, s[48:49]
	s_add_i32 s17, s28, 0x8000
	s_mov_b32 s29, m0
	s_mov_b32 m0, s17
	s_nop 0
	global_load_lds_dwordx4 v[84:85], off
	s_mov_b32 m0, s29
	s_waitcnt lgkmcnt(14)
	v_mfma_f32_32x32x16_bf16 v[16:31], v[140:143], v[188:191], v[16:31]
	v_exp_f32_e32 v112, v112
	v_exp_f32_e32 v113, v113
	v_exp_f32_e32 v114, v114
	v_exp_f32_e32 v115, v115
	s_waitcnt lgkmcnt(12)
	v_mfma_f32_32x32x16_bf16 v[32:47], v[140:143], v[96:99], v[32:47]
	v_exp_f32_e32 v116, v116
	v_exp_f32_e32 v117, v117
	v_exp_f32_e32 v118, v118
	v_exp_f32_e32 v119, v119
	ds_read_b128 v[84:87], v182 offset:8192
	ds_read_b128 v[96:99], v182 offset:8704
	s_waitcnt lgkmcnt(12)
	v_mfma_f32_32x32x16_bf16 v[16:31], v[136:139], v[64:67], v[16:31]
	v_exp_f32_e32 v120, v120
	v_exp_f32_e32 v121, v121
	v_exp_f32_e32 v122, v122
	v_exp_f32_e32 v123, v123
	ds_read_b128 v[104:107], v182 offset:10240
	ds_read_b128 v[108:111], v182 offset:10752
	s_waitcnt lgkmcnt(12)
	v_mfma_f32_32x32x16_bf16 v[32:47], v[136:139], v[68:71], v[32:47]
	v_exp_f32_e32 v124, v124
	v_exp_f32_e32 v125, v125
	v_exp_f32_e32 v126, v126
	v_exp_f32_e32 v127, v127
	ds_read_b128 v[160:163], v182 offset:12288
	ds_read_b128 v[164:167], v182 offset:12800
	s_waitcnt lgkmcnt(12)
	v_mfma_f32_32x32x16_bf16 v[16:31], v[132:135], v[100:103], v[16:31]
	v_exp_f32_e32 v48, v48
	v_exp_f32_e32 v49, v49
	v_exp_f32_e32 v50, v50
	v_exp_f32_e32 v51, v51
	ds_read_b128 v[100:103], v182 offset:14336
	ds_read_b128 v[184:187], v182 offset:14848
	s_waitcnt lgkmcnt(12)
	v_mfma_f32_32x32x16_bf16 v[32:47], v[132:135], v[72:75], v[32:47]
	v_exp_f32_e32 v52, v52
	v_exp_f32_e32 v53, v53
	v_exp_f32_e32 v54, v54
	v_exp_f32_e32 v55, v55
	s_waitcnt lgkmcnt(10)
	v_mfma_f32_32x32x16_bf16 v[16:31], v[128:131], v[80:83], v[16:31]
	v_exp_f32_e32 v56, v56
	v_exp_f32_e32 v57, v57
	v_exp_f32_e32 v58, v58
	v_exp_f32_e32 v59, v59
	s_waitcnt lgkmcnt(8)
	v_mfma_f32_32x32x16_bf16 v[32:47], v[128:131], v[76:79], v[32:47]
	v_exp_f32_e32 v60, v60
	v_exp_f32_e32 v61, v61
	v_exp_f32_e32 v62, v62
	v_exp_f32_e32 v63, v63
	s_waitcnt vmcnt(2) lgkmcnt(0)
	s_barrier
	ds_read_b64_tr_b16 v[188:189], v168 offset:24576
	ds_read_b64_tr_b16 v[190:191], v168 offset:25088
	v_add_f32_e32 v64, v112, v113
	v_add_f32_e32 v64, v114, v64
	v_add_f32_e32 v64, v115, v64
	v_add_f32_e32 v64, v116, v64
	v_add_f32_e32 v64, v117, v64
	v_cvt_pk_bf16_f32 v140, v112, v113
	v_cvt_pk_bf16_f32 v141, v114, v115
	s_waitcnt lgkmcnt(9)
	v_mfma_f32_32x32x16_bf16 v[80:95], v[84:87], v[156:159], 0
	ds_read_b64_tr_b16 v[112:113], v168 offset:28672
	ds_read_b64_tr_b16 v[114:115], v168 offset:29184
	v_add_f32_e32 v64, v118, v64
	v_add_f32_e32 v64, v119, v64
	v_add_f32_e32 v64, v120, v64
	v_add_f32_e32 v128, v121, v64
	v_cvt_pk_bf16_f32 v142, v116, v117
	v_cvt_pk_bf16_f32 v143, v118, v119
	s_waitcnt lgkmcnt(10)
	v_mfma_f32_32x32x16_bf16 v[64:79], v[96:99], v[156:159], 0
	ds_read_b64_tr_b16 v[96:97], v168 offset:25600
	ds_read_b64_tr_b16 v[98:99], v168 offset:26112
	v_add_f32_e32 v116, v122, v128
	v_add_f32_e32 v116, v123, v116
	v_add_f32_e32 v116, v124, v116
	v_add_f32_e32 v116, v125, v116
	v_cvt_pk_bf16_f32 v136, v120, v121
	v_cvt_pk_bf16_f32 v137, v122, v123
	s_waitcnt lgkmcnt(11)
	v_mfma_f32_32x32x16_bf16 v[80:95], v[104:107], v[152:155], v[80:95]
	ds_read_b64_tr_b16 v[104:105], v168 offset:29696
	ds_read_b64_tr_b16 v[106:107], v168 offset:30208
	v_add_f32_e32 v116, v126, v116
	v_add_f32_e32 v116, v127, v116
	v_add_f32_e32 v116, v48, v116
	v_add_f32_e32 v116, v49, v116
	v_cvt_pk_bf16_f32 v138, v124, v125
	v_cvt_pk_bf16_f32 v139, v126, v127
	s_waitcnt lgkmcnt(12)
	v_mfma_f32_32x32x16_bf16 v[64:79], v[108:111], v[152:155], v[64:79]
	ds_read_b64_tr_b16 v[108:109], v168 offset:26624
	ds_read_b64_tr_b16 v[110:111], v168 offset:27136
	v_add_f32_e32 v116, v50, v116
	v_add_f32_e32 v116, v51, v116
	v_add_f32_e32 v116, v52, v116
	v_add_f32_e32 v116, v53, v116
	v_cvt_pk_bf16_f32 v132, v48, v49
	v_cvt_pk_bf16_f32 v133, v50, v51
	s_waitcnt lgkmcnt(13)
	v_mfma_f32_32x32x16_bf16 v[80:95], v[160:163], v[148:151], v[80:95]
	ds_read_b64_tr_b16 v[48:49], v168 offset:30720
	ds_read_b64_tr_b16 v[50:51], v168 offset:31232
	v_add_f32_e32 v116, v54, v116
	v_add_f32_e32 v116, v55, v116
	v_add_f32_e32 v116, v56, v116
	v_add_f32_e32 v116, v57, v116
	v_cvt_pk_bf16_f32 v134, v52, v53
	v_cvt_pk_bf16_f32 v135, v54, v55
	s_waitcnt lgkmcnt(14)
	v_mfma_f32_32x32x16_bf16 v[64:79], v[164:167], v[148:151], v[64:79]
	ds_read_b64_tr_b16 v[52:53], v168 offset:27648
	ds_read_b64_tr_b16 v[54:55], v168 offset:28160
	v_add_f32_e32 v116, v58, v116
	v_add_f32_e32 v116, v59, v116
	v_add_f32_e32 v116, v60, v116
	v_add_f32_e32 v116, v61, v116
	v_cvt_pk_bf16_f32 v128, v56, v57
	v_cvt_pk_bf16_f32 v129, v58, v59
	s_waitcnt lgkmcnt(14)
	v_mfma_f32_32x32x16_bf16 v[80:95], v[100:103], v[144:147], v[80:95]
	ds_read_b64_tr_b16 v[56:57], v168 offset:31744
	ds_read_b64_tr_b16 v[58:59], v168 offset:32256
	v_add_f32_e32 v100, v62, v116
	v_add_f32_e32 v100, v63, v100
	v_add_f32_e32 v100, 0, v100
	v_cvt_pk_bf16_f32 v130, v60, v61
	v_cvt_pk_bf16_f32 v131, v62, v63
	v_mfma_f32_32x32x16_bf16 v[64:79], v[184:187], v[144:147], v[64:79]
	v_lshl_add_u64 v[60:61], v[170:171], 0, s[40:41]
	s_add_i32 s28, s28, 0xa000
	s_mov_b32 s17, m0
	s_mov_b32 m0, s28
	s_nop 0
	global_load_lds_dwordx4 v[60:61], off
	s_mov_b32 m0, s17
	v_add_f32_e32 v172, v175, v100
	s_waitcnt lgkmcnt(14)
	v_mfma_f32_32x32x16_bf16 v[16:31], v[140:143], v[188:191], v[16:31]
	v_exp_f32_e32 v80, v80
	v_exp_f32_e32 v81, v81
	v_exp_f32_e32 v82, v82
	v_exp_f32_e32 v83, v83
	s_waitcnt lgkmcnt(12)
	v_mfma_f32_32x32x16_bf16 v[32:47], v[140:143], v[112:115], v[32:47]
	v_exp_f32_e32 v84, v84
	v_exp_f32_e32 v85, v85
	v_exp_f32_e32 v86, v86
	v_exp_f32_e32 v87, v87
	ds_read_b128 v[60:63], v182 offset:16384
	ds_read_b128 v[112:115], v182 offset:16896
	s_waitcnt lgkmcnt(12)
	v_mfma_f32_32x32x16_bf16 v[16:31], v[136:139], v[96:99], v[16:31]
	v_exp_f32_e32 v88, v88
	v_exp_f32_e32 v89, v89
	v_exp_f32_e32 v90, v90
	v_exp_f32_e32 v91, v91
	ds_read_b128 v[116:119], v182 offset:18432
	ds_read_b128 v[120:123], v182 offset:18944
	s_waitcnt lgkmcnt(12)
	v_mfma_f32_32x32x16_bf16 v[32:47], v[136:139], v[104:107], v[32:47]
	v_exp_f32_e32 v92, v92
	v_exp_f32_e32 v93, v93
	v_exp_f32_e32 v94, v94
	v_exp_f32_e32 v95, v95
	ds_read_b128 v[124:127], v182 offset:20480
	ds_read_b128 v[160:163], v182 offset:20992
	s_waitcnt lgkmcnt(12)
	v_mfma_f32_32x32x16_bf16 v[16:31], v[132:135], v[108:111], v[16:31]
	v_exp_f32_e32 v64, v64
	v_exp_f32_e32 v65, v65
	v_exp_f32_e32 v66, v66
	v_exp_f32_e32 v67, v67
	ds_read_b128 v[164:167], v182 offset:22528
	ds_read_b128 v[184:187], v182 offset:23040
	s_waitcnt lgkmcnt(12)
	v_mfma_f32_32x32x16_bf16 v[32:47], v[132:135], v[48:51], v[32:47]
	v_exp_f32_e32 v68, v68
	v_exp_f32_e32 v69, v69
	v_exp_f32_e32 v70, v70
	v_exp_f32_e32 v71, v71
	s_waitcnt lgkmcnt(10)
	v_mfma_f32_32x32x16_bf16 v[16:31], v[128:131], v[52:55], v[16:31]
	v_exp_f32_e32 v72, v72
	v_exp_f32_e32 v73, v73
	v_exp_f32_e32 v74, v74
	v_exp_f32_e32 v75, v75
	s_waitcnt lgkmcnt(8)
	v_mfma_f32_32x32x16_bf16 v[32:47], v[128:131], v[56:59], v[32:47]
	v_exp_f32_e32 v76, v76
	v_exp_f32_e32 v77, v77
	v_exp_f32_e32 v78, v78
	v_exp_f32_e32 v79, v79
	s_waitcnt vmcnt(1) lgkmcnt(0)
	s_barrier
	ds_read_b64_tr_b16 v[188:189], v168 offset:32768
	ds_read_b64_tr_b16 v[190:191], v168 offset:33280
	v_add_f32_e32 v48, v80, v81
	v_add_f32_e32 v48, v82, v48
	v_add_f32_e32 v48, v83, v48
	v_add_f32_e32 v48, v84, v48
	v_add_f32_e32 v48, v85, v48
	v_cvt_pk_bf16_f32 v140, v80, v81
	v_cvt_pk_bf16_f32 v141, v82, v83
	s_waitcnt lgkmcnt(9)
	v_mfma_f32_32x32x16_bf16 v[96:111], v[60:63], v[156:159], 0
	ds_read_b64_tr_b16 v[80:81], v168 offset:36864
	ds_read_b64_tr_b16 v[82:83], v168 offset:37376
	v_add_f32_e32 v48, v86, v48
	v_add_f32_e32 v48, v87, v48
	v_add_f32_e32 v48, v88, v48
	v_add_f32_e32 v128, v89, v48
	s_waitcnt lgkmcnt(10)
	v_mfma_f32_32x32x16_bf16 v[48:63], v[112:115], v[156:159], 0
	v_cvt_pk_bf16_f32 v142, v84, v85
	v_cvt_pk_bf16_f32 v143, v86, v87
	ds_read_b64_tr_b16 v[84:85], v168 offset:33792
	ds_read_b64_tr_b16 v[86:87], v168 offset:34304
	v_add_f32_e32 v112, v90, v128
	v_add_f32_e32 v112, v91, v112
	v_add_f32_e32 v112, v92, v112
	v_add_f32_e32 v112, v93, v112
	v_cvt_pk_bf16_f32 v136, v88, v89
	v_cvt_pk_bf16_f32 v137, v90, v91
	s_waitcnt lgkmcnt(11)
	v_mfma_f32_32x32x16_bf16 v[96:111], v[116:119], v[152:155], v[96:111]
	ds_read_b64_tr_b16 v[88:89], v168 offset:37888
	ds_read_b64_tr_b16 v[90:91], v168 offset:38400
	s_waitcnt lgkmcnt(12)
	v_mfma_f32_32x32x16_bf16 v[48:63], v[120:123], v[152:155], v[48:63]
	v_add_f32_e32 v112, v94, v112
	v_add_f32_e32 v112, v95, v112
	v_add_f32_e32 v112, v64, v112
	v_add_f32_e32 v112, v65, v112
	v_cvt_pk_bf16_f32 v138, v92, v93
	v_cvt_pk_bf16_f32 v139, v94, v95
	ds_read_b64_tr_b16 v[92:93], v168 offset:34816
	ds_read_b64_tr_b16 v[94:95], v168 offset:35328
	v_add_f32_e32 v112, v66, v112
	v_add_f32_e32 v112, v67, v112
	v_add_f32_e32 v112, v68, v112
	v_add_f32_e32 v112, v69, v112
	v_cvt_pk_bf16_f32 v132, v64, v65
	v_cvt_pk_bf16_f32 v133, v66, v67
	s_waitcnt lgkmcnt(13)
	v_mfma_f32_32x32x16_bf16 v[96:111], v[124:127], v[148:151], v[96:111]
	ds_read_b64_tr_b16 v[64:65], v168 offset:38912
	ds_read_b64_tr_b16 v[66:67], v168 offset:39424
	s_waitcnt lgkmcnt(14)
	v_mfma_f32_32x32x16_bf16 v[48:63], v[160:163], v[148:151], v[48:63]
	v_add_f32_e32 v112, v70, v112
	v_add_f32_e32 v112, v71, v112
	v_add_f32_e32 v112, v72, v112
	v_add_f32_e32 v112, v73, v112
	v_cvt_pk_bf16_f32 v134, v68, v69
	v_cvt_pk_bf16_f32 v135, v70, v71
	ds_read_b64_tr_b16 v[68:69], v168 offset:35840
	ds_read_b64_tr_b16 v[70:71], v168 offset:36352
	v_add_f32_e32 v112, v74, v112
	v_add_f32_e32 v112, v75, v112
	v_add_f32_e32 v112, v76, v112
	v_add_f32_e32 v112, v77, v112
	v_cvt_pk_bf16_f32 v128, v72, v73
	v_cvt_pk_bf16_f32 v129, v74, v75
	s_waitcnt lgkmcnt(14)
	v_mfma_f32_32x32x16_bf16 v[96:111], v[164:167], v[144:147], v[96:111]
	ds_read_b64_tr_b16 v[72:73], v168 offset:39936
	ds_read_b64_tr_b16 v[74:75], v168 offset:40448
	v_mfma_f32_32x32x16_bf16 v[48:63], v[184:187], v[144:147], v[48:63]
	v_add_f32_e32 v112, v78, v112
	v_add_f32_e32 v112, v79, v112
	v_add_f32_e32 v112, 0, v112
	v_cvt_pk_bf16_f32 v130, v76, v77
	v_cvt_pk_bf16_f32 v131, v78, v79
	v_lshl_add_u64 v[76:77], v[170:171], 0, s[44:45]
	s_mov_b32 s17, m0
	s_mov_b32 m0, s16
	s_nop 0
	global_load_lds_dwordx4 v[76:77], off
	s_mov_b32 m0, s17
	v_add_f32_e32 v120, v172, v112
	s_waitcnt lgkmcnt(14)
	v_mfma_f32_32x32x16_bf16 v[16:31], v[140:143], v[188:191], v[16:31]
	v_exp_f32_e32 v96, v96
	v_exp_f32_e32 v97, v97
	v_exp_f32_e32 v98, v98
	v_exp_f32_e32 v99, v99
	s_waitcnt lgkmcnt(12)
	v_mfma_f32_32x32x16_bf16 v[32:47], v[140:143], v[80:83], v[32:47]
	v_exp_f32_e32 v100, v100
	v_exp_f32_e32 v101, v101
	v_exp_f32_e32 v102, v102
	v_exp_f32_e32 v103, v103
	ds_read_b128 v[76:79], v182
	ds_read_b128 v[80:83], v182 offset:512
	s_waitcnt lgkmcnt(12)
	v_mfma_f32_32x32x16_bf16 v[16:31], v[136:139], v[84:87], v[16:31]
	v_exp_f32_e32 v104, v104
	v_exp_f32_e32 v105, v105
	v_exp_f32_e32 v106, v106
	v_exp_f32_e32 v107, v107
	ds_read_b128 v[122:125], v182 offset:2048
	ds_read_b128 v[160:163], v182 offset:2560
	s_waitcnt lgkmcnt(12)
	v_mfma_f32_32x32x16_bf16 v[32:47], v[136:139], v[88:91], v[32:47]
	v_exp_f32_e32 v108, v108
	v_exp_f32_e32 v109, v109
	v_exp_f32_e32 v110, v110
	v_exp_f32_e32 v111, v111
	ds_read_b128 v[164:167], v182 offset:4096
	ds_read_b128 v[170:173], v182 offset:4608
	s_waitcnt lgkmcnt(12)
	v_mfma_f32_32x32x16_bf16 v[16:31], v[132:135], v[92:95], v[16:31]
	v_exp_f32_e32 v48, v48
	v_exp_f32_e32 v49, v49
	v_exp_f32_e32 v50, v50
	v_exp_f32_e32 v51, v51
	ds_read_b128 v[184:187], v182 offset:6144
	ds_read_b128 v[188:191], v182 offset:6656
	s_waitcnt lgkmcnt(12)
	v_mfma_f32_32x32x16_bf16 v[32:47], v[132:135], v[64:67], v[32:47]
	v_exp_f32_e32 v52, v52
	v_exp_f32_e32 v53, v53
	v_exp_f32_e32 v54, v54
	v_exp_f32_e32 v55, v55
	s_waitcnt lgkmcnt(10)
	v_mfma_f32_32x32x16_bf16 v[16:31], v[128:131], v[68:71], v[16:31]
	v_exp_f32_e32 v56, v56
	v_exp_f32_e32 v57, v57
	v_exp_f32_e32 v58, v58
	v_exp_f32_e32 v59, v59
	s_waitcnt lgkmcnt(8)
	v_mfma_f32_32x32x16_bf16 v[32:47], v[128:131], v[72:75], v[32:47]
	v_exp_f32_e32 v60, v60
	v_exp_f32_e32 v61, v61
	v_exp_f32_e32 v62, v62
	v_exp_f32_e32 v63, v63
	s_waitcnt vmcnt(0) lgkmcnt(0)
	s_barrier
	ds_read_b64_tr_b16 v[112:113], v168 offset:40960
	ds_read_b64_tr_b16 v[114:115], v168 offset:41472
	v_add_f32_e32 v64, v96, v97
	v_add_f32_e32 v64, v98, v64
	v_add_f32_e32 v64, v99, v64
	v_add_f32_e32 v64, v100, v64
	v_add_f32_e32 v84, v101, v64
	v_cvt_pk_bf16_f32 v140, v96, v97
	v_cvt_pk_bf16_f32 v141, v98, v99
	s_waitcnt lgkmcnt(9)
	v_mfma_f32_32x32x16_bf16 v[64:79], v[76:79], v[156:159], 0
	ds_read_b64_tr_b16 v[96:97], v168 offset:45056
	ds_read_b64_tr_b16 v[98:99], v168 offset:45568
	v_add_f32_e32 v84, v102, v84
	v_add_f32_e32 v84, v103, v84
	v_add_f32_e32 v84, v104, v84
	v_add_f32_e32 v121, v105, v84
	v_cvt_pk_bf16_f32 v142, v100, v101
	v_cvt_pk_bf16_f32 v143, v102, v103
	s_waitcnt lgkmcnt(10)
	v_mfma_f32_32x32x16_bf16 v[80:95], v[80:83], v[156:159], 0
	ds_read_b64_tr_b16 v[116:117], v168 offset:41984
	ds_read_b64_tr_b16 v[118:119], v168 offset:42496
	v_add_f32_e32 v100, v106, v121
	v_add_f32_e32 v100, v107, v100
	v_add_f32_e32 v100, v108, v100
	v_add_f32_e32 v121, v109, v100
	v_cvt_pk_bf16_f32 v136, v104, v105
	v_cvt_pk_bf16_f32 v137, v106, v107
	s_waitcnt lgkmcnt(11)
	v_mfma_f32_32x32x16_bf16 v[64:79], v[122:125], v[152:155], v[64:79]
	ds_read_b64_tr_b16 v[100:101], v168 offset:46080
	ds_read_b64_tr_b16 v[102:103], v168 offset:46592
	v_add_f32_e32 v104, v110, v121
	v_add_f32_e32 v104, v111, v104
	v_add_f32_e32 v104, v48, v104
	v_add_f32_e32 v121, v49, v104
	v_cvt_pk_bf16_f32 v138, v108, v109
	v_cvt_pk_bf16_f32 v139, v110, v111
	s_waitcnt lgkmcnt(12)
	v_mfma_f32_32x32x16_bf16 v[80:95], v[160:163], v[152:155], v[80:95]
	ds_read_b64_tr_b16 v[104:105], v168 offset:43008
	ds_read_b64_tr_b16 v[106:107], v168 offset:43520
	v_add_f32_e32 v108, v50, v121
	v_add_f32_e32 v108, v51, v108
	v_add_f32_e32 v108, v52, v108
	v_add_f32_e32 v108, v53, v108
	v_cvt_pk_bf16_f32 v132, v48, v49
	v_cvt_pk_bf16_f32 v133, v50, v51
	s_waitcnt lgkmcnt(13)
	v_mfma_f32_32x32x16_bf16 v[64:79], v[164:167], v[148:151], v[64:79]
	ds_read_b64_tr_b16 v[48:49], v168 offset:47104
	ds_read_b64_tr_b16 v[50:51], v168 offset:47616
	v_add_f32_e32 v108, v54, v108
	v_add_f32_e32 v108, v55, v108
	v_add_f32_e32 v108, v56, v108
	v_add_f32_e32 v121, v57, v108
	v_cvt_pk_bf16_f32 v134, v52, v53
	v_cvt_pk_bf16_f32 v135, v54, v55
	s_waitcnt lgkmcnt(14)
	v_mfma_f32_32x32x16_bf16 v[80:95], v[170:173], v[148:151], v[80:95]
	ds_read_b64_tr_b16 v[108:109], v168 offset:44032
	ds_read_b64_tr_b16 v[110:111], v168 offset:44544
	v_add_f32_e32 v52, v58, v121
	v_add_f32_e32 v52, v59, v52
	v_add_f32_e32 v52, v60, v52
	v_add_f32_e32 v121, v61, v52
	v_cvt_pk_bf16_f32 v128, v56, v57
	v_cvt_pk_bf16_f32 v129, v58, v59
	s_waitcnt lgkmcnt(14)
	v_mfma_f32_32x32x16_bf16 v[64:79], v[184:187], v[144:147], v[64:79]
	ds_read_b64_tr_b16 v[52:53], v168 offset:48128
	ds_read_b64_tr_b16 v[54:55], v168 offset:48640
	v_add_f32_e32 v56, v62, v121
	v_add_f32_e32 v56, v63, v56
	v_add_f32_e32 v56, 0, v56
	v_cvt_pk_bf16_f32 v130, v60, v61
	v_cvt_pk_bf16_f32 v131, v62, v63
	v_mfma_f32_32x32x16_bf16 v[80:95], v[188:191], v[144:147], v[80:95]
	s_nop 3
	v_exp_f32_e32 v64, v64
	v_exp_f32_e32 v65, v65
	v_exp_f32_e32 v66, v66
	v_exp_f32_e32 v67, v67
	s_nop 0
	v_exp_f32_e32 v68, v68
	v_exp_f32_e32 v69, v69
	v_exp_f32_e32 v70, v70
	v_exp_f32_e32 v71, v71
	s_nop 0
	v_exp_f32_e32 v72, v72
	v_exp_f32_e32 v73, v73
	v_exp_f32_e32 v74, v74
	v_exp_f32_e32 v75, v75
	s_nop 0
	v_exp_f32_e32 v76, v76
	v_exp_f32_e32 v77, v77
	v_exp_f32_e32 v78, v78
	v_exp_f32_e32 v79, v79
	v_exp_f32_e32 v80, v80
	v_exp_f32_e32 v81, v81
	v_exp_f32_e32 v82, v82
	v_exp_f32_e32 v83, v83
	s_nop 0
	v_exp_f32_e32 v84, v84
	v_exp_f32_e32 v85, v85
	v_exp_f32_e32 v86, v86
	v_exp_f32_e32 v87, v87
	s_nop 0
	v_exp_f32_e32 v88, v88
	v_exp_f32_e32 v89, v89
	v_exp_f32_e32 v90, v90
	v_exp_f32_e32 v91, v91
	s_nop 0
	v_exp_f32_e32 v92, v92
	v_exp_f32_e32 v93, v93
	v_exp_f32_e32 v94, v94
	v_exp_f32_e32 v95, v95
	s_waitcnt lgkmcnt(14)
; #define SBAR() __builtin_amdgcn_sched_barrier(0)
;   #define PKW(P,B) cvtpk_s(P[B],P[B+1])
; template<int THRL,int VM,bool NOMAX> __device__ __forceinline__ void attn_unit(const bf16*Qb,const bf16*__restrict__ Kh,const bf16*__restrict__ Vh,bf16*Ob,const int NT,const int sp,float*wscr,char*shm){
;     ...
;   { float sacc=pB0[0]+pB0[1]; _Pragma("unroll") for(int r=2;r<16;++r)sacc+=pB0[r]; _Pragma("unroll") for(int r=0;r<16;++r)sacc+=pB1[r]; l_reg+=sacc;
;     pw0=(u32x4){PKW(pB0,0),PKW(pB0,2),PKW(pB0,4),PKW(pB0,6)};pw1=(u32x4){PKW(pB0,8),PKW(pB0,10),PKW(pB0,12),PKW(pB0,14)};pw2=(u32x4){PKW(pB1,0),PKW(pB1,2),PKW(pB1,4),PKW(pB1,6)};pw3=(u32x4){PKW(pB1,8),PKW(pB1,10),PKW(pB1,12),PKW(pB1,14)};
;     SBAR(); pv(o,vb0+VM*sl_cur,PAF(0),PAF(1),PAF(2),PAF(3)); if constexpr(VM==2) pv(o+2,vb0+VM*sl_cur+8192,PAF(0),PAF(1),PAF(2),PAF(3)); }
;     ...
;   {auto rr=__builtin_amdgcn_permlane32_swap(__float_as_uint(l_reg),__float_as_uint(l_reg),false,false);l_reg=__uint_as_float(rr[0])+__uint_as_float(rr[1]);}
;   if(hi==0)wsf[32+r32]=l_reg;asm volatile("s_waitcnt lgkmcnt(0)":::"memory");
	v_mfma_f32_32x32x16_bf16 v[16:31], v[140:143], v[112:115], v[16:31]
	v_add_f32_e32 v57, v64, v65
	v_add_f32_e32 v57, v66, v57
	v_add_f32_e32 v57, v67, v57
	v_add_f32_e32 v57, v68, v57
	v_add_f32_e32 v57, v69, v57
	v_add_f32_e32 v57, v70, v57
	v_add_f32_e32 v57, v71, v57
	s_waitcnt lgkmcnt(12)
	v_mfma_f32_32x32x16_bf16 v[32:47], v[140:143], v[96:99], v[32:47]
	v_add_f32_e32 v57, v72, v57
	v_add_f32_e32 v57, v73, v57
	v_add_f32_e32 v57, v74, v57
	v_add_f32_e32 v57, v75, v57
	v_add_f32_e32 v57, v76, v57
	v_add_f32_e32 v57, v77, v57
	v_add_f32_e32 v57, v78, v57
	s_waitcnt lgkmcnt(10)
	v_mfma_f32_32x32x16_bf16 v[16:31], v[136:139], v[116:119], v[16:31]
	v_add_f32_e32 v57, v79, v57
	v_add_f32_e32 v57, v80, v57
	v_add_f32_e32 v57, v81, v57
	v_add_f32_e32 v57, v82, v57
	v_add_f32_e32 v57, v83, v57
	v_add_f32_e32 v57, v84, v57
	v_add_f32_e32 v57, v85, v57
	s_waitcnt lgkmcnt(8)
	v_mfma_f32_32x32x16_bf16 v[32:47], v[136:139], v[100:103], v[32:47]
	v_add_f32_e32 v57, v86, v57
	v_add_f32_e32 v57, v87, v57
	v_add_f32_e32 v57, v88, v57
	v_add_f32_e32 v57, v89, v57
	v_add_f32_e32 v57, v90, v57
	v_add_f32_e32 v57, v91, v57
	v_add_f32_e32 v57, v92, v57
	s_waitcnt lgkmcnt(6)
	v_mfma_f32_32x32x16_bf16 v[16:31], v[132:135], v[104:107], v[16:31]
	v_add_f32_e32 v57, v93, v57
	v_add_f32_e32 v57, v94, v57
	v_add_f32_e32 v57, v95, v57
	v_add_f32_e32 v56, v120, v56
	v_add_f32_e32 v56, v56, v57
	v_cvt_pk_bf16_f32 v58, v64, v65
	v_cvt_pk_bf16_f32 v59, v66, v67
	s_waitcnt lgkmcnt(4)
	v_mfma_f32_32x32x16_bf16 v[32:47], v[132:135], v[48:51], v[32:47]
	v_cvt_pk_bf16_f32 v48, v80, v81
	v_cvt_pk_bf16_f32 v60, v68, v69
	v_cvt_pk_bf16_f32 v61, v70, v71
	v_cvt_pk_bf16_f32 v62, v72, v73
	v_cvt_pk_bf16_f32 v63, v74, v75
	v_cvt_pk_bf16_f32 v64, v76, v77
	v_cvt_pk_bf16_f32 v65, v78, v79
	s_waitcnt lgkmcnt(2)
	v_mfma_f32_32x32x16_bf16 v[16:31], v[128:131], v[108:111], v[16:31]
	v_cvt_pk_bf16_f32 v49, v82, v83
	v_cvt_pk_bf16_f32 v50, v84, v85
	v_cvt_pk_bf16_f32 v51, v86, v87
	v_cvt_pk_bf16_f32 v66, v88, v89
	v_cvt_pk_bf16_f32 v67, v90, v91
	v_cvt_pk_bf16_f32 v68, v92, v93
	v_cvt_pk_bf16_f32 v69, v94, v95
	s_waitcnt lgkmcnt(0)
	v_mfma_f32_32x32x16_bf16 v[32:47], v[128:131], v[52:55], v[32:47]
	ds_read_b64_tr_b16 v[52:53],v174 offset:0
	ds_read_b64_tr_b16 v[54:55],v174 offset:512
	ds_read_b64_tr_b16 v[70:71],v174 offset:1024
	ds_read_b64_tr_b16 v[72:73],v174 offset:1536
	ds_read_b64_tr_b16 v[74:75],v174 offset:2048
	ds_read_b64_tr_b16 v[76:77],v174 offset:2560
	ds_read_b64_tr_b16 v[78:79],v174 offset:3072
	ds_read_b64_tr_b16 v[80:81],v174 offset:3584
	s_waitcnt lgkmcnt(0)
	s_nop 0
	v_mfma_f32_32x32x16_bf16 v[16:31], v[58:61], v[52:55], v[16:31]
	ds_read_b64_tr_b16 v[52:53],v174 offset:4096
	ds_read_b64_tr_b16 v[54:55],v174 offset:4608
	v_mfma_f32_32x32x16_bf16 v[16:31], v[62:65], v[70:73], v[16:31]
	ds_read_b64_tr_b16 v[70:71],v174 offset:5120
	ds_read_b64_tr_b16 v[72:73],v174 offset:5632
	v_mfma_f32_32x32x16_bf16 v[16:31], v[48:51], v[74:77], v[16:31]
	ds_read_b64_tr_b16 v[74:75],v174 offset:6144
	ds_read_b64_tr_b16 v[76:77],v174 offset:6656
	ds_read_b64_tr_b16 v[82:83],v174 offset:7168
	ds_read_b64_tr_b16 v[84:85],v174 offset:7680
	s_waitcnt lgkmcnt(0)
	v_mfma_f32_32x32x16_bf16 v[16:31], v[66:69], v[78:81], v[16:31]
	v_mfma_f32_32x32x16_bf16 v[32:47], v[58:61], v[52:55], v[32:47]
	v_cmp_gt_u32_e32 vcc, 32, v178
	v_mfma_f32_32x32x16_bf16 v[32:47], v[62:65], v[70:73], v[32:47]
	v_mfma_f32_32x32x16_bf16 v[32:47], v[48:51], v[74:77], v[32:47]
	v_mov_b32_e32 v48, v56
	s_nop 1
	v_permlane32_swap_b32_e32 v56, v48
	v_mfma_f32_32x32x16_bf16 v[32:47], v[66:69], v[82:85], v[32:47]
	s_and_saveexec_b64 s[16:17], vcc
	s_cbranch_execz .LBB0_887
	v_add_f32_e32 v48, v56, v48
	v_lshl_add_u32 v49, v180, 2, s19
	ds_write_b32 v49, v48 offset:49280
	s_branch .LBB0_887
